# static s_setprio 1 for the second workgroup of each CU inside the register-staged GEMM k-loops
# speedup vs baseline: 1.1157x; 1.0044x over previous
; template <int NJ>
; __device__ __forceinline__ void gemm_tile(const f16* __restrict__ A, int lda, const f16* __restrict__ Bt, int ldb,
;                                           int K, f32x4 (&acc)[4][NJ], f16* sA, f16* sB, const int tid) {
;     ...
;   const int crow = tid >> 3, ckc = (tid & 7) * 8;
;   const f16* ap = A + (size_t)crow * lda + ckc;
;   const f16* bp = Bt + (size_t)crow * ldb + ckc;
;   const int woff = crow * LDT + ckc;
;   const int aoff = (wm * 64 + (lane & 15)) * LDT + (lane >> 4) * 8;
;   const int boff = (wn * (NJ * 16) + (lane & 15)) * LDT + (lane >> 4) * 8;
;     ...
;   G_LOAD(ra0, rb0, 0)
;   if (K > 64) G_LOAD(ra1, rb1, 64)
;   __syncthreads();
;   G_STORE(ra0, rb0, 0)
;   if (K > 128) G_LOAD(ra0, rb0, 128)
;   __syncthreads();
; #pragma unroll 1
;   for (int k0 = 0; k0 < K; k0 += 128) {
; __device__ __forceinline__ void phase_g1(const Params& p, int l, f16* smem) {
;     ...
;     int m0 = (t / NT) * 128, n0 = (t % NT) * 128;
;     f32x4 acc[4][4];
;     zero_acc<4>(acc);
;     gemm_tile<4>(H + (size_t)m0 * DM, DM, W + (size_t)n0 * DM, DM, DM, acc, sA, sB, TIDX(p));
.Lxm_done_g1:
	s_lshl_b64 s[6:7], s[14:15], 11
	v_lshl_add_u64 v[156:157], v[154:155], 0, s[6:7]
	v_add_co_u32_e32 v4, vcc, s94, v156
	s_lshl_b32 s16, s21, 7
	s_nop 0
	v_addc_co_u32_e32 v5, vcc, 0, v157, vcc
	v_add_co_u32_e32 v6, vcc, s72, v156
	s_ashr_i32 s17, s16, 31
	s_nop 0
	v_addc_co_u32_e32 v7, vcc, 0, v157, vcc
	s_lshl_b64 s[8:9], s[16:17], 11
	v_add_co_u32_e32 v8, vcc, s73, v156
	v_lshl_add_u64 v[158:159], v[152:153], 0, s[8:9]
	s_nop 0
	v_addc_co_u32_e32 v9, vcc, 0, v157, vcc
	v_add_co_u32_e32 v10, vcc, s94, v158
	global_load_dwordx4 v[18:21], v[156:157], off
	s_nop 0
	v_addc_co_u32_e32 v11, vcc, 0, v159, vcc
	v_add_co_u32_e32 v12, vcc, s72, v158
	global_load_dwordx4 v[22:25], v[4:5], off
	global_load_dwordx4 v[26:29], v[6:7], off
	v_addc_co_u32_e32 v13, vcc, 0, v159, vcc
	v_add_co_u32_e32 v14, vcc, s73, v158
	global_load_dwordx4 v[30:33], v[8:9], off
	global_load_dwordx4 v[38:41], v[10:11], off
	v_addc_co_u32_e32 v15, vcc, 0, v159, vcc
	global_load_dwordx4 v[34:37], v[158:159], off
	global_load_dwordx4 v[42:45], v[12:13], off
	global_load_dwordx4 v[46:49], v[14:15], off
	global_load_dwordx4 v[68:71], v[156:157], off offset:128
	global_load_dwordx4 v[76:79], v[4:5], off offset:128
	global_load_dwordx4 v[80:83], v[6:7], off offset:128
	global_load_dwordx4 v[84:87], v[8:9], off offset:128
	global_load_dwordx4 v[72:75], v[158:159], off offset:128
	global_load_dwordx4 v[88:91], v[10:11], off offset:128
	global_load_dwordx4 v[96:99], v[12:13], off offset:128
	global_load_dwordx4 v[100:103], v[14:15], off offset:128
	s_barrier
	global_load_dwordx4 v[108:111], v[4:5], off offset:256
	global_load_dwordx4 v[112:115], v[6:7], off offset:256
	global_load_dwordx4 v[92:95], v[156:157], off offset:256
	global_load_dwordx4 v[104:107], v[158:159], off offset:256
	global_load_dwordx4 v[116:119], v[8:9], off offset:256
	global_load_dwordx4 v[120:123], v[10:11], off offset:256
	global_load_dwordx4 v[124:127], v[12:13], off offset:256
	global_load_dwordx4 v[128:131], v[14:15], off offset:256
	v_mov_b32_e32 v4, 0
	s_mov_b32 s6, 0
	v_mov_b32_e32 v5, v4
	v_mov_b32_e32 v6, v4
	v_mov_b32_e32 v7, v4
	v_mov_b32_e32 v8, v4
	v_mov_b32_e32 v9, v4
	v_mov_b32_e32 v10, v4
	v_mov_b32_e32 v11, v4
	v_mov_b32_e32 v12, v4
	v_mov_b32_e32 v13, v4
	v_mov_b32_e32 v14, v4
	v_mov_b32_e32 v15, v4
	v_mov_b32_e32 v16, v4
	v_mov_b32_e32 v17, v4
	v_mov_b32_e32 v50, v4
	v_mov_b32_e32 v51, v4
	v_mov_b32_e32 v52, v4
	v_mov_b32_e32 v53, v4
	v_mov_b32_e32 v54, v4
	v_mov_b32_e32 v55, v4
	v_mov_b32_e32 v56, v4
	v_mov_b32_e32 v57, v4
	v_mov_b32_e32 v58, v4
	v_mov_b32_e32 v59, v4
	v_mov_b32_e32 v60, v4
	v_mov_b32_e32 v61, v4
	v_mov_b32_e32 v62, v4
	v_mov_b32_e32 v63, v4
	v_mov_b32_e32 v64, v4
	v_mov_b32_e32 v65, v4
	v_mov_b32_e32 v66, v4
	v_mov_b32_e32 v67, v4
	s_waitcnt vmcnt(23)
	ds_write_b128 v167, v[18:21]
	s_waitcnt vmcnt(22)
	ds_write_b128 v167, v[22:25] offset:4096
	s_waitcnt vmcnt(21)
	ds_write_b128 v167, v[26:29] offset:8192
	s_waitcnt vmcnt(20)
	ds_write_b128 v167, v[30:33] offset:12288
	s_waitcnt vmcnt(18)
	ds_write_b128 v167, v[34:37] offset:16384
	ds_write_b128 v167, v[38:41] offset:20480
	s_waitcnt vmcnt(17)
	ds_write_b128 v167, v[42:45] offset:24576
	s_waitcnt vmcnt(16)
	ds_write_b128 v167, v[46:49] offset:28672
	v_mov_b32_e32 v18, v4
	v_mov_b32_e32 v19, v4
	v_mov_b32_e32 v20, v4
	v_mov_b32_e32 v21, v4
	v_mov_b32_e32 v22, v4
	v_mov_b32_e32 v23, v4
	v_mov_b32_e32 v24, v4
	v_mov_b32_e32 v25, v4
	v_mov_b32_e32 v26, v4
	v_mov_b32_e32 v27, v4
	v_mov_b32_e32 v28, v4
	v_mov_b32_e32 v29, v4
	v_mov_b32_e32 v30, v4
	v_mov_b32_e32 v31, v4
	v_mov_b32_e32 v32, v4
	v_mov_b32_e32 v33, v4
	v_mov_b32_e32 v34, v4
	v_mov_b32_e32 v35, v4
	v_mov_b32_e32 v36, v4
	v_mov_b32_e32 v37, v4
	v_mov_b32_e32 v38, v4
	v_mov_b32_e32 v39, v4
	v_mov_b32_e32 v40, v4
	v_mov_b32_e32 v41, v4
	v_mov_b32_e32 v42, v4
	v_mov_b32_e32 v43, v4
	v_mov_b32_e32 v44, v4
	v_mov_b32_e32 v45, v4
	v_mov_b32_e32 v46, v4
	v_mov_b32_e32 v47, v4
	v_mov_b32_e32 v48, v4
	v_mov_b32_e32 v49, v4
	s_waitcnt lgkmcnt(0)
	s_barrier
	s_bitcmp1_b32 s95, 8
	s_cbranch_scc0 .Lprio_195
	s_setprio 1
.Lprio_195:
.LBB0_195:
	ds_read_b128 v[204:207], v168 offset:16384
	ds_read_b128 v[208:211], v168 offset:18432
	ds_read_b128 v[212:215], v168 offset:20480
	ds_read_b128 v[216:219], v168 offset:22528
	s_add_i32 s7, s6, 0xc0
	ds_read_b128 v[192:195], v170
	ds_read_b128 v[196:199], v170 offset:2048
	s_cmpk_lt_u32 s6, 0x340
	s_cselect_b32 s42, s7, 0x3c0
	ds_read_b128 v[200:203], v170 offset:4096
	s_lshl_b64 s[8:9], s[42:43], 1
	v_lshl_add_u64 v[162:163], v[156:157], 0, s[8:9]
	ds_read_b128 v[132:135], v170 offset:6144
	ds_read_b128 v[244:247], v243 offset:16384
	ds_read_b128 v[248:251], v243 offset:18432
	ds_read_b128 v[252:255], v243 offset:20480
	s_waitcnt lgkmcnt(6)
	v_mfma_f32_16x16x32_f16 v[64:67], v[204:207], v[192:195], v[64:67]
	v_lshl_add_u64 v[160:161], v[158:159], 0, s[8:9]
	s_add_i32 s7, s6, 0x100
	s_cmpk_lt_u32 s6, 0x300
	v_mfma_f32_16x16x32_f16 v[60:63], v[208:211], v[192:195], v[60:63]
	s_cselect_b32 s42, s7, 0x3c0
	s_lshl_b64 s[8:9], s[42:43], 1
	s_add_i32 s7, s6, 0x80
	v_mfma_f32_16x16x32_f16 v[56:59], v[212:215], v[192:195], v[56:59]
	s_cmpk_lt_u32 s6, 0x280
	s_mov_b32 s6, s7
	v_mfma_f32_16x16x32_f16 v[52:55], v[216:219], v[192:195], v[52:55]
	ds_read_b128 v[192:195], v243 offset:22528
	s_waitcnt vmcnt(15)
	ds_write_b128 v167, v[68:71] offset:32768
	global_load_dwordx4 v[68:71], v[162:163], off
	s_waitcnt lgkmcnt(7)
	v_mfma_f32_16x16x32_f16 v[48:51], v[204:207], v[196:199], v[48:51]
	v_mfma_f32_16x16x32_f16 v[44:47], v[208:211], v[196:199], v[44:47]
	v_mfma_f32_16x16x32_f16 v[40:43], v[212:215], v[196:199], v[40:43]
	v_mfma_f32_16x16x32_f16 v[36:39], v[216:219], v[196:199], v[36:39]
	ds_read_b128 v[196:199], v242
	s_waitcnt vmcnt(15)
; template <int NJ>
; __device__ __forceinline__ void gemm_tile(const f16* __restrict__ A, int lda, const f16* __restrict__ Bt, int ldb,
;                                           int K, f32x4 (&acc)[4][NJ], f16* sA, f16* sB, const int tid) {
;     ...
;   G_LOAD(ra0, rb0, 0)
;   if (K > 64) G_LOAD(ra1, rb1, 64)
;   __syncthreads();
;   G_STORE(ra0, rb0, 0)
;   if (K > 128) G_LOAD(ra0, rb0, 128)
;   __syncthreads();
; #pragma unroll 1
;   for (int k0 = 0; k0 < K; k0 += 128) {
;     {
;       const int kof = (k0 + 192 < K) ? k0 + 192 : K - 64;
;       G_STEP(0, ra1, rb1, true, true, kof)
;     }
;     __syncthreads();
;     if (k0 + 64 >= K) break;
;     {
;       const int kof = (k0 + 256 < K) ? k0 + 256 : K - 64;
;       G_STEP(1, ra0, rb0, true, true, kof)
;     }
;     __syncthreads();
	ds_write_b128 v167, v[76:79] offset:36864
	v_add_co_u32_e32 v76, vcc, s94, v162
	s_nop 1
	v_addc_co_u32_e32 v77, vcc, 0, v163, vcc
	global_load_dwordx4 v[76:79], v[76:77], off
	s_waitcnt lgkmcnt(8)
	v_mfma_f32_16x16x32_f16 v[32:35], v[204:207], v[200:203], v[32:35]
	v_mfma_f32_16x16x32_f16 v[28:31], v[208:211], v[200:203], v[28:31]
	v_mfma_f32_16x16x32_f16 v[24:27], v[212:215], v[200:203], v[24:27]
	v_mfma_f32_16x16x32_f16 v[20:23], v[216:219], v[200:203], v[20:23]
	ds_read_b128 v[200:203], v242 offset:2048
	s_waitcnt vmcnt(15)
	ds_write_b128 v167, v[80:83] offset:40960
	v_add_co_u32_e32 v80, vcc, s72, v162
	s_nop 1
	v_addc_co_u32_e32 v81, vcc, 0, v163, vcc
	global_load_dwordx4 v[80:83], v[80:81], off
	s_waitcnt lgkmcnt(9)
	v_mfma_f32_16x16x32_f16 v[16:19], v[204:207], v[132:135], v[16:19]
	v_mfma_f32_16x16x32_f16 v[12:15], v[208:211], v[132:135], v[12:15]
	v_mfma_f32_16x16x32_f16 v[8:11], v[212:215], v[132:135], v[8:11]
	v_mfma_f32_16x16x32_f16 v[4:7], v[216:219], v[132:135], v[4:7]
	ds_read_b128 v[132:135], v242 offset:4096
	ds_read_b128 v[204:207], v242 offset:6144
	s_waitcnt vmcnt(15)
	ds_write_b128 v167, v[84:87] offset:45056
	v_add_co_u32_e32 v84, vcc, s73, v162
	s_nop 1
	v_addc_co_u32_e32 v85, vcc, 0, v163, vcc
	global_load_dwordx4 v[84:87], v[84:85], off
	s_waitcnt lgkmcnt(6)
	v_mfma_f32_16x16x32_f16 v[64:67], v[244:247], v[196:199], v[64:67]
	v_mfma_f32_16x16x32_f16 v[60:63], v[248:251], v[196:199], v[60:63]
	v_mfma_f32_16x16x32_f16 v[56:59], v[252:255], v[196:199], v[56:59]
	v_mfma_f32_16x16x32_f16 v[52:55], v[192:195], v[196:199], v[52:55]
	s_waitcnt vmcnt(15)
	ds_write_b128 v167, v[72:75] offset:49152
	global_load_dwordx4 v[72:75], v[160:161], off
	v_lshl_add_u64 v[218:219], v[156:157], 0, s[8:9]
	s_waitcnt lgkmcnt(5)
	v_mfma_f32_16x16x32_f16 v[48:51], v[244:247], v[200:203], v[48:51]
	v_lshl_add_u64 v[216:217], v[158:159], 0, s[8:9]
	v_mfma_f32_16x16x32_f16 v[44:47], v[248:251], v[200:203], v[44:47]
	v_mfma_f32_16x16x32_f16 v[40:43], v[252:255], v[200:203], v[40:43]
	v_mfma_f32_16x16x32_f16 v[36:39], v[192:195], v[200:203], v[36:39]
	s_waitcnt vmcnt(15)
	ds_write_b128 v167, v[88:91] offset:53248
	v_add_co_u32_e32 v88, vcc, s94, v160
	s_nop 1
	v_addc_co_u32_e32 v89, vcc, 0, v161, vcc
	global_load_dwordx4 v[88:91], v[88:89], off
	s_waitcnt lgkmcnt(4)
	v_mfma_f32_16x16x32_f16 v[32:35], v[244:247], v[132:135], v[32:35]
	v_mfma_f32_16x16x32_f16 v[28:31], v[248:251], v[132:135], v[28:31]
	v_mfma_f32_16x16x32_f16 v[24:27], v[252:255], v[132:135], v[24:27]
	v_mfma_f32_16x16x32_f16 v[20:23], v[192:195], v[132:135], v[20:23]
	s_waitcnt vmcnt(15)
	ds_write_b128 v167, v[96:99] offset:57344
	v_add_co_u32_e32 v96, vcc, s72, v160
	s_nop 1
	v_addc_co_u32_e32 v97, vcc, 0, v161, vcc
	global_load_dwordx4 v[96:99], v[96:97], off
	s_waitcnt lgkmcnt(4)
	v_mfma_f32_16x16x32_f16 v[16:19], v[244:247], v[204:207], v[16:19]
	v_mfma_f32_16x16x32_f16 v[12:15], v[248:251], v[204:207], v[12:15]
	v_mfma_f32_16x16x32_f16 v[8:11], v[252:255], v[204:207], v[8:11]
	v_mfma_f32_16x16x32_f16 v[4:7], v[192:195], v[204:207], v[4:7]
	s_waitcnt vmcnt(15)
	ds_write_b128 v167, v[100:103] offset:61440
	v_add_co_u32_e32 v100, vcc, s73, v160
	s_nop 1
	v_addc_co_u32_e32 v101, vcc, 0, v161, vcc
	global_load_dwordx4 v[100:103], v[100:101], off
	s_waitcnt lgkmcnt(0)
	s_barrier
	ds_read_b128 v[200:203], v168 offset:49152
	ds_read_b128 v[204:207], v168 offset:51200
	ds_read_b128 v[208:211], v168 offset:53248
	ds_read_b128 v[212:215], v168 offset:55296
	ds_read_b128 v[132:135], v170 offset:32768
	ds_read_b128 v[160:163], v170 offset:34816
	ds_read_b128 v[192:195], v170 offset:36864
	ds_read_b128 v[196:199], v170 offset:38912
	ds_read_b128 v[244:247], v243 offset:49152
	ds_read_b128 v[248:251], v243 offset:51200
	ds_read_b128 v[252:255], v243 offset:53248
	s_waitcnt lgkmcnt(6)
	v_mfma_f32_16x16x32_f16 v[64:67], v[200:203], v[132:135], v[64:67]
	v_mfma_f32_16x16x32_f16 v[60:63], v[204:207], v[132:135], v[60:63]
	v_mfma_f32_16x16x32_f16 v[56:59], v[208:211], v[132:135], v[56:59]
	v_mfma_f32_16x16x32_f16 v[52:55], v[212:215], v[132:135], v[52:55]
	ds_read_b128 v[132:135], v243 offset:55296
	s_waitcnt vmcnt(13)
	ds_write_b128 v167, v[92:95]
	global_load_dwordx4 v[92:95], v[218:219], off
	s_waitcnt lgkmcnt(7)
	v_mfma_f32_16x16x32_f16 v[48:51], v[200:203], v[160:163], v[48:51]
	v_mfma_f32_16x16x32_f16 v[44:47], v[204:207], v[160:163], v[44:47]
	v_mfma_f32_16x16x32_f16 v[40:43], v[208:211], v[160:163], v[40:43]
	v_mfma_f32_16x16x32_f16 v[36:39], v[212:215], v[160:163], v[36:39]
	ds_read_b128 v[160:163], v242 offset:32768
	ds_write_b128 v167, v[108:111] offset:4096
	v_add_co_u32_e32 v108, vcc, s94, v218
	s_nop 1
	v_addc_co_u32_e32 v109, vcc, 0, v219, vcc
	global_load_dwordx4 v[108:111], v[108:109], off
	s_waitcnt lgkmcnt(8)
	v_mfma_f32_16x16x32_f16 v[32:35], v[200:203], v[192:195], v[32:35]
	v_mfma_f32_16x16x32_f16 v[28:31], v[204:207], v[192:195], v[28:31]
	v_mfma_f32_16x16x32_f16 v[24:27], v[208:211], v[192:195], v[24:27]
	v_mfma_f32_16x16x32_f16 v[20:23], v[212:215], v[192:195], v[20:23]
	ds_read_b128 v[192:195], v242 offset:34816
	ds_write_b128 v167, v[112:115] offset:8192
	v_add_co_u32_e32 v112, vcc, s72, v218
	s_nop 1
	v_addc_co_u32_e32 v113, vcc, 0, v219, vcc
	global_load_dwordx4 v[112:115], v[112:113], off
	s_waitcnt lgkmcnt(9)
	v_mfma_f32_16x16x32_f16 v[16:19], v[200:203], v[196:199], v[16:19]
	v_mfma_f32_16x16x32_f16 v[12:15], v[204:207], v[196:199], v[12:15]
	v_mfma_f32_16x16x32_f16 v[8:11], v[208:211], v[196:199], v[8:11]
	v_mfma_f32_16x16x32_f16 v[4:7], v[212:215], v[196:199], v[4:7]
	ds_read_b128 v[196:199], v242 offset:36864
	ds_read_b128 v[200:203], v242 offset:38912
	s_waitcnt vmcnt(14)
; template <int NJ>
; __device__ __forceinline__ void gemm_tile(const f16* __restrict__ A, int lda, const f16* __restrict__ Bt, int ldb,
;                                           int K, f32x4 (&acc)[4][NJ], f16* sA, f16* sB, const int tid) {
;     ...
; #pragma unroll 1
;   for (int k0 = 0; k0 < K; k0 += 128) {
;     {
;       const int kof = (k0 + 192 < K) ? k0 + 192 : K - 64;
;       G_STEP(0, ra1, rb1, true, true, kof)
;     }
;     __syncthreads();
;     if (k0 + 64 >= K) break;
;     {
;       const int kof = (k0 + 256 < K) ? k0 + 256 : K - 64;
;       G_STEP(1, ra0, rb0, true, true, kof)
;     }
;     __syncthreads();
	ds_write_b128 v167, v[116:119] offset:12288
	v_add_co_u32_e32 v116, vcc, s73, v218
	s_nop 1
	v_addc_co_u32_e32 v117, vcc, 0, v219, vcc
	global_load_dwordx4 v[116:119], v[116:117], off
	s_waitcnt lgkmcnt(6)
	v_mfma_f32_16x16x32_f16 v[64:67], v[244:247], v[160:163], v[64:67]
	v_mfma_f32_16x16x32_f16 v[60:63], v[248:251], v[160:163], v[60:63]
	v_mfma_f32_16x16x32_f16 v[56:59], v[252:255], v[160:163], v[56:59]
	v_mfma_f32_16x16x32_f16 v[52:55], v[132:135], v[160:163], v[52:55]
	ds_write_b128 v167, v[104:107] offset:16384
	global_load_dwordx4 v[104:107], v[216:217], off
	s_waitcnt lgkmcnt(5)
	v_mfma_f32_16x16x32_f16 v[48:51], v[244:247], v[192:195], v[48:51]
	v_mfma_f32_16x16x32_f16 v[44:47], v[248:251], v[192:195], v[44:47]
	v_mfma_f32_16x16x32_f16 v[40:43], v[252:255], v[192:195], v[40:43]
	v_mfma_f32_16x16x32_f16 v[36:39], v[132:135], v[192:195], v[36:39]
	s_waitcnt vmcnt(15)
	ds_write_b128 v167, v[120:123] offset:20480
	v_add_co_u32_e32 v120, vcc, s94, v216
	s_nop 1
	v_addc_co_u32_e32 v121, vcc, 0, v217, vcc
	global_load_dwordx4 v[120:123], v[120:121], off
	s_waitcnt lgkmcnt(4)
	v_mfma_f32_16x16x32_f16 v[32:35], v[244:247], v[196:199], v[32:35]
	v_mfma_f32_16x16x32_f16 v[28:31], v[248:251], v[196:199], v[28:31]
	v_mfma_f32_16x16x32_f16 v[24:27], v[252:255], v[196:199], v[24:27]
	v_mfma_f32_16x16x32_f16 v[20:23], v[132:135], v[196:199], v[20:23]
	s_waitcnt vmcnt(15)
	ds_write_b128 v167, v[124:127] offset:24576
	v_add_co_u32_e32 v124, vcc, s72, v216
	s_nop 1
	v_addc_co_u32_e32 v125, vcc, 0, v217, vcc
	global_load_dwordx4 v[124:127], v[124:125], off
	s_waitcnt lgkmcnt(4)
	v_mfma_f32_16x16x32_f16 v[16:19], v[244:247], v[200:203], v[16:19]
	v_mfma_f32_16x16x32_f16 v[12:15], v[248:251], v[200:203], v[12:15]
	v_mfma_f32_16x16x32_f16 v[8:11], v[252:255], v[200:203], v[8:11]
	v_mfma_f32_16x16x32_f16 v[4:7], v[132:135], v[200:203], v[4:7]
	s_waitcnt vmcnt(15)
	ds_write_b128 v167, v[128:131] offset:28672
	v_add_co_u32_e32 v128, vcc, s73, v216
	s_nop 1
	v_addc_co_u32_e32 v129, vcc, 0, v217, vcc
	global_load_dwordx4 v[128:131], v[128:129], off
	s_waitcnt lgkmcnt(0)
	s_barrier
	s_cbranch_scc1 .LBB0_195
	ds_read_b128 v[204:207], v168 offset:16384
	ds_read_b128 v[208:211], v168 offset:18432
	ds_read_b128 v[212:215], v168 offset:20480
	ds_read_b128 v[216:219], v168 offset:22528
	s_add_i32 s7, s6, 0xc0
	ds_read_b128 v[192:195], v170
	ds_read_b128 v[196:199], v170 offset:2048
	s_cmpk_lt_u32 s6, 0x340
	s_cselect_b32 s42, s7, 0x3c0
	ds_read_b128 v[200:203], v170 offset:4096
	s_lshl_b64 s[8:9], s[42:43], 1
	v_lshl_add_u64 v[162:163], v[156:157], 0, s[8:9]
	ds_read_b128 v[132:135], v170 offset:6144
	ds_read_b128 v[244:247], v243 offset:16384
	ds_read_b128 v[248:251], v243 offset:18432
	ds_read_b128 v[252:255], v243 offset:20480
	s_waitcnt lgkmcnt(6)
	v_mfma_f32_16x16x32_f16 v[64:67], v[204:207], v[192:195], v[64:67]
	v_lshl_add_u64 v[160:161], v[158:159], 0, s[8:9]
	s_add_i32 s7, s6, 0x100
	s_cmpk_lt_u32 s6, 0x300
	v_mfma_f32_16x16x32_f16 v[60:63], v[208:211], v[192:195], v[60:63]
	s_cselect_b32 s42, s7, 0x3c0
	s_lshl_b64 s[8:9], s[42:43], 1
	s_add_i32 s7, s6, 0x80
	v_mfma_f32_16x16x32_f16 v[56:59], v[212:215], v[192:195], v[56:59]
	s_cmpk_lt_u32 s6, 0x380
	s_mov_b32 s6, s7
	v_mfma_f32_16x16x32_f16 v[52:55], v[216:219], v[192:195], v[52:55]
	ds_read_b128 v[192:195], v243 offset:22528
	s_waitcnt vmcnt(15)
	ds_write_b128 v167, v[68:71] offset:32768
	global_load_dwordx4 v[68:71], v[162:163], off
	s_waitcnt lgkmcnt(7)
	v_mfma_f32_16x16x32_f16 v[48:51], v[204:207], v[196:199], v[48:51]
	v_mfma_f32_16x16x32_f16 v[44:47], v[208:211], v[196:199], v[44:47]
	v_mfma_f32_16x16x32_f16 v[40:43], v[212:215], v[196:199], v[40:43]
	v_mfma_f32_16x16x32_f16 v[36:39], v[216:219], v[196:199], v[36:39]
	ds_read_b128 v[196:199], v242
	s_waitcnt vmcnt(15)
	ds_write_b128 v167, v[76:79] offset:36864
	v_add_co_u32_e32 v76, vcc, s94, v162
	s_nop 1
	v_addc_co_u32_e32 v77, vcc, 0, v163, vcc
	global_load_dwordx4 v[76:79], v[76:77], off
	s_waitcnt lgkmcnt(8)
	v_mfma_f32_16x16x32_f16 v[32:35], v[204:207], v[200:203], v[32:35]
	v_mfma_f32_16x16x32_f16 v[28:31], v[208:211], v[200:203], v[28:31]
	v_mfma_f32_16x16x32_f16 v[24:27], v[212:215], v[200:203], v[24:27]
	v_mfma_f32_16x16x32_f16 v[20:23], v[216:219], v[200:203], v[20:23]
	ds_read_b128 v[200:203], v242 offset:2048
	s_waitcnt vmcnt(15)
	ds_write_b128 v167, v[80:83] offset:40960
	v_add_co_u32_e32 v80, vcc, s72, v162
	s_nop 1
	v_addc_co_u32_e32 v81, vcc, 0, v163, vcc
	global_load_dwordx4 v[80:83], v[80:81], off
	s_waitcnt lgkmcnt(9)
	v_mfma_f32_16x16x32_f16 v[16:19], v[204:207], v[132:135], v[16:19]
	v_mfma_f32_16x16x32_f16 v[12:15], v[208:211], v[132:135], v[12:15]
	v_mfma_f32_16x16x32_f16 v[8:11], v[212:215], v[132:135], v[8:11]
	v_mfma_f32_16x16x32_f16 v[4:7], v[216:219], v[132:135], v[4:7]
	ds_read_b128 v[132:135], v242 offset:4096
	ds_read_b128 v[204:207], v242 offset:6144
	s_waitcnt vmcnt(15)
	ds_write_b128 v167, v[84:87] offset:45056
	v_add_co_u32_e32 v84, vcc, s73, v162
	s_nop 1
	v_addc_co_u32_e32 v85, vcc, 0, v163, vcc
	global_load_dwordx4 v[84:87], v[84:85], off
	s_waitcnt lgkmcnt(6)
	v_mfma_f32_16x16x32_f16 v[64:67], v[244:247], v[196:199], v[64:67]
	v_mfma_f32_16x16x32_f16 v[60:63], v[248:251], v[196:199], v[60:63]
	v_mfma_f32_16x16x32_f16 v[56:59], v[252:255], v[196:199], v[56:59]
	v_mfma_f32_16x16x32_f16 v[52:55], v[192:195], v[196:199], v[52:55]
	s_waitcnt vmcnt(15)
	ds_write_b128 v167, v[72:75] offset:49152
	global_load_dwordx4 v[72:75], v[160:161], off
	v_lshl_add_u64 v[218:219], v[156:157], 0, s[8:9]
	s_waitcnt lgkmcnt(5)
; template <int NJ>
; __device__ __forceinline__ void gemm_tile(const f16* __restrict__ A, int lda, const f16* __restrict__ Bt, int ldb,
;                                           int K, f32x4 (&acc)[4][NJ], f16* sA, f16* sB, const int tid) {
;     ...
;   G_LOAD(ra0, rb0, 0)
;   if (K > 64) G_LOAD(ra1, rb1, 64)
;   __syncthreads();
;   G_STORE(ra0, rb0, 0)
;   if (K > 128) G_LOAD(ra0, rb0, 128)
;   __syncthreads();
; #pragma unroll 1
;   for (int k0 = 0; k0 < K; k0 += 128) {
;     {
;       const int kof = (k0 + 192 < K) ? k0 + 192 : K - 64;
;       G_STEP(0, ra1, rb1, true, true, kof)
;     }
;     __syncthreads();
;     if (k0 + 64 >= K) break;
;     {
;       const int kof = (k0 + 256 < K) ? k0 + 256 : K - 64;
;       G_STEP(1, ra0, rb0, true, true, kof)
;     }
;     __syncthreads();
	v_mfma_f32_16x16x32_f16 v[48:51], v[244:247], v[200:203], v[48:51]
	v_lshl_add_u64 v[216:217], v[158:159], 0, s[8:9]
	v_mfma_f32_16x16x32_f16 v[44:47], v[248:251], v[200:203], v[44:47]
	v_mfma_f32_16x16x32_f16 v[40:43], v[252:255], v[200:203], v[40:43]
	v_mfma_f32_16x16x32_f16 v[36:39], v[192:195], v[200:203], v[36:39]
	s_waitcnt vmcnt(15)
	ds_write_b128 v167, v[88:91] offset:53248
	v_add_co_u32_e32 v88, vcc, s94, v160
	s_nop 1
	v_addc_co_u32_e32 v89, vcc, 0, v161, vcc
	global_load_dwordx4 v[88:91], v[88:89], off
	s_waitcnt lgkmcnt(4)
	v_mfma_f32_16x16x32_f16 v[32:35], v[244:247], v[132:135], v[32:35]
	v_mfma_f32_16x16x32_f16 v[28:31], v[248:251], v[132:135], v[28:31]
	v_mfma_f32_16x16x32_f16 v[24:27], v[252:255], v[132:135], v[24:27]
	v_mfma_f32_16x16x32_f16 v[20:23], v[192:195], v[132:135], v[20:23]
	s_waitcnt vmcnt(15)
	ds_write_b128 v167, v[96:99] offset:57344
	v_add_co_u32_e32 v96, vcc, s72, v160
	s_nop 1
	v_addc_co_u32_e32 v97, vcc, 0, v161, vcc
	global_load_dwordx4 v[96:99], v[96:97], off
	s_waitcnt lgkmcnt(4)
	v_mfma_f32_16x16x32_f16 v[16:19], v[244:247], v[204:207], v[16:19]
	v_mfma_f32_16x16x32_f16 v[12:15], v[248:251], v[204:207], v[12:15]
	v_mfma_f32_16x16x32_f16 v[8:11], v[252:255], v[204:207], v[8:11]
	v_mfma_f32_16x16x32_f16 v[4:7], v[192:195], v[204:207], v[4:7]
	s_waitcnt vmcnt(15)
	ds_write_b128 v167, v[100:103] offset:61440
	v_add_co_u32_e32 v100, vcc, s73, v160
	s_nop 1
	v_addc_co_u32_e32 v101, vcc, 0, v161, vcc
	global_load_dwordx4 v[100:103], v[100:101], off
	s_waitcnt lgkmcnt(0)
	s_barrier
	ds_read_b128 v[200:203], v168 offset:49152
	ds_read_b128 v[204:207], v168 offset:51200
	ds_read_b128 v[208:211], v168 offset:53248
	ds_read_b128 v[212:215], v168 offset:55296
	ds_read_b128 v[132:135], v170 offset:32768
	ds_read_b128 v[160:163], v170 offset:34816
	ds_read_b128 v[192:195], v170 offset:36864
	ds_read_b128 v[196:199], v170 offset:38912
	ds_read_b128 v[244:247], v243 offset:49152
	ds_read_b128 v[248:251], v243 offset:51200
	ds_read_b128 v[252:255], v243 offset:53248
	s_waitcnt lgkmcnt(6)
	v_mfma_f32_16x16x32_f16 v[64:67], v[200:203], v[132:135], v[64:67]
	v_mfma_f32_16x16x32_f16 v[60:63], v[204:207], v[132:135], v[60:63]
	v_mfma_f32_16x16x32_f16 v[56:59], v[208:211], v[132:135], v[56:59]
	v_mfma_f32_16x16x32_f16 v[52:55], v[212:215], v[132:135], v[52:55]
	ds_read_b128 v[132:135], v243 offset:55296
	s_waitcnt vmcnt(15)
	ds_write_b128 v167, v[92:95]
	s_waitcnt lgkmcnt(7)
	v_mfma_f32_16x16x32_f16 v[48:51], v[200:203], v[160:163], v[48:51]
	v_mfma_f32_16x16x32_f16 v[44:47], v[204:207], v[160:163], v[44:47]
	v_mfma_f32_16x16x32_f16 v[40:43], v[208:211], v[160:163], v[40:43]
	v_mfma_f32_16x16x32_f16 v[36:39], v[212:215], v[160:163], v[36:39]
	ds_read_b128 v[160:163], v242 offset:32768
	s_waitcnt vmcnt(14)
	ds_write_b128 v167, v[108:111] offset:4096
	s_waitcnt lgkmcnt(8)
	v_mfma_f32_16x16x32_f16 v[32:35], v[200:203], v[192:195], v[32:35]
	v_mfma_f32_16x16x32_f16 v[28:31], v[204:207], v[192:195], v[28:31]
	v_mfma_f32_16x16x32_f16 v[24:27], v[208:211], v[192:195], v[24:27]
	v_mfma_f32_16x16x32_f16 v[20:23], v[212:215], v[192:195], v[20:23]
	ds_read_b128 v[192:195], v242 offset:34816
	s_waitcnt vmcnt(13)
	ds_write_b128 v167, v[112:115] offset:8192
	s_waitcnt lgkmcnt(9)
	v_mfma_f32_16x16x32_f16 v[16:19], v[200:203], v[196:199], v[16:19]
	v_mfma_f32_16x16x32_f16 v[12:15], v[204:207], v[196:199], v[12:15]
	v_mfma_f32_16x16x32_f16 v[8:11], v[208:211], v[196:199], v[8:11]
	v_mfma_f32_16x16x32_f16 v[4:7], v[212:215], v[196:199], v[4:7]
	ds_read_b128 v[196:199], v242 offset:36864
	ds_read_b128 v[200:203], v242 offset:38912
	s_waitcnt vmcnt(12)
	ds_write_b128 v167, v[116:119] offset:12288
	s_waitcnt lgkmcnt(6)
	v_mfma_f32_16x16x32_f16 v[64:67], v[244:247], v[160:163], v[64:67]
	v_mfma_f32_16x16x32_f16 v[60:63], v[248:251], v[160:163], v[60:63]
	v_mfma_f32_16x16x32_f16 v[56:59], v[252:255], v[160:163], v[56:59]
	v_mfma_f32_16x16x32_f16 v[52:55], v[132:135], v[160:163], v[52:55]
	s_waitcnt vmcnt(11)
	ds_write_b128 v167, v[104:107] offset:16384
	s_waitcnt lgkmcnt(5)
	v_mfma_f32_16x16x32_f16 v[48:51], v[244:247], v[192:195], v[48:51]
	v_mfma_f32_16x16x32_f16 v[44:47], v[248:251], v[192:195], v[44:47]
	v_mfma_f32_16x16x32_f16 v[40:43], v[252:255], v[192:195], v[40:43]
	v_mfma_f32_16x16x32_f16 v[36:39], v[132:135], v[192:195], v[36:39]
	s_waitcnt vmcnt(10)
	ds_write_b128 v167, v[120:123] offset:20480
	s_waitcnt lgkmcnt(4)
	v_mfma_f32_16x16x32_f16 v[32:35], v[244:247], v[196:199], v[32:35]
	v_mfma_f32_16x16x32_f16 v[28:31], v[248:251], v[196:199], v[28:31]
	v_mfma_f32_16x16x32_f16 v[24:27], v[252:255], v[196:199], v[24:27]
	v_mfma_f32_16x16x32_f16 v[20:23], v[132:135], v[196:199], v[20:23]
	s_waitcnt vmcnt(9)
	ds_write_b128 v167, v[124:127] offset:24576
	s_waitcnt lgkmcnt(4)
	v_mfma_f32_16x16x32_f16 v[16:19], v[244:247], v[200:203], v[16:19]
	v_mfma_f32_16x16x32_f16 v[12:15], v[248:251], v[200:203], v[12:15]
	v_mfma_f32_16x16x32_f16 v[8:11], v[252:255], v[200:203], v[8:11]
	v_mfma_f32_16x16x32_f16 v[4:7], v[132:135], v[200:203], v[4:7]
	s_waitcnt vmcnt(8)
	ds_write_b128 v167, v[128:131] offset:28672
	s_waitcnt lgkmcnt(0)
	s_barrier
; template <int NJ>
; __device__ __forceinline__ void gemm_tile(const f16* __restrict__ A, int lda, const f16* __restrict__ Bt, int ldb,
;                                           int K, f32x4 (&acc)[4][NJ], f16* sA, f16* sB, const int tid) {
;     ...
;       G_STEP(0, ra1, rb1, true, true, kof)
;     }
;     __syncthreads();
;     if (k0 + 64 >= K) break;
;     {
;       const int kof = (k0 + 256 < K) ? k0 + 256 : K - 64;
;       G_STEP(1, ra0, rb0, true, true, kof)
;     }
;     __syncthreads();
	ds_read_b128 v[204:207], v168 offset:16384
	ds_read_b128 v[208:211], v168 offset:18432
	ds_read_b128 v[212:215], v168 offset:20480
	ds_read_b128 v[216:219], v168 offset:22528
	s_add_i32 s7, s6, 0xc0
	ds_read_b128 v[192:195], v170
	ds_read_b128 v[196:199], v170 offset:2048
	s_cmpk_lt_u32 s6, 0x340
	s_cselect_b32 s42, s7, 0x3c0
	ds_read_b128 v[200:203], v170 offset:4096
	s_lshl_b64 s[8:9], s[42:43], 1
	v_lshl_add_u64 v[162:163], v[156:157], 0, s[8:9]
	ds_read_b128 v[132:135], v170 offset:6144
	ds_read_b128 v[244:247], v243 offset:16384
	ds_read_b128 v[248:251], v243 offset:18432
	ds_read_b128 v[252:255], v243 offset:20480
	s_waitcnt lgkmcnt(6)
	v_mfma_f32_16x16x32_f16 v[64:67], v[204:207], v[192:195], v[64:67]
	v_lshl_add_u64 v[160:161], v[158:159], 0, s[8:9]
	s_add_i32 s7, s6, 0x100
	s_cmpk_lt_u32 s6, 0x300
	v_mfma_f32_16x16x32_f16 v[60:63], v[208:211], v[192:195], v[60:63]
	s_cselect_b32 s42, s7, 0x3c0
	s_lshl_b64 s[8:9], s[42:43], 1
	s_add_i32 s7, s6, 0x80
	v_mfma_f32_16x16x32_f16 v[56:59], v[212:215], v[192:195], v[56:59]
	s_cmpk_lt_u32 s6, 0x380
	s_mov_b32 s6, s7
	v_mfma_f32_16x16x32_f16 v[52:55], v[216:219], v[192:195], v[52:55]
	ds_read_b128 v[192:195], v243 offset:22528
	s_waitcnt vmcnt(7)
	ds_write_b128 v167, v[68:71] offset:32768
	s_waitcnt lgkmcnt(7)
	v_mfma_f32_16x16x32_f16 v[48:51], v[204:207], v[196:199], v[48:51]
	v_mfma_f32_16x16x32_f16 v[44:47], v[208:211], v[196:199], v[44:47]
	v_mfma_f32_16x16x32_f16 v[40:43], v[212:215], v[196:199], v[40:43]
	v_mfma_f32_16x16x32_f16 v[36:39], v[216:219], v[196:199], v[36:39]
	ds_read_b128 v[196:199], v242
	s_waitcnt vmcnt(6)
	ds_write_b128 v167, v[76:79] offset:36864
	s_waitcnt lgkmcnt(8)
	v_mfma_f32_16x16x32_f16 v[32:35], v[204:207], v[200:203], v[32:35]
	v_mfma_f32_16x16x32_f16 v[28:31], v[208:211], v[200:203], v[28:31]
	v_mfma_f32_16x16x32_f16 v[24:27], v[212:215], v[200:203], v[24:27]
	v_mfma_f32_16x16x32_f16 v[20:23], v[216:219], v[200:203], v[20:23]
	ds_read_b128 v[200:203], v242 offset:2048
	s_waitcnt vmcnt(5)
	ds_write_b128 v167, v[80:83] offset:40960
	s_waitcnt lgkmcnt(9)
	v_mfma_f32_16x16x32_f16 v[16:19], v[204:207], v[132:135], v[16:19]
	v_mfma_f32_16x16x32_f16 v[12:15], v[208:211], v[132:135], v[12:15]
	v_mfma_f32_16x16x32_f16 v[8:11], v[212:215], v[132:135], v[8:11]
	v_mfma_f32_16x16x32_f16 v[4:7], v[216:219], v[132:135], v[4:7]
	ds_read_b128 v[132:135], v242 offset:4096
	ds_read_b128 v[204:207], v242 offset:6144
	s_waitcnt vmcnt(4)
	ds_write_b128 v167, v[84:87] offset:45056
	s_waitcnt lgkmcnt(6)
	v_mfma_f32_16x16x32_f16 v[64:67], v[244:247], v[196:199], v[64:67]
	v_mfma_f32_16x16x32_f16 v[60:63], v[248:251], v[196:199], v[60:63]
	v_mfma_f32_16x16x32_f16 v[56:59], v[252:255], v[196:199], v[56:59]
	v_mfma_f32_16x16x32_f16 v[52:55], v[192:195], v[196:199], v[52:55]
	s_waitcnt vmcnt(3)
	ds_write_b128 v167, v[72:75] offset:49152
	v_lshl_add_u64 v[218:219], v[156:157], 0, s[8:9]
	s_waitcnt lgkmcnt(5)
	v_mfma_f32_16x16x32_f16 v[48:51], v[244:247], v[200:203], v[48:51]
	v_lshl_add_u64 v[216:217], v[158:159], 0, s[8:9]
	v_mfma_f32_16x16x32_f16 v[44:47], v[248:251], v[200:203], v[44:47]
	v_mfma_f32_16x16x32_f16 v[40:43], v[252:255], v[200:203], v[40:43]
	v_mfma_f32_16x16x32_f16 v[36:39], v[192:195], v[200:203], v[36:39]
	s_waitcnt vmcnt(2)
	ds_write_b128 v167, v[88:91] offset:53248
	s_waitcnt lgkmcnt(4)
	v_mfma_f32_16x16x32_f16 v[32:35], v[244:247], v[132:135], v[32:35]
	v_mfma_f32_16x16x32_f16 v[28:31], v[248:251], v[132:135], v[28:31]
	v_mfma_f32_16x16x32_f16 v[24:27], v[252:255], v[132:135], v[24:27]
	v_mfma_f32_16x16x32_f16 v[20:23], v[192:195], v[132:135], v[20:23]
	s_waitcnt vmcnt(1)
	ds_write_b128 v167, v[96:99] offset:57344
	s_waitcnt lgkmcnt(4)
	v_mfma_f32_16x16x32_f16 v[16:19], v[244:247], v[204:207], v[16:19]
	v_mfma_f32_16x16x32_f16 v[12:15], v[248:251], v[204:207], v[12:15]
	v_mfma_f32_16x16x32_f16 v[8:11], v[252:255], v[204:207], v[8:11]
	v_mfma_f32_16x16x32_f16 v[4:7], v[192:195], v[204:207], v[4:7]
	s_waitcnt vmcnt(0)
	ds_write_b128 v167, v[100:103] offset:61440
	s_waitcnt lgkmcnt(0)
	s_barrier
; __device__ __forceinline__ void phase_g1(const Params& p, int l, f16* smem) {
;     ...
;     } else {
; #pragma unroll
;       for (int i = 0; i < 4; ++i) {
;         int m = m0 + wm * 64 + i * 16 + (lane & 15);
; #pragma unroll
;         for (int j = 0; j < 4; ++j) {
;           int n = n0 + wn * 64 + j * 16 + 4 * (lane >> 4);
;           if (n < N1) {
;             f16x4 o;
;             o[0] = (f16)acc[i][j][0];
;             o[1] = (f16)acc[i][j][1];
;             o[2] = (f16)acc[i][j][2];
;             o[3] = (f16)acc[i][j][3];
;             *(f16x4*)(proj + (size_t)m * PJ + (n - 384)) = o;
;           }
;         }
	ds_read_b128 v[200:203], v168 offset:49152
	ds_read_b128 v[204:207], v168 offset:51200
	ds_read_b128 v[208:211], v168 offset:53248
	ds_read_b128 v[212:215], v168 offset:55296
	ds_read_b128 v[132:135], v170 offset:32768
	ds_read_b128 v[160:163], v170 offset:34816
	ds_read_b128 v[192:195], v170 offset:36864
	ds_read_b128 v[196:199], v170 offset:38912
	ds_read_b128 v[244:247], v243 offset:49152
	ds_read_b128 v[248:251], v243 offset:51200
	ds_read_b128 v[252:255], v243 offset:53248
	s_waitcnt lgkmcnt(6)
	v_mfma_f32_16x16x32_f16 v[64:67], v[200:203], v[132:135], v[64:67]
	v_mfma_f32_16x16x32_f16 v[60:63], v[204:207], v[132:135], v[60:63]
	v_mfma_f32_16x16x32_f16 v[56:59], v[208:211], v[132:135], v[56:59]
	v_mfma_f32_16x16x32_f16 v[52:55], v[212:215], v[132:135], v[52:55]
	ds_read_b128 v[132:135], v243 offset:55296
	s_waitcnt lgkmcnt(6)
	v_mfma_f32_16x16x32_f16 v[48:51], v[200:203], v[160:163], v[48:51]
	v_mfma_f32_16x16x32_f16 v[44:47], v[204:207], v[160:163], v[44:47]
	v_mfma_f32_16x16x32_f16 v[40:43], v[208:211], v[160:163], v[40:43]
	v_mfma_f32_16x16x32_f16 v[36:39], v[212:215], v[160:163], v[36:39]
	ds_read_b128 v[160:163], v242 offset:32768
	s_waitcnt lgkmcnt(6)
	v_mfma_f32_16x16x32_f16 v[32:35], v[200:203], v[192:195], v[32:35]
	v_mfma_f32_16x16x32_f16 v[28:31], v[204:207], v[192:195], v[28:31]
	v_mfma_f32_16x16x32_f16 v[24:27], v[208:211], v[192:195], v[24:27]
	v_mfma_f32_16x16x32_f16 v[20:23], v[212:215], v[192:195], v[20:23]
	ds_read_b128 v[192:195], v242 offset:34816
	s_waitcnt lgkmcnt(6)
	v_mfma_f32_16x16x32_f16 v[16:19], v[200:203], v[196:199], v[16:19]
	v_mfma_f32_16x16x32_f16 v[12:15], v[204:207], v[196:199], v[12:15]
	v_mfma_f32_16x16x32_f16 v[8:11], v[208:211], v[196:199], v[8:11]
	v_mfma_f32_16x16x32_f16 v[4:7], v[212:215], v[196:199], v[4:7]
	ds_read_b128 v[196:199], v242 offset:36864
	ds_read_b128 v[200:203], v242 offset:38912
	s_waitcnt lgkmcnt(3)
	v_mfma_f32_16x16x32_f16 v[64:67], v[244:247], v[160:163], v[64:67]
	v_mfma_f32_16x16x32_f16 v[60:63], v[248:251], v[160:163], v[60:63]
	v_mfma_f32_16x16x32_f16 v[56:59], v[252:255], v[160:163], v[56:59]
	v_mfma_f32_16x16x32_f16 v[52:55], v[132:135], v[160:163], v[52:55]
	s_waitcnt lgkmcnt(2)
	v_mfma_f32_16x16x32_f16 v[48:51], v[244:247], v[192:195], v[48:51]
	v_mfma_f32_16x16x32_f16 v[44:47], v[248:251], v[192:195], v[44:47]
	v_mfma_f32_16x16x32_f16 v[40:43], v[252:255], v[192:195], v[40:43]
	v_mfma_f32_16x16x32_f16 v[36:39], v[132:135], v[192:195], v[36:39]
	s_waitcnt lgkmcnt(1)
	v_mfma_f32_16x16x32_f16 v[32:35], v[244:247], v[196:199], v[32:35]
	v_mfma_f32_16x16x32_f16 v[28:31], v[248:251], v[196:199], v[28:31]
	v_mfma_f32_16x16x32_f16 v[24:27], v[252:255], v[196:199], v[24:27]
	v_mfma_f32_16x16x32_f16 v[20:23], v[132:135], v[196:199], v[20:23]
	s_waitcnt lgkmcnt(0)
	v_mfma_f32_16x16x32_f16 v[16:19], v[244:247], v[200:203], v[16:19]
	v_mfma_f32_16x16x32_f16 v[12:15], v[248:251], v[200:203], v[12:15]
	v_mfma_f32_16x16x32_f16 v[8:11], v[252:255], v[200:203], v[8:11]
	v_mfma_f32_16x16x32_f16 v[4:7], v[132:135], v[200:203], v[4:7]
	s_waitcnt lgkmcnt(0)
	s_setprio 0
	s_cmp_gt_i32 s21, 5
	s_mov_b64 s[6:7], -1
	s_cbranch_scc0 .LBB0_210
	s_cmp_lt_u32 s21, 9
	s_cbranch_scc1 .LBB0_232
	s_waitcnt vmcnt(15)
	v_add_u32_e32 v70, s14, v143
	v_or_b32_e32 v164, s16, v166
	v_mad_i64_i32 v[68:69], s[6:7], v70, s22, v[144:145]
	v_cmp_gt_i32_e32 vcc, s62, v164
	s_and_saveexec_b64 s[6:7], vcc
	s_cbranch_execz .LBB0_200
	s_waitcnt vmcnt(11)
	v_cvt_pk_f16_f32 v73, v66, v67
	v_cvt_pk_f16_f32 v72, v64, v65
	v_lshl_add_u64 v[74:75], v[164:165], 1, v[68:69]
	global_store_dwordx2 v[74:75], v[72:73], off offset:-768

; template <int NJ>
; __device__ __forceinline__ void gemm_tile(const f16* __restrict__ A, int lda, const f16* __restrict__ Bt, int ldb,
;                                           int K, f32x4 (&acc)[4][NJ], f16* sA, f16* sB, const int tid) {
;     ...
;   G_LOAD(ra0, rb0, 0)
;   if (K > 64) G_LOAD(ra1, rb1, 64)
;   __syncthreads();
;   G_STORE(ra0, rb0, 0)
;   if (K > 128) G_LOAD(ra0, rb0, 128)
;   __syncthreads();
; template <int NJ>
; __device__ __forceinline__ void gres_tile(const Params& p, const f16* A, int lda, const f16* W, int K, const float* mod,
;                                           bool first_in, f16* sA, f16* sB, int m0, int n0) {
;     ...
;   f32x4 acc[4][NJ];
;   zero_acc<NJ>(acc);
;   gemm_tile<NJ>(A + (size_t)m0 * lda, lda, W + (size_t)n0 * K, K, K, acc, sA, sB, TIDX(p));
.Lxm_g3:
	s_ashr_i32 s8, s12, 31
	s_lshr_b32 s8, s8, 29
	s_add_i32 s9, s12, s8
	s_lshl_b32 s8, s9, 4
	s_and_b32 s9, s9, 0x1fffff8
	s_and_b32 s8, s8, 0xffffff80
	s_sub_i32 s9, s12, s9
	s_lshl_b32 s12, s9, 7
	s_ashr_i32 s9, s8, 31
	s_lshl_b64 s[10:11], s[8:9], 11
	v_lshl_add_u64 v[154:155], v[148:149], 0, s[10:11]
	v_add_co_u32_e32 v2, vcc, s94, v154
	s_ashr_i32 s13, s12, 31
	s_nop 0
	v_addc_co_u32_e32 v3, vcc, 0, v155, vcc
	v_add_co_u32_e32 v4, vcc, s72, v154
	s_lshl_b64 s[14:15], s[12:13], 11
	s_nop 0
	v_addc_co_u32_e32 v5, vcc, 0, v155, vcc
	v_add_co_u32_e32 v6, vcc, s73, v154
	v_lshl_add_u64 v[156:157], v[150:151], 0, s[14:15]
	s_nop 0
	v_addc_co_u32_e32 v7, vcc, 0, v155, vcc
	v_add_co_u32_e32 v8, vcc, s94, v156
	global_load_dwordx4 v[16:19], v[154:155], off
	s_nop 0
	v_addc_co_u32_e32 v9, vcc, 0, v157, vcc
	v_add_co_u32_e32 v10, vcc, s72, v156
	global_load_dwordx4 v[20:23], v[2:3], off
	s_nop 0
	v_addc_co_u32_e32 v11, vcc, 0, v157, vcc
	v_add_co_u32_e32 v12, vcc, s73, v156
	global_load_dwordx4 v[24:27], v[4:5], off
	s_nop 0
	v_addc_co_u32_e32 v13, vcc, 0, v157, vcc
	global_load_dwordx4 v[28:31], v[6:7], off
	global_load_dwordx4 v[98:101], v[156:157], off
	global_load_dwordx4 v[102:105], v[8:9], off
	global_load_dwordx4 v[106:109], v[10:11], off
	global_load_dwordx4 v[110:113], v[12:13], off
	global_load_dwordx4 v[34:37], v[154:155], off offset:128
	global_load_dwordx4 v[42:45], v[2:3], off offset:128
	global_load_dwordx4 v[46:49], v[4:5], off offset:128
	global_load_dwordx4 v[50:53], v[6:7], off offset:128
	global_load_dwordx4 v[38:41], v[156:157], off offset:128
	global_load_dwordx4 v[54:57], v[8:9], off offset:128
	global_load_dwordx4 v[62:65], v[10:11], off offset:128
	global_load_dwordx4 v[66:69], v[12:13], off offset:128
	s_barrier
	global_load_dwordx4 v[74:77], v[2:3], off offset:256
	global_load_dwordx4 v[78:81], v[4:5], off offset:256
	global_load_dwordx4 v[58:61], v[154:155], off offset:256
	global_load_dwordx4 v[70:73], v[156:157], off offset:256
	global_load_dwordx4 v[82:85], v[6:7], off offset:256
	global_load_dwordx4 v[86:89], v[8:9], off offset:256
	global_load_dwordx4 v[90:93], v[10:11], off offset:256
	global_load_dwordx4 v[94:97], v[12:13], off offset:256
	v_mov_b32_e32 v2, 0
	s_mov_b32 s9, 0
	v_mov_b32_e32 v3, v2
	v_mov_b32_e32 v4, v2
	v_mov_b32_e32 v5, v2
	v_mov_b32_e32 v6, v2
	v_mov_b32_e32 v7, v2
	v_mov_b32_e32 v8, v2
	v_mov_b32_e32 v9, v2
	v_mov_b32_e32 v10, v2
	v_mov_b32_e32 v11, v2
	v_mov_b32_e32 v12, v2
	v_mov_b32_e32 v13, v2
	v_mov_b32_e32 v14, v2
	v_mov_b32_e32 v15, v2
	v_mov_b32_e32 v32, v2
	v_mov_b32_e32 v33, v2
	v_mov_b32_e32 v114, v2
	v_mov_b32_e32 v115, v2
	v_mov_b32_e32 v116, v2
	v_mov_b32_e32 v117, v2
	v_mov_b32_e32 v118, v2
	v_mov_b32_e32 v119, v2
	v_mov_b32_e32 v120, v2
	v_mov_b32_e32 v121, v2
	v_mov_b32_e32 v122, v2
	v_mov_b32_e32 v123, v2
	v_mov_b32_e32 v124, v2
	v_mov_b32_e32 v125, v2
	v_mov_b32_e32 v126, v2
	v_mov_b32_e32 v127, v2
	v_mov_b32_e32 v128, v2
	v_mov_b32_e32 v129, v2
	s_waitcnt vmcnt(23)
	ds_write_b128 v169, v[16:19]
	s_waitcnt vmcnt(22)
	ds_write_b128 v169, v[20:23] offset:4096
	s_waitcnt vmcnt(21)
	ds_write_b128 v169, v[24:27] offset:8192
	s_waitcnt vmcnt(20)
	ds_write_b128 v169, v[28:31] offset:12288
	s_waitcnt vmcnt(19)
	ds_write_b128 v169, v[98:101] offset:16384
	s_waitcnt vmcnt(18)
	ds_write_b128 v169, v[102:105] offset:20480
	s_waitcnt vmcnt(17)
	ds_write_b128 v169, v[106:109] offset:24576
	s_waitcnt vmcnt(16)
	ds_write_b128 v169, v[110:113] offset:28672
	v_mov_b32_e32 v16, v2
	v_mov_b32_e32 v17, v2
	v_mov_b32_e32 v18, v2
	v_mov_b32_e32 v19, v2
	v_mov_b32_e32 v20, v2
	v_mov_b32_e32 v21, v2
	v_mov_b32_e32 v22, v2
	v_mov_b32_e32 v23, v2
	v_mov_b32_e32 v24, v2
	v_mov_b32_e32 v25, v2
	v_mov_b32_e32 v26, v2
	v_mov_b32_e32 v27, v2
	v_mov_b32_e32 v28, v2
	v_mov_b32_e32 v29, v2
	v_mov_b32_e32 v30, v2
	v_mov_b32_e32 v31, v2
	v_mov_b32_e32 v98, v2
	v_mov_b32_e32 v99, v2
	v_mov_b32_e32 v100, v2
	v_mov_b32_e32 v101, v2
	v_mov_b32_e32 v102, v2
	v_mov_b32_e32 v103, v2
	v_mov_b32_e32 v104, v2
	v_mov_b32_e32 v105, v2
	v_mov_b32_e32 v106, v2
	v_mov_b32_e32 v107, v2
	v_mov_b32_e32 v108, v2
	v_mov_b32_e32 v109, v2
	v_mov_b32_e32 v110, v2
	v_mov_b32_e32 v111, v2
	v_mov_b32_e32 v112, v2
	v_mov_b32_e32 v113, v2
	s_waitcnt lgkmcnt(0)
	s_barrier
	s_bitcmp1_b32 s95, 8
	s_cbranch_scc0 .Lprio_1186
	s_setprio 1
; template <int NJ>
; __device__ __forceinline__ void gemm_tile(const f16* __restrict__ A, int lda, const f16* __restrict__ Bt, int ldb,
;                                           int K, f32x4 (&acc)[4][NJ], f16* sA, f16* sB, const int tid) {
;     ...
;     {
;       const int kof = (k0 + 192 < K) ? k0 + 192 : K - 64;
;       G_STEP(0, ra1, rb1, true, true, kof)
;     }
.Lprio_1186:
.LBB0_1186:
	ds_read_b128 v[208:211], v192 offset:16384
	ds_read_b128 v[212:215], v192 offset:18432
	ds_read_b128 v[216:219], v192 offset:20480
	ds_read_b128 v[220:223], v192 offset:22528
	s_add_i32 s10, s9, 0xc0
	ds_read_b128 v[196:199], v170
	ds_read_b128 v[200:203], v170 offset:2048
	s_cmpk_lt_u32 s9, 0x340
	s_cselect_b32 s42, s10, 0x3c0
	ds_read_b128 v[204:207], v170 offset:4096
	s_lshl_b64 s[10:11], s[42:43], 1
	v_lshl_add_u64 v[160:161], v[154:155], 0, s[10:11]
	ds_read_b128 v[130:133], v170 offset:6144
	ds_read_b128 v[244:247], v243 offset:16384
	ds_read_b128 v[248:251], v243 offset:18432
	ds_read_b128 v[252:255], v243 offset:20480
	s_waitcnt lgkmcnt(6)
	v_mfma_f32_16x16x32_f16 v[126:129], v[208:211], v[196:199], v[126:129]
	v_lshl_add_u64 v[158:159], v[156:157], 0, s[10:11]
	s_add_i32 s10, s9, 0x100
	s_cmpk_lt_u32 s9, 0x300
	v_mfma_f32_16x16x32_f16 v[122:125], v[212:215], v[196:199], v[122:125]
	s_cselect_b32 s42, s10, 0x3c0
	s_lshl_b64 s[10:11], s[42:43], 1
	v_mfma_f32_16x16x32_f16 v[118:121], v[216:219], v[196:199], v[118:121]
	v_mfma_f32_16x16x32_f16 v[114:117], v[220:223], v[196:199], v[114:117]
	ds_read_b128 v[196:199], v243 offset:22528
	s_waitcnt vmcnt(15)
	ds_write_b128 v169, v[34:37] offset:32768
	global_load_dwordx4 v[34:37], v[160:161], off
	s_waitcnt lgkmcnt(7)
	v_mfma_f32_16x16x32_f16 v[110:113], v[208:211], v[200:203], v[110:113]
	v_mfma_f32_16x16x32_f16 v[106:109], v[212:215], v[200:203], v[106:109]
	v_mfma_f32_16x16x32_f16 v[102:105], v[216:219], v[200:203], v[102:105]
	v_mfma_f32_16x16x32_f16 v[98:101], v[220:223], v[200:203], v[98:101]
	ds_read_b128 v[200:203], v242
	s_waitcnt vmcnt(15)
	ds_write_b128 v169, v[42:45] offset:36864
	v_add_co_u32_e32 v42, vcc, s94, v160
	s_nop 1
	v_addc_co_u32_e32 v43, vcc, 0, v161, vcc
	global_load_dwordx4 v[42:45], v[42:43], off
	s_waitcnt lgkmcnt(8)
	v_mfma_f32_16x16x32_f16 v[30:33], v[208:211], v[204:207], v[30:33]
	v_mfma_f32_16x16x32_f16 v[26:29], v[212:215], v[204:207], v[26:29]
	v_mfma_f32_16x16x32_f16 v[22:25], v[216:219], v[204:207], v[22:25]
	v_mfma_f32_16x16x32_f16 v[18:21], v[220:223], v[204:207], v[18:21]
	ds_read_b128 v[204:207], v242 offset:2048
	s_waitcnt vmcnt(15)
	ds_write_b128 v169, v[46:49] offset:40960
	v_add_co_u32_e32 v46, vcc, s72, v160
	s_nop 1
	v_addc_co_u32_e32 v47, vcc, 0, v161, vcc
	global_load_dwordx4 v[46:49], v[46:47], off
	s_waitcnt lgkmcnt(9)
	v_mfma_f32_16x16x32_f16 v[14:17], v[208:211], v[130:133], v[14:17]
	v_mfma_f32_16x16x32_f16 v[10:13], v[212:215], v[130:133], v[10:13]
	v_mfma_f32_16x16x32_f16 v[6:9], v[216:219], v[130:133], v[6:9]
	v_mfma_f32_16x16x32_f16 v[2:5], v[220:223], v[130:133], v[2:5]
	ds_read_b128 v[130:133], v242 offset:4096
	ds_read_b128 v[208:211], v242 offset:6144
	s_waitcnt vmcnt(15)
	ds_write_b128 v169, v[50:53] offset:45056
	v_add_co_u32_e32 v50, vcc, s73, v160
	s_nop 1
	v_addc_co_u32_e32 v51, vcc, 0, v161, vcc
	global_load_dwordx4 v[50:53], v[50:51], off
	s_waitcnt lgkmcnt(6)
	v_mfma_f32_16x16x32_f16 v[126:129], v[244:247], v[200:203], v[126:129]
	v_mfma_f32_16x16x32_f16 v[122:125], v[248:251], v[200:203], v[122:125]
	v_mfma_f32_16x16x32_f16 v[118:121], v[252:255], v[200:203], v[118:121]
	v_mfma_f32_16x16x32_f16 v[114:117], v[196:199], v[200:203], v[114:117]
	s_waitcnt vmcnt(15)
	ds_write_b128 v169, v[38:41] offset:49152
	global_load_dwordx4 v[38:41], v[158:159], off
	v_lshl_add_u64 v[222:223], v[154:155], 0, s[10:11]
	s_waitcnt lgkmcnt(5)
	v_mfma_f32_16x16x32_f16 v[110:113], v[244:247], v[204:207], v[110:113]
	v_lshl_add_u64 v[220:221], v[156:157], 0, s[10:11]
	s_add_i32 s10, s9, 0x80
	s_cmpk_lt_u32 s9, 0x280
	v_mfma_f32_16x16x32_f16 v[106:109], v[248:251], v[204:207], v[106:109]
	s_mov_b32 s9, s10
	v_mfma_f32_16x16x32_f16 v[102:105], v[252:255], v[204:207], v[102:105]
	v_mfma_f32_16x16x32_f16 v[98:101], v[196:199], v[204:207], v[98:101]
	s_waitcnt vmcnt(15)
	ds_write_b128 v169, v[54:57] offset:53248
	v_add_co_u32_e32 v54, vcc, s94, v158
	s_nop 1
	v_addc_co_u32_e32 v55, vcc, 0, v159, vcc
	global_load_dwordx4 v[54:57], v[54:55], off
	s_waitcnt lgkmcnt(4)
	v_mfma_f32_16x16x32_f16 v[30:33], v[244:247], v[130:133], v[30:33]
	v_mfma_f32_16x16x32_f16 v[26:29], v[248:251], v[130:133], v[26:29]
	v_mfma_f32_16x16x32_f16 v[22:25], v[252:255], v[130:133], v[22:25]
	v_mfma_f32_16x16x32_f16 v[18:21], v[196:199], v[130:133], v[18:21]
	s_waitcnt vmcnt(15)
	ds_write_b128 v169, v[62:65] offset:57344
	v_add_co_u32_e32 v62, vcc, s72, v158
	s_nop 1
	v_addc_co_u32_e32 v63, vcc, 0, v159, vcc
	global_load_dwordx4 v[62:65], v[62:63], off
	s_waitcnt lgkmcnt(4)
	v_mfma_f32_16x16x32_f16 v[14:17], v[244:247], v[208:211], v[14:17]
	v_mfma_f32_16x16x32_f16 v[10:13], v[248:251], v[208:211], v[10:13]
	v_mfma_f32_16x16x32_f16 v[6:9], v[252:255], v[208:211], v[6:9]
	v_mfma_f32_16x16x32_f16 v[2:5], v[196:199], v[208:211], v[2:5]
	s_waitcnt vmcnt(15)
	ds_write_b128 v169, v[66:69] offset:61440
	v_add_co_u32_e32 v66, vcc, s73, v158
	s_nop 1
	v_addc_co_u32_e32 v67, vcc, 0, v159, vcc
	global_load_dwordx4 v[66:69], v[66:67], off
	s_waitcnt lgkmcnt(0)
	s_barrier
; template <int NJ>
; __device__ __forceinline__ void gemm_tile(const f16* __restrict__ A, int lda, const f16* __restrict__ Bt, int ldb,
;                                           int K, f32x4 (&acc)[4][NJ], f16* sA, f16* sB, const int tid) {
;     ...
;     {
;       const int kof = (k0 + 256 < K) ? k0 + 256 : K - 64;
;       G_STEP(1, ra0, rb0, true, true, kof)
;     }
;     __syncthreads();
	ds_read_b128 v[204:207], v192 offset:49152
	ds_read_b128 v[208:211], v192 offset:51200
	ds_read_b128 v[212:215], v192 offset:53248
	ds_read_b128 v[216:219], v192 offset:55296
	ds_read_b128 v[130:133], v170 offset:32768
	ds_read_b128 v[158:161], v170 offset:34816
	ds_read_b128 v[196:199], v170 offset:36864
	ds_read_b128 v[200:203], v170 offset:38912
	ds_read_b128 v[244:247], v243 offset:49152
	ds_read_b128 v[248:251], v243 offset:51200
	ds_read_b128 v[252:255], v243 offset:53248
	s_waitcnt lgkmcnt(6)
	v_mfma_f32_16x16x32_f16 v[126:129], v[204:207], v[130:133], v[126:129]
	v_mfma_f32_16x16x32_f16 v[122:125], v[208:211], v[130:133], v[122:125]
	v_mfma_f32_16x16x32_f16 v[118:121], v[212:215], v[130:133], v[118:121]
	v_mfma_f32_16x16x32_f16 v[114:117], v[216:219], v[130:133], v[114:117]
	ds_read_b128 v[130:133], v243 offset:55296
	s_waitcnt vmcnt(13)
	ds_write_b128 v169, v[58:61]
	global_load_dwordx4 v[58:61], v[222:223], off
	s_waitcnt lgkmcnt(7)
	v_mfma_f32_16x16x32_f16 v[110:113], v[204:207], v[158:161], v[110:113]
	v_mfma_f32_16x16x32_f16 v[106:109], v[208:211], v[158:161], v[106:109]
	v_mfma_f32_16x16x32_f16 v[102:105], v[212:215], v[158:161], v[102:105]
	v_mfma_f32_16x16x32_f16 v[98:101], v[216:219], v[158:161], v[98:101]
	ds_read_b128 v[158:161], v242 offset:32768
	ds_write_b128 v169, v[74:77] offset:4096
	v_add_co_u32_e32 v74, vcc, s94, v222
	s_nop 1
	v_addc_co_u32_e32 v75, vcc, 0, v223, vcc
	global_load_dwordx4 v[74:77], v[74:75], off
	s_waitcnt lgkmcnt(8)
	v_mfma_f32_16x16x32_f16 v[30:33], v[204:207], v[196:199], v[30:33]
	v_mfma_f32_16x16x32_f16 v[26:29], v[208:211], v[196:199], v[26:29]
	v_mfma_f32_16x16x32_f16 v[22:25], v[212:215], v[196:199], v[22:25]
	v_mfma_f32_16x16x32_f16 v[18:21], v[216:219], v[196:199], v[18:21]
	ds_read_b128 v[196:199], v242 offset:34816
	ds_write_b128 v169, v[78:81] offset:8192
	v_add_co_u32_e32 v78, vcc, s72, v222
	s_nop 1
	v_addc_co_u32_e32 v79, vcc, 0, v223, vcc
	global_load_dwordx4 v[78:81], v[78:79], off
	s_waitcnt lgkmcnt(9)
	v_mfma_f32_16x16x32_f16 v[14:17], v[204:207], v[200:203], v[14:17]
	v_mfma_f32_16x16x32_f16 v[10:13], v[208:211], v[200:203], v[10:13]
	v_mfma_f32_16x16x32_f16 v[6:9], v[212:215], v[200:203], v[6:9]
	v_mfma_f32_16x16x32_f16 v[2:5], v[216:219], v[200:203], v[2:5]
	ds_read_b128 v[200:203], v242 offset:36864
	ds_read_b128 v[204:207], v242 offset:38912
	s_waitcnt vmcnt(14)
	ds_write_b128 v169, v[82:85] offset:12288
	v_add_co_u32_e32 v82, vcc, s73, v222
	s_nop 1
	v_addc_co_u32_e32 v83, vcc, 0, v223, vcc
	global_load_dwordx4 v[82:85], v[82:83], off
	s_waitcnt lgkmcnt(6)
	v_mfma_f32_16x16x32_f16 v[126:129], v[244:247], v[158:161], v[126:129]
	v_mfma_f32_16x16x32_f16 v[122:125], v[248:251], v[158:161], v[122:125]
	v_mfma_f32_16x16x32_f16 v[118:121], v[252:255], v[158:161], v[118:121]
	v_mfma_f32_16x16x32_f16 v[114:117], v[130:133], v[158:161], v[114:117]
	ds_write_b128 v169, v[70:73] offset:16384
	global_load_dwordx4 v[70:73], v[220:221], off
	s_waitcnt lgkmcnt(5)
	v_mfma_f32_16x16x32_f16 v[110:113], v[244:247], v[196:199], v[110:113]
	v_mfma_f32_16x16x32_f16 v[106:109], v[248:251], v[196:199], v[106:109]
	v_mfma_f32_16x16x32_f16 v[102:105], v[252:255], v[196:199], v[102:105]
	v_mfma_f32_16x16x32_f16 v[98:101], v[130:133], v[196:199], v[98:101]
	s_waitcnt vmcnt(15)
	ds_write_b128 v169, v[86:89] offset:20480
	v_add_co_u32_e32 v86, vcc, s94, v220
	s_nop 1
	v_addc_co_u32_e32 v87, vcc, 0, v221, vcc
	global_load_dwordx4 v[86:89], v[86:87], off
	s_waitcnt lgkmcnt(4)
	v_mfma_f32_16x16x32_f16 v[30:33], v[244:247], v[200:203], v[30:33]
	v_mfma_f32_16x16x32_f16 v[26:29], v[248:251], v[200:203], v[26:29]
	v_mfma_f32_16x16x32_f16 v[22:25], v[252:255], v[200:203], v[22:25]
	v_mfma_f32_16x16x32_f16 v[18:21], v[130:133], v[200:203], v[18:21]
	s_waitcnt vmcnt(15)
	ds_write_b128 v169, v[90:93] offset:24576
	v_add_co_u32_e32 v90, vcc, s72, v220
	s_nop 1
	v_addc_co_u32_e32 v91, vcc, 0, v221, vcc
	global_load_dwordx4 v[90:93], v[90:91], off
	s_waitcnt lgkmcnt(4)
	v_mfma_f32_16x16x32_f16 v[14:17], v[244:247], v[204:207], v[14:17]
	v_mfma_f32_16x16x32_f16 v[10:13], v[248:251], v[204:207], v[10:13]
	v_mfma_f32_16x16x32_f16 v[6:9], v[252:255], v[204:207], v[6:9]
	v_mfma_f32_16x16x32_f16 v[2:5], v[130:133], v[204:207], v[2:5]
	s_waitcnt vmcnt(15)
	ds_write_b128 v169, v[94:97] offset:28672
	v_add_co_u32_e32 v94, vcc, s73, v220
	s_nop 1
	v_addc_co_u32_e32 v95, vcc, 0, v221, vcc
	global_load_dwordx4 v[94:97], v[94:95], off
	s_waitcnt lgkmcnt(0)
	s_barrier
	s_cbranch_scc1 .LBB0_1186
; template <int NJ>
; __device__ __forceinline__ void gemm_tile(const f16* __restrict__ A, int lda, const f16* __restrict__ Bt, int ldb,
;                                           int K, f32x4 (&acc)[4][NJ], f16* sA, f16* sB, const int tid) {
;     ...
;     {
;       const int kof = (k0 + 192 < K) ? k0 + 192 : K - 64;
;       G_STEP(0, ra1, rb1, true, true, kof)
;     }
	ds_read_b128 v[208:211], v192 offset:16384
	ds_read_b128 v[212:215], v192 offset:18432
	ds_read_b128 v[216:219], v192 offset:20480
	ds_read_b128 v[220:223], v192 offset:22528
	s_add_i32 s10, s9, 0xc0
	ds_read_b128 v[196:199], v170
	ds_read_b128 v[200:203], v170 offset:2048
	s_cmpk_lt_u32 s9, 0x340
	s_cselect_b32 s42, s10, 0x3c0
	ds_read_b128 v[204:207], v170 offset:4096
	s_lshl_b64 s[10:11], s[42:43], 1
	v_lshl_add_u64 v[160:161], v[154:155], 0, s[10:11]
	ds_read_b128 v[130:133], v170 offset:6144
	ds_read_b128 v[244:247], v243 offset:16384
	ds_read_b128 v[248:251], v243 offset:18432
	ds_read_b128 v[252:255], v243 offset:20480
	s_waitcnt lgkmcnt(6)
	v_mfma_f32_16x16x32_f16 v[126:129], v[208:211], v[196:199], v[126:129]
	v_lshl_add_u64 v[158:159], v[156:157], 0, s[10:11]
	s_add_i32 s10, s9, 0x100
	s_cmpk_lt_u32 s9, 0x300
	v_mfma_f32_16x16x32_f16 v[122:125], v[212:215], v[196:199], v[122:125]
	s_cselect_b32 s42, s10, 0x3c0
	s_lshl_b64 s[10:11], s[42:43], 1
	v_mfma_f32_16x16x32_f16 v[118:121], v[216:219], v[196:199], v[118:121]
	v_mfma_f32_16x16x32_f16 v[114:117], v[220:223], v[196:199], v[114:117]
	ds_read_b128 v[196:199], v243 offset:22528
	s_waitcnt vmcnt(15)
	ds_write_b128 v169, v[34:37] offset:32768
	global_load_dwordx4 v[34:37], v[160:161], off
	s_waitcnt lgkmcnt(7)
	v_mfma_f32_16x16x32_f16 v[110:113], v[208:211], v[200:203], v[110:113]
	v_mfma_f32_16x16x32_f16 v[106:109], v[212:215], v[200:203], v[106:109]
	v_mfma_f32_16x16x32_f16 v[102:105], v[216:219], v[200:203], v[102:105]
	v_mfma_f32_16x16x32_f16 v[98:101], v[220:223], v[200:203], v[98:101]
	ds_read_b128 v[200:203], v242
	s_waitcnt vmcnt(15)
	ds_write_b128 v169, v[42:45] offset:36864
	v_add_co_u32_e32 v42, vcc, s94, v160
	s_nop 1
	v_addc_co_u32_e32 v43, vcc, 0, v161, vcc
	global_load_dwordx4 v[42:45], v[42:43], off
	s_waitcnt lgkmcnt(8)
	v_mfma_f32_16x16x32_f16 v[30:33], v[208:211], v[204:207], v[30:33]
	v_mfma_f32_16x16x32_f16 v[26:29], v[212:215], v[204:207], v[26:29]
	v_mfma_f32_16x16x32_f16 v[22:25], v[216:219], v[204:207], v[22:25]
	v_mfma_f32_16x16x32_f16 v[18:21], v[220:223], v[204:207], v[18:21]
	ds_read_b128 v[204:207], v242 offset:2048
	s_waitcnt vmcnt(15)
	ds_write_b128 v169, v[46:49] offset:40960
	v_add_co_u32_e32 v46, vcc, s72, v160
	s_nop 1
	v_addc_co_u32_e32 v47, vcc, 0, v161, vcc
	global_load_dwordx4 v[46:49], v[46:47], off
	s_waitcnt lgkmcnt(9)
	v_mfma_f32_16x16x32_f16 v[14:17], v[208:211], v[130:133], v[14:17]
	v_mfma_f32_16x16x32_f16 v[10:13], v[212:215], v[130:133], v[10:13]
	v_mfma_f32_16x16x32_f16 v[6:9], v[216:219], v[130:133], v[6:9]
	v_mfma_f32_16x16x32_f16 v[2:5], v[220:223], v[130:133], v[2:5]
	ds_read_b128 v[130:133], v242 offset:4096
	ds_read_b128 v[208:211], v242 offset:6144
	s_waitcnt vmcnt(15)
	ds_write_b128 v169, v[50:53] offset:45056
	v_add_co_u32_e32 v50, vcc, s73, v160
	s_nop 1
	v_addc_co_u32_e32 v51, vcc, 0, v161, vcc
	global_load_dwordx4 v[50:53], v[50:51], off
	s_waitcnt lgkmcnt(6)
	v_mfma_f32_16x16x32_f16 v[126:129], v[244:247], v[200:203], v[126:129]
	v_mfma_f32_16x16x32_f16 v[122:125], v[248:251], v[200:203], v[122:125]
	v_mfma_f32_16x16x32_f16 v[118:121], v[252:255], v[200:203], v[118:121]
	v_mfma_f32_16x16x32_f16 v[114:117], v[196:199], v[200:203], v[114:117]
	s_waitcnt vmcnt(15)
	ds_write_b128 v169, v[38:41] offset:49152
	global_load_dwordx4 v[38:41], v[158:159], off
	v_lshl_add_u64 v[222:223], v[154:155], 0, s[10:11]
	s_waitcnt lgkmcnt(5)
	v_mfma_f32_16x16x32_f16 v[110:113], v[244:247], v[204:207], v[110:113]
	v_lshl_add_u64 v[220:221], v[156:157], 0, s[10:11]
	s_add_i32 s10, s9, 0x80
	s_cmpk_lt_u32 s9, 0x380
	v_mfma_f32_16x16x32_f16 v[106:109], v[248:251], v[204:207], v[106:109]
	s_mov_b32 s9, s10
	v_mfma_f32_16x16x32_f16 v[102:105], v[252:255], v[204:207], v[102:105]
	v_mfma_f32_16x16x32_f16 v[98:101], v[196:199], v[204:207], v[98:101]
	s_waitcnt vmcnt(15)
	ds_write_b128 v169, v[54:57] offset:53248
	v_add_co_u32_e32 v54, vcc, s94, v158
	s_nop 1
	v_addc_co_u32_e32 v55, vcc, 0, v159, vcc
	global_load_dwordx4 v[54:57], v[54:55], off
	s_waitcnt lgkmcnt(4)
	v_mfma_f32_16x16x32_f16 v[30:33], v[244:247], v[130:133], v[30:33]
	v_mfma_f32_16x16x32_f16 v[26:29], v[248:251], v[130:133], v[26:29]
	v_mfma_f32_16x16x32_f16 v[22:25], v[252:255], v[130:133], v[22:25]
	v_mfma_f32_16x16x32_f16 v[18:21], v[196:199], v[130:133], v[18:21]
	s_waitcnt vmcnt(15)
	ds_write_b128 v169, v[62:65] offset:57344
	v_add_co_u32_e32 v62, vcc, s72, v158
	s_nop 1
	v_addc_co_u32_e32 v63, vcc, 0, v159, vcc
	global_load_dwordx4 v[62:65], v[62:63], off
	s_waitcnt lgkmcnt(4)
	v_mfma_f32_16x16x32_f16 v[14:17], v[244:247], v[208:211], v[14:17]
	v_mfma_f32_16x16x32_f16 v[10:13], v[248:251], v[208:211], v[10:13]
	v_mfma_f32_16x16x32_f16 v[6:9], v[252:255], v[208:211], v[6:9]
	v_mfma_f32_16x16x32_f16 v[2:5], v[196:199], v[208:211], v[2:5]
	s_waitcnt vmcnt(15)
	ds_write_b128 v169, v[66:69] offset:61440
	v_add_co_u32_e32 v66, vcc, s73, v158
	s_nop 1
	v_addc_co_u32_e32 v67, vcc, 0, v159, vcc
	global_load_dwordx4 v[66:69], v[66:67], off
	s_waitcnt lgkmcnt(0)
	s_barrier
; template <int NJ>
; __device__ __forceinline__ void gemm_tile(const f16* __restrict__ A, int lda, const f16* __restrict__ Bt, int ldb,
;                                           int K, f32x4 (&acc)[4][NJ], f16* sA, f16* sB, const int tid) {
;     ...
;     {
;       const int kof = (k0 + 256 < K) ? k0 + 256 : K - 64;
;       G_STEP(1, ra0, rb0, true, true, kof)
;     }
;     __syncthreads();
	ds_read_b128 v[204:207], v192 offset:49152
	ds_read_b128 v[208:211], v192 offset:51200
	ds_read_b128 v[212:215], v192 offset:53248
	ds_read_b128 v[216:219], v192 offset:55296
	ds_read_b128 v[130:133], v170 offset:32768
	ds_read_b128 v[158:161], v170 offset:34816
	ds_read_b128 v[196:199], v170 offset:36864
	ds_read_b128 v[200:203], v170 offset:38912
	ds_read_b128 v[244:247], v243 offset:49152
	ds_read_b128 v[248:251], v243 offset:51200
	ds_read_b128 v[252:255], v243 offset:53248
	s_waitcnt lgkmcnt(6)
	v_mfma_f32_16x16x32_f16 v[126:129], v[204:207], v[130:133], v[126:129]
	v_mfma_f32_16x16x32_f16 v[122:125], v[208:211], v[130:133], v[122:125]
	v_mfma_f32_16x16x32_f16 v[118:121], v[212:215], v[130:133], v[118:121]
	v_mfma_f32_16x16x32_f16 v[114:117], v[216:219], v[130:133], v[114:117]
	ds_read_b128 v[130:133], v243 offset:55296
	s_waitcnt vmcnt(15)
	ds_write_b128 v169, v[58:61]
	s_waitcnt lgkmcnt(7)
	v_mfma_f32_16x16x32_f16 v[110:113], v[204:207], v[158:161], v[110:113]
	v_mfma_f32_16x16x32_f16 v[106:109], v[208:211], v[158:161], v[106:109]
	v_mfma_f32_16x16x32_f16 v[102:105], v[212:215], v[158:161], v[102:105]
	v_mfma_f32_16x16x32_f16 v[98:101], v[216:219], v[158:161], v[98:101]
	ds_read_b128 v[158:161], v242 offset:32768
	s_waitcnt vmcnt(14)
	ds_write_b128 v169, v[74:77] offset:4096
	s_waitcnt lgkmcnt(8)
	v_mfma_f32_16x16x32_f16 v[30:33], v[204:207], v[196:199], v[30:33]
	v_mfma_f32_16x16x32_f16 v[26:29], v[208:211], v[196:199], v[26:29]
	v_mfma_f32_16x16x32_f16 v[22:25], v[212:215], v[196:199], v[22:25]
	v_mfma_f32_16x16x32_f16 v[18:21], v[216:219], v[196:199], v[18:21]
	ds_read_b128 v[196:199], v242 offset:34816
	s_waitcnt vmcnt(13)
	ds_write_b128 v169, v[78:81] offset:8192
	s_waitcnt lgkmcnt(9)
	v_mfma_f32_16x16x32_f16 v[14:17], v[204:207], v[200:203], v[14:17]
	v_mfma_f32_16x16x32_f16 v[10:13], v[208:211], v[200:203], v[10:13]
	v_mfma_f32_16x16x32_f16 v[6:9], v[212:215], v[200:203], v[6:9]
	v_mfma_f32_16x16x32_f16 v[2:5], v[216:219], v[200:203], v[2:5]
	ds_read_b128 v[200:203], v242 offset:36864
	ds_read_b128 v[204:207], v242 offset:38912
	s_waitcnt vmcnt(12)
	ds_write_b128 v169, v[82:85] offset:12288
	s_waitcnt lgkmcnt(6)
	v_mfma_f32_16x16x32_f16 v[126:129], v[244:247], v[158:161], v[126:129]
	v_mfma_f32_16x16x32_f16 v[122:125], v[248:251], v[158:161], v[122:125]
	v_mfma_f32_16x16x32_f16 v[118:121], v[252:255], v[158:161], v[118:121]
	v_mfma_f32_16x16x32_f16 v[114:117], v[130:133], v[158:161], v[114:117]
	s_waitcnt vmcnt(11)
	ds_write_b128 v169, v[70:73] offset:16384
	s_waitcnt lgkmcnt(5)
	v_mfma_f32_16x16x32_f16 v[110:113], v[244:247], v[196:199], v[110:113]
	v_mfma_f32_16x16x32_f16 v[106:109], v[248:251], v[196:199], v[106:109]
	v_mfma_f32_16x16x32_f16 v[102:105], v[252:255], v[196:199], v[102:105]
	v_mfma_f32_16x16x32_f16 v[98:101], v[130:133], v[196:199], v[98:101]
	s_waitcnt vmcnt(10)
	ds_write_b128 v169, v[86:89] offset:20480
	s_waitcnt lgkmcnt(4)
	v_mfma_f32_16x16x32_f16 v[30:33], v[244:247], v[200:203], v[30:33]
	v_mfma_f32_16x16x32_f16 v[26:29], v[248:251], v[200:203], v[26:29]
	v_mfma_f32_16x16x32_f16 v[22:25], v[252:255], v[200:203], v[22:25]
	v_mfma_f32_16x16x32_f16 v[18:21], v[130:133], v[200:203], v[18:21]
	s_waitcnt vmcnt(9)
	ds_write_b128 v169, v[90:93] offset:24576
	s_waitcnt lgkmcnt(4)
	v_mfma_f32_16x16x32_f16 v[14:17], v[244:247], v[204:207], v[14:17]
	v_mfma_f32_16x16x32_f16 v[10:13], v[248:251], v[204:207], v[10:13]
	v_mfma_f32_16x16x32_f16 v[6:9], v[252:255], v[204:207], v[6:9]
	v_mfma_f32_16x16x32_f16 v[2:5], v[130:133], v[204:207], v[2:5]
	s_waitcnt vmcnt(8)
	ds_write_b128 v169, v[94:97] offset:28672
	s_waitcnt lgkmcnt(0)
	s_barrier
	ds_read_b128 v[208:211], v192 offset:16384
	ds_read_b128 v[212:215], v192 offset:18432
	ds_read_b128 v[216:219], v192 offset:20480
	ds_read_b128 v[220:223], v192 offset:22528
	s_add_i32 s10, s9, 0xc0
	ds_read_b128 v[196:199], v170
	ds_read_b128 v[200:203], v170 offset:2048
	s_cmpk_lt_u32 s9, 0x340
	s_cselect_b32 s42, s10, 0x3c0
	ds_read_b128 v[204:207], v170 offset:4096
	s_lshl_b64 s[10:11], s[42:43], 1
	v_lshl_add_u64 v[160:161], v[154:155], 0, s[10:11]
	ds_read_b128 v[130:133], v170 offset:6144
	ds_read_b128 v[244:247], v243 offset:16384
	ds_read_b128 v[248:251], v243 offset:18432
	ds_read_b128 v[252:255], v243 offset:20480
	s_waitcnt lgkmcnt(6)
	v_mfma_f32_16x16x32_f16 v[126:129], v[208:211], v[196:199], v[126:129]
	v_lshl_add_u64 v[158:159], v[156:157], 0, s[10:11]
	s_add_i32 s10, s9, 0x100
	s_cmpk_lt_u32 s9, 0x300
	v_mfma_f32_16x16x32_f16 v[122:125], v[212:215], v[196:199], v[122:125]
	s_cselect_b32 s42, s10, 0x3c0
	s_lshl_b64 s[10:11], s[42:43], 1
	v_mfma_f32_16x16x32_f16 v[118:121], v[216:219], v[196:199], v[118:121]
	v_mfma_f32_16x16x32_f16 v[114:117], v[220:223], v[196:199], v[114:117]
	ds_read_b128 v[196:199], v243 offset:22528
	s_waitcnt vmcnt(7)
	ds_write_b128 v169, v[34:37] offset:32768
	s_waitcnt lgkmcnt(7)
	v_mfma_f32_16x16x32_f16 v[110:113], v[208:211], v[200:203], v[110:113]
	v_mfma_f32_16x16x32_f16 v[106:109], v[212:215], v[200:203], v[106:109]
	v_mfma_f32_16x16x32_f16 v[102:105], v[216:219], v[200:203], v[102:105]
	v_mfma_f32_16x16x32_f16 v[98:101], v[220:223], v[200:203], v[98:101]
	ds_read_b128 v[200:203], v242
	s_waitcnt vmcnt(6)
	ds_write_b128 v169, v[42:45] offset:36864
	s_waitcnt lgkmcnt(8)
	v_mfma_f32_16x16x32_f16 v[30:33], v[208:211], v[204:207], v[30:33]
	v_mfma_f32_16x16x32_f16 v[26:29], v[212:215], v[204:207], v[26:29]
	v_mfma_f32_16x16x32_f16 v[22:25], v[216:219], v[204:207], v[22:25]
	v_mfma_f32_16x16x32_f16 v[18:21], v[220:223], v[204:207], v[18:21]
	ds_read_b128 v[204:207], v242 offset:2048
	s_waitcnt vmcnt(5)
	ds_write_b128 v169, v[46:49] offset:40960
	s_waitcnt lgkmcnt(9)
; template <int NJ>
; __device__ __forceinline__ void gres_tile(const Params& p, const f16* A, int lda, const f16* W, int K, const float* mod,
;                                           bool first_in, f16* sA, f16* sB, int m0, int n0) {
;     ...
; #pragma unroll
;   for (int i = 0; i < 4; ++i) {
;     int m = m0 + wm * 64 + i * 16 + (lane & 15);
;     const float* xi = xrow_in(p, first_in ? 0 : 1, m);
;     float* xo = xrow_out(p, m);
;     const float* gt = mod + (size_t)modrow_of(m) * 6 * DM;
; #pragma unroll
;     for (int j = 0; j < NJ; ++j) {
;       int n = n0 + wn * (NJ * 16) + j * 16 + 4 * (lane >> 4);
;       float4 xv = *(const float4*)(xi + n);
;       float4 gv = *(const float4*)(gt + n);
	v_mfma_f32_16x16x32_f16 v[14:17], v[208:211], v[130:133], v[14:17]
	v_mfma_f32_16x16x32_f16 v[10:13], v[212:215], v[130:133], v[10:13]
	v_mfma_f32_16x16x32_f16 v[6:9], v[216:219], v[130:133], v[6:9]
	v_mfma_f32_16x16x32_f16 v[2:5], v[220:223], v[130:133], v[2:5]
	ds_read_b128 v[130:133], v242 offset:4096
	ds_read_b128 v[208:211], v242 offset:6144
	s_waitcnt vmcnt(4)
	ds_write_b128 v169, v[50:53] offset:45056
	s_waitcnt lgkmcnt(6)
	v_mfma_f32_16x16x32_f16 v[126:129], v[244:247], v[200:203], v[126:129]
	v_mfma_f32_16x16x32_f16 v[122:125], v[248:251], v[200:203], v[122:125]
	v_mfma_f32_16x16x32_f16 v[118:121], v[252:255], v[200:203], v[118:121]
	v_mfma_f32_16x16x32_f16 v[114:117], v[196:199], v[200:203], v[114:117]
	s_waitcnt vmcnt(3)
	ds_write_b128 v169, v[38:41] offset:49152
	v_lshl_add_u64 v[222:223], v[154:155], 0, s[10:11]
	s_waitcnt lgkmcnt(5)
	v_mfma_f32_16x16x32_f16 v[110:113], v[244:247], v[204:207], v[110:113]
	v_lshl_add_u64 v[220:221], v[156:157], 0, s[10:11]
	s_add_i32 s10, s9, 0x80
	s_cmpk_lt_u32 s9, 0x380
	v_mfma_f32_16x16x32_f16 v[106:109], v[248:251], v[204:207], v[106:109]
	s_mov_b32 s9, s10
	v_mfma_f32_16x16x32_f16 v[102:105], v[252:255], v[204:207], v[102:105]
	v_mfma_f32_16x16x32_f16 v[98:101], v[196:199], v[204:207], v[98:101]
	s_waitcnt vmcnt(2)
	ds_write_b128 v169, v[54:57] offset:53248
	s_waitcnt lgkmcnt(4)
	v_mfma_f32_16x16x32_f16 v[30:33], v[244:247], v[130:133], v[30:33]
	v_mfma_f32_16x16x32_f16 v[26:29], v[248:251], v[130:133], v[26:29]
	v_mfma_f32_16x16x32_f16 v[22:25], v[252:255], v[130:133], v[22:25]
	v_mfma_f32_16x16x32_f16 v[18:21], v[196:199], v[130:133], v[18:21]
	s_waitcnt vmcnt(1)
	ds_write_b128 v169, v[62:65] offset:57344
	s_waitcnt lgkmcnt(4)
	v_mfma_f32_16x16x32_f16 v[14:17], v[244:247], v[208:211], v[14:17]
	v_mfma_f32_16x16x32_f16 v[10:13], v[248:251], v[208:211], v[10:13]
	v_mfma_f32_16x16x32_f16 v[6:9], v[252:255], v[208:211], v[6:9]
	v_mfma_f32_16x16x32_f16 v[2:5], v[196:199], v[208:211], v[2:5]
	s_waitcnt vmcnt(0)
	ds_write_b128 v169, v[66:69] offset:61440
	s_waitcnt lgkmcnt(0)
	s_barrier
	ds_read_b128 v[204:207], v192 offset:49152
	ds_read_b128 v[208:211], v192 offset:51200
	ds_read_b128 v[212:215], v192 offset:53248
	ds_read_b128 v[216:219], v192 offset:55296
	ds_read_b128 v[130:133], v170 offset:32768
	ds_read_b128 v[158:161], v170 offset:34816
	ds_read_b128 v[196:199], v170 offset:36864
	ds_read_b128 v[200:203], v170 offset:38912
	ds_read_b128 v[244:247], v243 offset:49152
	ds_read_b128 v[248:251], v243 offset:51200
	ds_read_b128 v[252:255], v243 offset:53248
	s_waitcnt lgkmcnt(6)
	v_mfma_f32_16x16x32_f16 v[126:129], v[204:207], v[130:133], v[126:129]
	v_mfma_f32_16x16x32_f16 v[122:125], v[208:211], v[130:133], v[122:125]
	v_mfma_f32_16x16x32_f16 v[118:121], v[212:215], v[130:133], v[118:121]
	v_mfma_f32_16x16x32_f16 v[114:117], v[216:219], v[130:133], v[114:117]
	ds_read_b128 v[130:133], v243 offset:55296
	s_waitcnt lgkmcnt(6)
	v_mfma_f32_16x16x32_f16 v[110:113], v[204:207], v[158:161], v[110:113]
	v_mfma_f32_16x16x32_f16 v[106:109], v[208:211], v[158:161], v[106:109]
	v_mfma_f32_16x16x32_f16 v[102:105], v[212:215], v[158:161], v[102:105]
	v_mfma_f32_16x16x32_f16 v[98:101], v[216:219], v[158:161], v[98:101]
	ds_read_b128 v[158:161], v242 offset:32768
	s_waitcnt lgkmcnt(6)
	v_mfma_f32_16x16x32_f16 v[30:33], v[204:207], v[196:199], v[30:33]
	v_mfma_f32_16x16x32_f16 v[26:29], v[208:211], v[196:199], v[26:29]
	v_mfma_f32_16x16x32_f16 v[22:25], v[212:215], v[196:199], v[22:25]
	v_mfma_f32_16x16x32_f16 v[18:21], v[216:219], v[196:199], v[18:21]
	ds_read_b128 v[196:199], v242 offset:34816
	s_waitcnt lgkmcnt(6)
	v_mfma_f32_16x16x32_f16 v[14:17], v[204:207], v[200:203], v[14:17]
	v_mfma_f32_16x16x32_f16 v[10:13], v[208:211], v[200:203], v[10:13]
	v_mfma_f32_16x16x32_f16 v[6:9], v[212:215], v[200:203], v[6:9]
	v_mfma_f32_16x16x32_f16 v[2:5], v[216:219], v[200:203], v[2:5]
	ds_read_b128 v[200:203], v242 offset:36864
	ds_read_b128 v[204:207], v242 offset:38912
	s_waitcnt lgkmcnt(3)
	v_mfma_f32_16x16x32_f16 v[126:129], v[244:247], v[158:161], v[126:129]
	v_mfma_f32_16x16x32_f16 v[122:125], v[248:251], v[158:161], v[122:125]
	v_mfma_f32_16x16x32_f16 v[118:121], v[252:255], v[158:161], v[118:121]
	v_mfma_f32_16x16x32_f16 v[114:117], v[130:133], v[158:161], v[114:117]
	s_waitcnt lgkmcnt(2)
	v_mfma_f32_16x16x32_f16 v[110:113], v[244:247], v[196:199], v[110:113]
	v_mfma_f32_16x16x32_f16 v[106:109], v[248:251], v[196:199], v[106:109]
	v_mfma_f32_16x16x32_f16 v[102:105], v[252:255], v[196:199], v[102:105]
	v_mfma_f32_16x16x32_f16 v[98:101], v[130:133], v[196:199], v[98:101]
	s_waitcnt lgkmcnt(1)
	v_mfma_f32_16x16x32_f16 v[30:33], v[244:247], v[200:203], v[30:33]
	v_mfma_f32_16x16x32_f16 v[26:29], v[248:251], v[200:203], v[26:29]
	v_mfma_f32_16x16x32_f16 v[22:25], v[252:255], v[200:203], v[22:25]
	v_mfma_f32_16x16x32_f16 v[18:21], v[130:133], v[200:203], v[18:21]
	s_waitcnt lgkmcnt(0)
	v_mfma_f32_16x16x32_f16 v[14:17], v[244:247], v[204:207], v[14:17]
	v_mfma_f32_16x16x32_f16 v[10:13], v[248:251], v[204:207], v[10:13]
	v_mfma_f32_16x16x32_f16 v[6:9], v[252:255], v[204:207], v[6:9]
	v_mfma_f32_16x16x32_f16 v[2:5], v[130:133], v[204:207], v[2:5]
	s_waitcnt lgkmcnt(0)
	s_setprio 0
	s_waitcnt vmcnt(15)
	v_or_b32_e32 v34, s8, v162
	v_add_u32_e32 v34, v34, v147
	v_cmp_gt_i32_e64 s[8:9], s80, v34
	v_cmp_lt_i32_e64 s[10:11], s82, v34
	s_mov_b64 s[14:15], -1
	s_and_b64 vcc, exec, s[30:31]
	s_cbranch_vccz .LBB0_1193
	v_mov_b64_e32 v[36:37], v[0:1]
	s_and_saveexec_b64 s[14:15], s[10:11]
	s_xor_b64 s[14:15], exec, s[14:15]
	s_cbranch_execz .LBB0_1190
	v_add_u32_e32 v164, 0xffff8000, v34
	v_mov_b64_e32 v[36:37], v[152:153]
	s_waitcnt vmcnt(11)
	v_mov_b64_e32 v[38:39], v[164:165]

; template <int NJ>
; __device__ __forceinline__ void gemm_tile(const f16* __restrict__ A, int lda, const f16* __restrict__ Bt, int ldb,
;                                           int K, f32x4 (&acc)[4][NJ], f16* sA, f16* sB, const int tid) {
;     ...
;   G_LOAD(ra0, rb0, 0)
;   if (K > 64) G_LOAD(ra1, rb1, 64)
;   __syncthreads();
;   G_STORE(ra0, rb0, 0)
;   if (K > 128) G_LOAD(ra0, rb0, 128)
;   __syncthreads();
; #pragma unroll 1
;   for (int k0 = 0; k0 < K; k0 += 128) {
;     {
;       const int kof = (k0 + 192 < K) ? k0 + 192 : K - 64;
;       G_STEP(0, ra1, rb1, true, true, kof)
;     }
; __device__ __forceinline__ void phase_g4(const Params& p, f16* smem) {
;     ...
;   for (int t = blockIdx.x; t < MT * NT; t += gridDim.x) {
;     int m0 = (t / NT) * 128, nt = t % NT;
;     f32x4 acc[4][4];
;     zero_acc<4>(acc);
;     gemm_tile<4>(H2 + (size_t)m0 * DM, DM, W + (size_t)nt * 128 * DM, DM, DM, acc, sA, sB, TIDX(p));
.Lxm_done_g4:
	s_ashr_i32 s11, s10, 31
	s_lshl_b64 s[14:15], s[10:11], 11
	v_lshl_add_u64 v[138:139], v[134:135], 0, s[14:15]
	v_add_co_u32_e32 v0, vcc, s94, v138
	s_ashr_i32 s13, s12, 31
	s_nop 0
	v_addc_co_u32_e32 v1, vcc, 0, v139, vcc
	v_add_co_u32_e32 v2, vcc, s72, v138
	s_lshl_b64 s[16:17], s[12:13], 18
	s_nop 0
	v_addc_co_u32_e32 v3, vcc, 0, v139, vcc
	v_add_co_u32_e32 v4, vcc, s73, v138
	v_lshl_add_u64 v[140:141], v[136:137], 0, s[16:17]
	s_nop 0
	v_addc_co_u32_e32 v5, vcc, 0, v139, vcc
	v_add_co_u32_e32 v6, vcc, s94, v140
	global_load_dwordx4 v[14:17], v[138:139], off
	s_nop 0
	v_addc_co_u32_e32 v7, vcc, 0, v141, vcc
	v_add_co_u32_e32 v8, vcc, s72, v140
	global_load_dwordx4 v[18:21], v[0:1], off
	s_nop 0
	v_addc_co_u32_e32 v9, vcc, 0, v141, vcc
	v_add_co_u32_e32 v10, vcc, s73, v140
	global_load_dwordx4 v[22:25], v[2:3], off
	s_nop 0
	v_addc_co_u32_e32 v11, vcc, 0, v141, vcc
	global_load_dwordx4 v[26:29], v[4:5], off
	global_load_dwordx4 v[30:33], v[140:141], off
	global_load_dwordx4 v[34:37], v[6:7], off
	global_load_dwordx4 v[104:107], v[8:9], off
	global_load_dwordx4 v[108:111], v[10:11], off
	global_load_dwordx4 v[40:43], v[138:139], off offset:128
	global_load_dwordx4 v[44:47], v[140:141], off offset:128
	global_load_dwordx4 v[48:51], v[0:1], off offset:128
	global_load_dwordx4 v[52:55], v[2:3], off offset:128
	global_load_dwordx4 v[56:59], v[4:5], off offset:128
	global_load_dwordx4 v[60:63], v[6:7], off offset:128
	global_load_dwordx4 v[68:71], v[8:9], off offset:128
	global_load_dwordx4 v[72:75], v[10:11], off offset:128
	s_barrier
	global_load_dwordx4 v[80:83], v[0:1], off offset:256
	global_load_dwordx4 v[84:87], v[2:3], off offset:256
	global_load_dwordx4 v[64:67], v[138:139], off offset:256
	global_load_dwordx4 v[76:79], v[140:141], off offset:256
	global_load_dwordx4 v[88:91], v[4:5], off offset:256
	global_load_dwordx4 v[92:95], v[6:7], off offset:256
	global_load_dwordx4 v[96:99], v[8:9], off offset:256
	global_load_dwordx4 v[100:103], v[10:11], off offset:256
	v_mov_b32_e32 v0, 0
	s_mov_b32 s11, 0
	v_mov_b32_e32 v1, v0
	v_mov_b32_e32 v2, v0
	v_mov_b32_e32 v3, v0
	v_mov_b32_e32 v8, v0
	v_mov_b32_e32 v9, v0
	v_mov_b32_e32 v10, v0
	v_mov_b32_e32 v11, v0
	v_mov_b32_e32 v4, v0
	v_mov_b32_e32 v5, v0
	v_mov_b32_e32 v6, v0
	v_mov_b32_e32 v7, v0
	v_mov_b32_e32 v12, v0
	v_mov_b32_e32 v13, v0
	v_mov_b32_e32 v38, v0
	v_mov_b32_e32 v39, v0
	v_mov_b32_e32 v112, v0
	v_mov_b32_e32 v113, v0
	v_mov_b32_e32 v114, v0
	v_mov_b32_e32 v115, v0
	v_mov_b32_e32 v120, v0
	v_mov_b32_e32 v121, v0
	v_mov_b32_e32 v122, v0
	v_mov_b32_e32 v123, v0
	v_mov_b32_e32 v116, v0
	v_mov_b32_e32 v117, v0
	v_mov_b32_e32 v118, v0
	v_mov_b32_e32 v119, v0
	v_mov_b32_e32 v124, v0
	v_mov_b32_e32 v125, v0
	v_mov_b32_e32 v126, v0
	v_mov_b32_e32 v127, v0
	s_waitcnt vmcnt(23)
	ds_write_b128 v147, v[14:17]
	s_waitcnt vmcnt(19)
	ds_write_b128 v147, v[30:33] offset:16384
	ds_write_b128 v147, v[18:21] offset:4096
	ds_write_b128 v147, v[22:25] offset:8192
	ds_write_b128 v147, v[26:29] offset:12288
	s_waitcnt vmcnt(18)
	ds_write_b128 v147, v[34:37] offset:20480
	s_waitcnt vmcnt(17)
	ds_write_b128 v147, v[104:107] offset:24576
	s_waitcnt vmcnt(16)
	ds_write_b128 v147, v[108:111] offset:28672
	v_mov_b32_e32 v14, v0
	v_mov_b32_e32 v15, v0
	v_mov_b32_e32 v16, v0
	v_mov_b32_e32 v17, v0
	v_mov_b32_e32 v18, v0
	v_mov_b32_e32 v19, v0
	v_mov_b32_e32 v24, v0
	v_mov_b32_e32 v25, v0
	v_mov_b32_e32 v26, v0
	v_mov_b32_e32 v27, v0
	v_mov_b32_e32 v20, v0
	v_mov_b32_e32 v21, v0
	v_mov_b32_e32 v22, v0
	v_mov_b32_e32 v23, v0
	v_mov_b32_e32 v28, v0
	v_mov_b32_e32 v29, v0
	v_mov_b32_e32 v30, v0
	v_mov_b32_e32 v31, v0
	v_mov_b32_e32 v32, v0
	v_mov_b32_e32 v33, v0
	v_mov_b32_e32 v34, v0
	v_mov_b32_e32 v35, v0
	v_mov_b32_e32 v104, v0
	v_mov_b32_e32 v105, v0
	v_mov_b32_e32 v106, v0
	v_mov_b32_e32 v107, v0
	v_mov_b32_e32 v36, v0
	v_mov_b32_e32 v37, v0
	v_mov_b32_e32 v108, v0
	v_mov_b32_e32 v109, v0
	v_mov_b32_e32 v110, v0
	v_mov_b32_e32 v111, v0
	s_waitcnt lgkmcnt(0)
	s_barrier
	s_bitcmp1_b32 s95, 8
	s_cbranch_scc0 .Lprio_1398
	s_setprio 1
.Lprio_1398:
.LBB0_1398:
	ds_read_b128 v[166:169], v148 offset:16384
	ds_read_b128 v[192:195], v148 offset:18432
	ds_read_b128 v[196:199], v148 offset:20480
	ds_read_b128 v[200:203], v148 offset:22528
	s_add_i32 s13, s11, 0xc0
	ds_read_b128 v[152:155], v150
	ds_read_b128 v[156:159], v150 offset:2048
	s_cmpk_lt_u32 s11, 0x340
	s_cselect_b32 s42, s13, 0x3c0
	ds_read_b128 v[160:163], v150 offset:4096
	s_lshl_b64 s[14:15], s[42:43], 1
	v_lshl_add_u64 v[144:145], v[138:139], 0, s[14:15]
	ds_read_b128 v[128:131], v150 offset:6144
	ds_read_b128 v[244:247], v243 offset:16384
	ds_read_b128 v[248:251], v243 offset:18432
	ds_read_b128 v[252:255], v243 offset:20480
	s_waitcnt lgkmcnt(6)
	v_mfma_f32_16x16x32_f16 v[124:127], v[166:169], v[152:155], v[124:127]
	v_lshl_add_u64 v[142:143], v[140:141], 0, s[14:15]
	s_add_i32 s13, s11, 0x100
	s_cmpk_lt_u32 s11, 0x300
	v_mfma_f32_16x16x32_f16 v[116:119], v[192:195], v[152:155], v[116:119]
	s_cselect_b32 s42, s13, 0x3c0
	s_lshl_b64 s[14:15], s[42:43], 1
	s_add_i32 s13, s11, 0x80
	v_mfma_f32_16x16x32_f16 v[120:123], v[196:199], v[152:155], v[120:123]
	s_cmpk_lt_u32 s11, 0x280
	s_mov_b32 s11, s13
	v_mfma_f32_16x16x32_f16 v[112:115], v[200:203], v[152:155], v[112:115]
	ds_read_b128 v[152:155], v243 offset:22528
	s_waitcnt vmcnt(15)
	ds_write_b128 v147, v[40:43] offset:32768
	global_load_dwordx4 v[40:43], v[144:145], off
	s_waitcnt lgkmcnt(7)
	v_mfma_f32_16x16x32_f16 v[108:111], v[166:169], v[156:159], v[108:111]
	v_mfma_f32_16x16x32_f16 v[36:39], v[192:195], v[156:159], v[36:39]
	v_mfma_f32_16x16x32_f16 v[104:107], v[196:199], v[156:159], v[104:107]
	v_mfma_f32_16x16x32_f16 v[32:35], v[200:203], v[156:159], v[32:35]
	ds_read_b128 v[156:159], v242
	s_waitcnt vmcnt(14)
	ds_write_b128 v147, v[48:51] offset:36864
	v_add_co_u32_e32 v48, vcc, s94, v144
	s_nop 1
	v_addc_co_u32_e32 v49, vcc, 0, v145, vcc
	global_load_dwordx4 v[48:51], v[48:49], off
	s_waitcnt lgkmcnt(8)
	v_mfma_f32_16x16x32_f16 v[28:31], v[166:169], v[160:163], v[28:31]
	v_mfma_f32_16x16x32_f16 v[20:23], v[192:195], v[160:163], v[20:23]
	v_mfma_f32_16x16x32_f16 v[24:27], v[196:199], v[160:163], v[24:27]
	v_mfma_f32_16x16x32_f16 v[16:19], v[200:203], v[160:163], v[16:19]
	ds_read_b128 v[160:163], v242 offset:2048
	s_waitcnt vmcnt(14)
	ds_write_b128 v147, v[52:55] offset:40960
	v_add_co_u32_e32 v52, vcc, s72, v144
	s_nop 1
	v_addc_co_u32_e32 v53, vcc, 0, v145, vcc
	global_load_dwordx4 v[52:55], v[52:53], off
	s_waitcnt lgkmcnt(9)
	v_mfma_f32_16x16x32_f16 v[12:15], v[166:169], v[128:131], v[12:15]
	v_mfma_f32_16x16x32_f16 v[4:7], v[192:195], v[128:131], v[4:7]
	v_mfma_f32_16x16x32_f16 v[8:11], v[196:199], v[128:131], v[8:11]
	v_mfma_f32_16x16x32_f16 v[0:3], v[200:203], v[128:131], v[0:3]
	ds_read_b128 v[128:131], v242 offset:4096
	ds_read_b128 v[166:169], v242 offset:6144
	s_waitcnt vmcnt(14)
	ds_write_b128 v147, v[56:59] offset:45056
	v_add_co_u32_e32 v56, vcc, s73, v144
	s_nop 1
	v_addc_co_u32_e32 v57, vcc, 0, v145, vcc
	global_load_dwordx4 v[56:59], v[56:57], off
	s_waitcnt lgkmcnt(6)
	v_mfma_f32_16x16x32_f16 v[124:127], v[244:247], v[156:159], v[124:127]
	v_mfma_f32_16x16x32_f16 v[116:119], v[248:251], v[156:159], v[116:119]
	v_mfma_f32_16x16x32_f16 v[120:123], v[252:255], v[156:159], v[120:123]
	v_mfma_f32_16x16x32_f16 v[112:115], v[152:155], v[156:159], v[112:115]
	ds_write_b128 v147, v[44:47] offset:49152
	global_load_dwordx4 v[44:47], v[142:143], off
	v_lshl_add_u64 v[202:203], v[138:139], 0, s[14:15]
	s_waitcnt lgkmcnt(5)
	v_mfma_f32_16x16x32_f16 v[108:111], v[244:247], v[160:163], v[108:111]
	v_lshl_add_u64 v[200:201], v[140:141], 0, s[14:15]
	v_mfma_f32_16x16x32_f16 v[36:39], v[248:251], v[160:163], v[36:39]
	v_mfma_f32_16x16x32_f16 v[104:107], v[252:255], v[160:163], v[104:107]
	v_mfma_f32_16x16x32_f16 v[32:35], v[152:155], v[160:163], v[32:35]
	s_waitcnt vmcnt(15)
	ds_write_b128 v147, v[60:63] offset:53248
	v_add_co_u32_e32 v60, vcc, s94, v142
	s_nop 1
	v_addc_co_u32_e32 v61, vcc, 0, v143, vcc
	global_load_dwordx4 v[60:63], v[60:61], off
	s_waitcnt lgkmcnt(4)
	v_mfma_f32_16x16x32_f16 v[28:31], v[244:247], v[128:131], v[28:31]
	v_mfma_f32_16x16x32_f16 v[20:23], v[248:251], v[128:131], v[20:23]
	v_mfma_f32_16x16x32_f16 v[24:27], v[252:255], v[128:131], v[24:27]
	v_mfma_f32_16x16x32_f16 v[16:19], v[152:155], v[128:131], v[16:19]
	s_waitcnt vmcnt(15)
	ds_write_b128 v147, v[68:71] offset:57344
	v_add_co_u32_e32 v68, vcc, s72, v142
	s_nop 1
	v_addc_co_u32_e32 v69, vcc, 0, v143, vcc
	global_load_dwordx4 v[68:71], v[68:69], off
	s_waitcnt lgkmcnt(4)
	v_mfma_f32_16x16x32_f16 v[12:15], v[244:247], v[166:169], v[12:15]
	v_mfma_f32_16x16x32_f16 v[4:7], v[248:251], v[166:169], v[4:7]
	v_mfma_f32_16x16x32_f16 v[8:11], v[252:255], v[166:169], v[8:11]
	v_mfma_f32_16x16x32_f16 v[0:3], v[152:155], v[166:169], v[0:3]
	s_waitcnt vmcnt(15)
	ds_write_b128 v147, v[72:75] offset:61440
	v_add_co_u32_e32 v72, vcc, s73, v142
	s_nop 1
	v_addc_co_u32_e32 v73, vcc, 0, v143, vcc
	global_load_dwordx4 v[72:75], v[72:73], off
	s_waitcnt lgkmcnt(0)
	s_barrier
	ds_read_b128 v[160:163], v148 offset:49152
	ds_read_b128 v[166:169], v148 offset:51200
	ds_read_b128 v[192:195], v148 offset:53248
	ds_read_b128 v[196:199], v148 offset:55296
	ds_read_b128 v[128:131], v150 offset:32768
	ds_read_b128 v[142:145], v150 offset:34816
	ds_read_b128 v[152:155], v150 offset:36864
	ds_read_b128 v[156:159], v150 offset:38912
	ds_read_b128 v[244:247], v243 offset:49152
	ds_read_b128 v[248:251], v243 offset:51200
	ds_read_b128 v[252:255], v243 offset:53248
	s_waitcnt lgkmcnt(6)
	v_mfma_f32_16x16x32_f16 v[124:127], v[160:163], v[128:131], v[124:127]
	v_mfma_f32_16x16x32_f16 v[116:119], v[166:169], v[128:131], v[116:119]
	v_mfma_f32_16x16x32_f16 v[120:123], v[192:195], v[128:131], v[120:123]
	v_mfma_f32_16x16x32_f16 v[112:115], v[196:199], v[128:131], v[112:115]
	ds_read_b128 v[128:131], v243 offset:55296
	s_waitcnt vmcnt(13)
	ds_write_b128 v147, v[64:67]
	global_load_dwordx4 v[64:67], v[202:203], off
	s_waitcnt lgkmcnt(7)
	v_mfma_f32_16x16x32_f16 v[108:111], v[160:163], v[142:145], v[108:111]
	v_mfma_f32_16x16x32_f16 v[36:39], v[166:169], v[142:145], v[36:39]
	v_mfma_f32_16x16x32_f16 v[104:107], v[192:195], v[142:145], v[104:107]
	v_mfma_f32_16x16x32_f16 v[32:35], v[196:199], v[142:145], v[32:35]
	ds_read_b128 v[142:145], v242 offset:32768
	ds_write_b128 v147, v[80:83] offset:4096
	v_add_co_u32_e32 v80, vcc, s94, v202
	s_nop 1
	v_addc_co_u32_e32 v81, vcc, 0, v203, vcc
	global_load_dwordx4 v[80:83], v[80:81], off
	s_waitcnt lgkmcnt(8)
	v_mfma_f32_16x16x32_f16 v[28:31], v[160:163], v[152:155], v[28:31]
	v_mfma_f32_16x16x32_f16 v[20:23], v[166:169], v[152:155], v[20:23]
	v_mfma_f32_16x16x32_f16 v[24:27], v[192:195], v[152:155], v[24:27]
	v_mfma_f32_16x16x32_f16 v[16:19], v[196:199], v[152:155], v[16:19]
	ds_read_b128 v[152:155], v242 offset:34816
	ds_write_b128 v147, v[84:87] offset:8192
	v_add_co_u32_e32 v84, vcc, s72, v202
	s_nop 1
	v_addc_co_u32_e32 v85, vcc, 0, v203, vcc
	global_load_dwordx4 v[84:87], v[84:85], off
	s_waitcnt lgkmcnt(9)
	v_mfma_f32_16x16x32_f16 v[12:15], v[160:163], v[156:159], v[12:15]
	v_mfma_f32_16x16x32_f16 v[4:7], v[166:169], v[156:159], v[4:7]
	v_mfma_f32_16x16x32_f16 v[8:11], v[192:195], v[156:159], v[8:11]
	v_mfma_f32_16x16x32_f16 v[0:3], v[196:199], v[156:159], v[0:3]
	ds_read_b128 v[156:159], v242 offset:36864
	ds_read_b128 v[160:163], v242 offset:38912
	s_waitcnt vmcnt(14)
; template <int NJ>
; __device__ __forceinline__ void gemm_tile(const f16* __restrict__ A, int lda, const f16* __restrict__ Bt, int ldb,
;                                           int K, f32x4 (&acc)[4][NJ], f16* sA, f16* sB, const int tid) {
;     ...
;     __syncthreads();
;     if (k0 + 64 >= K) break;
;     {
;       const int kof = (k0 + 256 < K) ? k0 + 256 : K - 64;
;       G_STEP(1, ra0, rb0, true, true, kof)
;     }
;     __syncthreads();
	ds_write_b128 v147, v[88:91] offset:12288
	v_add_co_u32_e32 v88, vcc, s73, v202
	s_nop 1
	v_addc_co_u32_e32 v89, vcc, 0, v203, vcc
	global_load_dwordx4 v[88:91], v[88:89], off
	s_waitcnt lgkmcnt(6)
	v_mfma_f32_16x16x32_f16 v[124:127], v[244:247], v[142:145], v[124:127]
	v_mfma_f32_16x16x32_f16 v[116:119], v[248:251], v[142:145], v[116:119]
	v_mfma_f32_16x16x32_f16 v[120:123], v[252:255], v[142:145], v[120:123]
	v_mfma_f32_16x16x32_f16 v[112:115], v[128:131], v[142:145], v[112:115]
	ds_write_b128 v147, v[76:79] offset:16384
	global_load_dwordx4 v[76:79], v[200:201], off
	s_waitcnt lgkmcnt(5)
	v_mfma_f32_16x16x32_f16 v[108:111], v[244:247], v[152:155], v[108:111]
	v_mfma_f32_16x16x32_f16 v[36:39], v[248:251], v[152:155], v[36:39]
	v_mfma_f32_16x16x32_f16 v[104:107], v[252:255], v[152:155], v[104:107]
	v_mfma_f32_16x16x32_f16 v[32:35], v[128:131], v[152:155], v[32:35]
	s_waitcnt vmcnt(15)
	ds_write_b128 v147, v[92:95] offset:20480
	v_add_co_u32_e32 v92, vcc, s94, v200
	s_nop 1
	v_addc_co_u32_e32 v93, vcc, 0, v201, vcc
	global_load_dwordx4 v[92:95], v[92:93], off
	s_waitcnt lgkmcnt(4)
	v_mfma_f32_16x16x32_f16 v[28:31], v[244:247], v[156:159], v[28:31]
	v_mfma_f32_16x16x32_f16 v[20:23], v[248:251], v[156:159], v[20:23]
	v_mfma_f32_16x16x32_f16 v[24:27], v[252:255], v[156:159], v[24:27]
	v_mfma_f32_16x16x32_f16 v[16:19], v[128:131], v[156:159], v[16:19]
	s_waitcnt vmcnt(15)
	ds_write_b128 v147, v[96:99] offset:24576
	v_add_co_u32_e32 v96, vcc, s72, v200
	s_nop 1
	v_addc_co_u32_e32 v97, vcc, 0, v201, vcc
	global_load_dwordx4 v[96:99], v[96:97], off
	s_waitcnt lgkmcnt(4)
	v_mfma_f32_16x16x32_f16 v[12:15], v[244:247], v[160:163], v[12:15]
	v_mfma_f32_16x16x32_f16 v[4:7], v[248:251], v[160:163], v[4:7]
	v_mfma_f32_16x16x32_f16 v[8:11], v[252:255], v[160:163], v[8:11]
	v_mfma_f32_16x16x32_f16 v[0:3], v[128:131], v[160:163], v[0:3]
	s_waitcnt vmcnt(15)
	ds_write_b128 v147, v[100:103] offset:28672
	v_add_co_u32_e32 v100, vcc, s73, v200
	s_nop 1
	v_addc_co_u32_e32 v101, vcc, 0, v201, vcc
	global_load_dwordx4 v[100:103], v[100:101], off
	s_waitcnt lgkmcnt(0)
	s_barrier
	s_cbranch_scc1 .LBB0_1398
	ds_read_b128 v[166:169], v148 offset:16384
	ds_read_b128 v[192:195], v148 offset:18432
	ds_read_b128 v[196:199], v148 offset:20480
	ds_read_b128 v[200:203], v148 offset:22528
	s_add_i32 s13, s11, 0xc0
	ds_read_b128 v[152:155], v150
	ds_read_b128 v[156:159], v150 offset:2048
	s_cmpk_lt_u32 s11, 0x340
	s_cselect_b32 s42, s13, 0x3c0
	ds_read_b128 v[160:163], v150 offset:4096
	s_lshl_b64 s[14:15], s[42:43], 1
	v_lshl_add_u64 v[144:145], v[138:139], 0, s[14:15]
	ds_read_b128 v[128:131], v150 offset:6144
	ds_read_b128 v[244:247], v243 offset:16384
	ds_read_b128 v[248:251], v243 offset:18432
	ds_read_b128 v[252:255], v243 offset:20480
	s_waitcnt lgkmcnt(6)
	v_mfma_f32_16x16x32_f16 v[124:127], v[166:169], v[152:155], v[124:127]
	v_lshl_add_u64 v[142:143], v[140:141], 0, s[14:15]
	s_add_i32 s13, s11, 0x100
	s_cmpk_lt_u32 s11, 0x300
	v_mfma_f32_16x16x32_f16 v[116:119], v[192:195], v[152:155], v[116:119]
	s_cselect_b32 s42, s13, 0x3c0
	s_lshl_b64 s[14:15], s[42:43], 1
	s_add_i32 s13, s11, 0x80
	v_mfma_f32_16x16x32_f16 v[120:123], v[196:199], v[152:155], v[120:123]
	s_cmpk_lt_u32 s11, 0x380
	s_mov_b32 s11, s13
	v_mfma_f32_16x16x32_f16 v[112:115], v[200:203], v[152:155], v[112:115]
	ds_read_b128 v[152:155], v243 offset:22528
	s_waitcnt vmcnt(15)
	ds_write_b128 v147, v[40:43] offset:32768
	global_load_dwordx4 v[40:43], v[144:145], off
	s_waitcnt lgkmcnt(7)
	v_mfma_f32_16x16x32_f16 v[108:111], v[166:169], v[156:159], v[108:111]
	v_mfma_f32_16x16x32_f16 v[36:39], v[192:195], v[156:159], v[36:39]
	v_mfma_f32_16x16x32_f16 v[104:107], v[196:199], v[156:159], v[104:107]
	v_mfma_f32_16x16x32_f16 v[32:35], v[200:203], v[156:159], v[32:35]
	ds_read_b128 v[156:159], v242
	s_waitcnt vmcnt(15)
	ds_write_b128 v147, v[48:51] offset:36864
	v_add_co_u32_e32 v48, vcc, s94, v144
	s_nop 1
	v_addc_co_u32_e32 v49, vcc, 0, v145, vcc
	global_load_dwordx4 v[48:51], v[48:49], off
	s_waitcnt lgkmcnt(8)
	v_mfma_f32_16x16x32_f16 v[28:31], v[166:169], v[160:163], v[28:31]
	v_mfma_f32_16x16x32_f16 v[20:23], v[192:195], v[160:163], v[20:23]
	v_mfma_f32_16x16x32_f16 v[24:27], v[196:199], v[160:163], v[24:27]
	v_mfma_f32_16x16x32_f16 v[16:19], v[200:203], v[160:163], v[16:19]
	ds_read_b128 v[160:163], v242 offset:2048
	s_waitcnt vmcnt(15)
	ds_write_b128 v147, v[52:55] offset:40960
	v_add_co_u32_e32 v52, vcc, s72, v144
	s_nop 1
	v_addc_co_u32_e32 v53, vcc, 0, v145, vcc
	global_load_dwordx4 v[52:55], v[52:53], off
	s_waitcnt lgkmcnt(9)
	v_mfma_f32_16x16x32_f16 v[12:15], v[166:169], v[128:131], v[12:15]
	v_mfma_f32_16x16x32_f16 v[4:7], v[192:195], v[128:131], v[4:7]
	v_mfma_f32_16x16x32_f16 v[8:11], v[196:199], v[128:131], v[8:11]
	v_mfma_f32_16x16x32_f16 v[0:3], v[200:203], v[128:131], v[0:3]
	ds_read_b128 v[128:131], v242 offset:4096
	ds_read_b128 v[166:169], v242 offset:6144
	s_waitcnt vmcnt(15)
	ds_write_b128 v147, v[56:59] offset:45056
	v_add_co_u32_e32 v56, vcc, s73, v144
	s_nop 1
	v_addc_co_u32_e32 v57, vcc, 0, v145, vcc
	global_load_dwordx4 v[56:59], v[56:57], off
	s_waitcnt lgkmcnt(6)
	v_mfma_f32_16x16x32_f16 v[124:127], v[244:247], v[156:159], v[124:127]
	v_mfma_f32_16x16x32_f16 v[116:119], v[248:251], v[156:159], v[116:119]
	v_mfma_f32_16x16x32_f16 v[120:123], v[252:255], v[156:159], v[120:123]
	v_mfma_f32_16x16x32_f16 v[112:115], v[152:155], v[156:159], v[112:115]
	s_waitcnt vmcnt(15)
	ds_write_b128 v147, v[44:47] offset:49152
	global_load_dwordx4 v[44:47], v[142:143], off
	v_lshl_add_u64 v[202:203], v[138:139], 0, s[14:15]
	s_waitcnt lgkmcnt(5)
	v_mfma_f32_16x16x32_f16 v[108:111], v[244:247], v[160:163], v[108:111]
	v_lshl_add_u64 v[200:201], v[140:141], 0, s[14:15]
	v_mfma_f32_16x16x32_f16 v[36:39], v[248:251], v[160:163], v[36:39]
	v_mfma_f32_16x16x32_f16 v[104:107], v[252:255], v[160:163], v[104:107]
	v_mfma_f32_16x16x32_f16 v[32:35], v[152:155], v[160:163], v[32:35]
	s_waitcnt vmcnt(15)
	ds_write_b128 v147, v[60:63] offset:53248
	v_add_co_u32_e32 v60, vcc, s94, v142
	s_nop 1
	v_addc_co_u32_e32 v61, vcc, 0, v143, vcc
	global_load_dwordx4 v[60:63], v[60:61], off
	s_waitcnt lgkmcnt(4)
	v_mfma_f32_16x16x32_f16 v[28:31], v[244:247], v[128:131], v[28:31]
	v_mfma_f32_16x16x32_f16 v[20:23], v[248:251], v[128:131], v[20:23]
	v_mfma_f32_16x16x32_f16 v[24:27], v[252:255], v[128:131], v[24:27]
	v_mfma_f32_16x16x32_f16 v[16:19], v[152:155], v[128:131], v[16:19]
	s_waitcnt vmcnt(15)
	ds_write_b128 v147, v[68:71] offset:57344
	v_add_co_u32_e32 v68, vcc, s72, v142
	s_nop 1
	v_addc_co_u32_e32 v69, vcc, 0, v143, vcc
	global_load_dwordx4 v[68:71], v[68:69], off
	s_waitcnt lgkmcnt(4)
	v_mfma_f32_16x16x32_f16 v[12:15], v[244:247], v[166:169], v[12:15]
	v_mfma_f32_16x16x32_f16 v[4:7], v[248:251], v[166:169], v[4:7]
	v_mfma_f32_16x16x32_f16 v[8:11], v[252:255], v[166:169], v[8:11]
	v_mfma_f32_16x16x32_f16 v[0:3], v[152:155], v[166:169], v[0:3]
	s_waitcnt vmcnt(15)
	ds_write_b128 v147, v[72:75] offset:61440
	v_add_co_u32_e32 v72, vcc, s73, v142
	s_nop 1
	v_addc_co_u32_e32 v73, vcc, 0, v143, vcc
	global_load_dwordx4 v[72:75], v[72:73], off
	s_waitcnt lgkmcnt(0)
	s_barrier
	ds_read_b128 v[160:163], v148 offset:49152
	ds_read_b128 v[166:169], v148 offset:51200
	ds_read_b128 v[192:195], v148 offset:53248
	ds_read_b128 v[196:199], v148 offset:55296
	ds_read_b128 v[128:131], v150 offset:32768
	ds_read_b128 v[142:145], v150 offset:34816
	ds_read_b128 v[152:155], v150 offset:36864
	ds_read_b128 v[156:159], v150 offset:38912
	ds_read_b128 v[244:247], v243 offset:49152
	ds_read_b128 v[248:251], v243 offset:51200
	ds_read_b128 v[252:255], v243 offset:53248
	s_waitcnt lgkmcnt(6)
	v_mfma_f32_16x16x32_f16 v[124:127], v[160:163], v[128:131], v[124:127]
	v_mfma_f32_16x16x32_f16 v[116:119], v[166:169], v[128:131], v[116:119]
	v_mfma_f32_16x16x32_f16 v[120:123], v[192:195], v[128:131], v[120:123]
	v_mfma_f32_16x16x32_f16 v[112:115], v[196:199], v[128:131], v[112:115]
	ds_read_b128 v[128:131], v243 offset:55296
	s_waitcnt vmcnt(15)
	ds_write_b128 v147, v[64:67]
	s_waitcnt lgkmcnt(7)
	v_mfma_f32_16x16x32_f16 v[108:111], v[160:163], v[142:145], v[108:111]
	v_mfma_f32_16x16x32_f16 v[36:39], v[166:169], v[142:145], v[36:39]
	v_mfma_f32_16x16x32_f16 v[104:107], v[192:195], v[142:145], v[104:107]
	v_mfma_f32_16x16x32_f16 v[32:35], v[196:199], v[142:145], v[32:35]
	ds_read_b128 v[142:145], v242 offset:32768
	s_waitcnt vmcnt(14)
	ds_write_b128 v147, v[80:83] offset:4096
	s_waitcnt lgkmcnt(8)
	v_mfma_f32_16x16x32_f16 v[28:31], v[160:163], v[152:155], v[28:31]
	v_mfma_f32_16x16x32_f16 v[20:23], v[166:169], v[152:155], v[20:23]
	v_mfma_f32_16x16x32_f16 v[24:27], v[192:195], v[152:155], v[24:27]
	v_mfma_f32_16x16x32_f16 v[16:19], v[196:199], v[152:155], v[16:19]
	ds_read_b128 v[152:155], v242 offset:34816
	s_waitcnt vmcnt(13)
	ds_write_b128 v147, v[84:87] offset:8192
	s_waitcnt lgkmcnt(9)
	v_mfma_f32_16x16x32_f16 v[12:15], v[160:163], v[156:159], v[12:15]
	v_mfma_f32_16x16x32_f16 v[4:7], v[166:169], v[156:159], v[4:7]
	v_mfma_f32_16x16x32_f16 v[8:11], v[192:195], v[156:159], v[8:11]
	v_mfma_f32_16x16x32_f16 v[0:3], v[196:199], v[156:159], v[0:3]
	ds_read_b128 v[156:159], v242 offset:36864
	ds_read_b128 v[160:163], v242 offset:38912
	s_waitcnt vmcnt(12)
	ds_write_b128 v147, v[88:91] offset:12288
	s_waitcnt lgkmcnt(6)
	v_mfma_f32_16x16x32_f16 v[124:127], v[244:247], v[142:145], v[124:127]
	v_mfma_f32_16x16x32_f16 v[116:119], v[248:251], v[142:145], v[116:119]
	v_mfma_f32_16x16x32_f16 v[120:123], v[252:255], v[142:145], v[120:123]
	v_mfma_f32_16x16x32_f16 v[112:115], v[128:131], v[142:145], v[112:115]
	s_waitcnt vmcnt(11)
	ds_write_b128 v147, v[76:79] offset:16384
	s_waitcnt lgkmcnt(5)
	v_mfma_f32_16x16x32_f16 v[108:111], v[244:247], v[152:155], v[108:111]
	v_mfma_f32_16x16x32_f16 v[36:39], v[248:251], v[152:155], v[36:39]
	v_mfma_f32_16x16x32_f16 v[104:107], v[252:255], v[152:155], v[104:107]
	v_mfma_f32_16x16x32_f16 v[32:35], v[128:131], v[152:155], v[32:35]
	s_waitcnt vmcnt(10)
	ds_write_b128 v147, v[92:95] offset:20480
	s_waitcnt lgkmcnt(4)
	v_mfma_f32_16x16x32_f16 v[28:31], v[244:247], v[156:159], v[28:31]
	v_mfma_f32_16x16x32_f16 v[20:23], v[248:251], v[156:159], v[20:23]
	v_mfma_f32_16x16x32_f16 v[24:27], v[252:255], v[156:159], v[24:27]
	v_mfma_f32_16x16x32_f16 v[16:19], v[128:131], v[156:159], v[16:19]
	s_waitcnt vmcnt(9)
	ds_write_b128 v147, v[96:99] offset:24576
	s_waitcnt lgkmcnt(4)
	v_mfma_f32_16x16x32_f16 v[12:15], v[244:247], v[160:163], v[12:15]
	v_mfma_f32_16x16x32_f16 v[4:7], v[248:251], v[160:163], v[4:7]
	v_mfma_f32_16x16x32_f16 v[8:11], v[252:255], v[160:163], v[8:11]
	v_mfma_f32_16x16x32_f16 v[0:3], v[128:131], v[160:163], v[0:3]
	s_waitcnt vmcnt(8)
	ds_write_b128 v147, v[100:103] offset:28672
	s_waitcnt lgkmcnt(0)
	s_barrier
	ds_read_b128 v[166:169], v148 offset:16384
	ds_read_b128 v[192:195], v148 offset:18432
	ds_read_b128 v[196:199], v148 offset:20480
	ds_read_b128 v[200:203], v148 offset:22528
	s_add_i32 s13, s11, 0xc0
	ds_read_b128 v[152:155], v150
	ds_read_b128 v[156:159], v150 offset:2048
	s_cmpk_lt_u32 s11, 0x340
	s_cselect_b32 s42, s13, 0x3c0
	ds_read_b128 v[160:163], v150 offset:4096
	s_lshl_b64 s[14:15], s[42:43], 1
	v_lshl_add_u64 v[144:145], v[138:139], 0, s[14:15]
	ds_read_b128 v[128:131], v150 offset:6144
	ds_read_b128 v[244:247], v243 offset:16384
	ds_read_b128 v[248:251], v243 offset:18432
	ds_read_b128 v[252:255], v243 offset:20480
	s_waitcnt lgkmcnt(6)
	v_mfma_f32_16x16x32_f16 v[124:127], v[166:169], v[152:155], v[124:127]
	v_lshl_add_u64 v[142:143], v[140:141], 0, s[14:15]
	s_add_i32 s13, s11, 0x100
	s_cmpk_lt_u32 s11, 0x300
	v_mfma_f32_16x16x32_f16 v[116:119], v[192:195], v[152:155], v[116:119]
	s_cselect_b32 s42, s13, 0x3c0
	s_lshl_b64 s[14:15], s[42:43], 1
	s_add_i32 s13, s11, 0x80
	v_mfma_f32_16x16x32_f16 v[120:123], v[196:199], v[152:155], v[120:123]
	s_cmpk_lt_u32 s11, 0x380
	s_mov_b32 s11, s13
	v_mfma_f32_16x16x32_f16 v[112:115], v[200:203], v[152:155], v[112:115]
	ds_read_b128 v[152:155], v243 offset:22528
	s_waitcnt vmcnt(7)
	ds_write_b128 v147, v[40:43] offset:32768
	s_waitcnt lgkmcnt(7)
	v_mfma_f32_16x16x32_f16 v[108:111], v[166:169], v[156:159], v[108:111]
	v_mfma_f32_16x16x32_f16 v[36:39], v[192:195], v[156:159], v[36:39]
	v_mfma_f32_16x16x32_f16 v[104:107], v[196:199], v[156:159], v[104:107]
	v_mfma_f32_16x16x32_f16 v[32:35], v[200:203], v[156:159], v[32:35]
	ds_read_b128 v[156:159], v242
	s_waitcnt vmcnt(6)
	ds_write_b128 v147, v[48:51] offset:36864
	s_waitcnt lgkmcnt(8)
	v_mfma_f32_16x16x32_f16 v[28:31], v[166:169], v[160:163], v[28:31]
	v_mfma_f32_16x16x32_f16 v[20:23], v[192:195], v[160:163], v[20:23]
	v_mfma_f32_16x16x32_f16 v[24:27], v[196:199], v[160:163], v[24:27]
	v_mfma_f32_16x16x32_f16 v[16:19], v[200:203], v[160:163], v[16:19]
	ds_read_b128 v[160:163], v242 offset:2048
	s_waitcnt vmcnt(5)
	ds_write_b128 v147, v[52:55] offset:40960
	s_waitcnt lgkmcnt(9)
	v_mfma_f32_16x16x32_f16 v[12:15], v[166:169], v[128:131], v[12:15]
	v_mfma_f32_16x16x32_f16 v[4:7], v[192:195], v[128:131], v[4:7]
	v_mfma_f32_16x16x32_f16 v[8:11], v[196:199], v[128:131], v[8:11]
	v_mfma_f32_16x16x32_f16 v[0:3], v[200:203], v[128:131], v[0:3]
	ds_read_b128 v[128:131], v242 offset:4096
	ds_read_b128 v[166:169], v242 offset:6144
	s_waitcnt vmcnt(4)
	ds_write_b128 v147, v[56:59] offset:45056
	s_waitcnt lgkmcnt(6)
	v_mfma_f32_16x16x32_f16 v[124:127], v[244:247], v[156:159], v[124:127]
	v_mfma_f32_16x16x32_f16 v[116:119], v[248:251], v[156:159], v[116:119]
	v_mfma_f32_16x16x32_f16 v[120:123], v[252:255], v[156:159], v[120:123]
	v_mfma_f32_16x16x32_f16 v[112:115], v[152:155], v[156:159], v[112:115]
	s_waitcnt vmcnt(3)
	ds_write_b128 v147, v[44:47] offset:49152
	v_lshl_add_u64 v[202:203], v[138:139], 0, s[14:15]
	s_waitcnt lgkmcnt(5)
	v_mfma_f32_16x16x32_f16 v[108:111], v[244:247], v[160:163], v[108:111]
	v_lshl_add_u64 v[200:201], v[140:141], 0, s[14:15]
	v_mfma_f32_16x16x32_f16 v[36:39], v[248:251], v[160:163], v[36:39]
	v_mfma_f32_16x16x32_f16 v[104:107], v[252:255], v[160:163], v[104:107]
	v_mfma_f32_16x16x32_f16 v[32:35], v[152:155], v[160:163], v[32:35]
	s_waitcnt vmcnt(2)
	ds_write_b128 v147, v[60:63] offset:53248
	s_waitcnt lgkmcnt(4)
	v_mfma_f32_16x16x32_f16 v[28:31], v[244:247], v[128:131], v[28:31]
	v_mfma_f32_16x16x32_f16 v[20:23], v[248:251], v[128:131], v[20:23]
	v_mfma_f32_16x16x32_f16 v[24:27], v[252:255], v[128:131], v[24:27]
	v_mfma_f32_16x16x32_f16 v[16:19], v[152:155], v[128:131], v[16:19]
	s_waitcnt vmcnt(1)
	ds_write_b128 v147, v[68:71] offset:57344
	s_waitcnt lgkmcnt(4)
	v_mfma_f32_16x16x32_f16 v[12:15], v[244:247], v[166:169], v[12:15]
	v_mfma_f32_16x16x32_f16 v[4:7], v[248:251], v[166:169], v[4:7]
	v_mfma_f32_16x16x32_f16 v[8:11], v[252:255], v[166:169], v[8:11]
	v_mfma_f32_16x16x32_f16 v[0:3], v[152:155], v[166:169], v[0:3]
	s_waitcnt vmcnt(0)
	ds_write_b128 v147, v[72:75] offset:61440
	s_waitcnt lgkmcnt(0)
	s_barrier
	ds_read_b128 v[160:163], v148 offset:49152
	ds_read_b128 v[166:169], v148 offset:51200
	ds_read_b128 v[192:195], v148 offset:53248
	ds_read_b128 v[196:199], v148 offset:55296
	ds_read_b128 v[128:131], v150 offset:32768
	ds_read_b128 v[142:145], v150 offset:34816
	ds_read_b128 v[152:155], v150 offset:36864
	ds_read_b128 v[156:159], v150 offset:38912
	ds_read_b128 v[244:247], v243 offset:49152
	ds_read_b128 v[248:251], v243 offset:51200
	ds_read_b128 v[252:255], v243 offset:53248
	s_waitcnt lgkmcnt(6)
	v_mfma_f32_16x16x32_f16 v[124:127], v[160:163], v[128:131], v[124:127]
	v_mfma_f32_16x16x32_f16 v[116:119], v[166:169], v[128:131], v[116:119]
	v_mfma_f32_16x16x32_f16 v[120:123], v[192:195], v[128:131], v[120:123]
	v_mfma_f32_16x16x32_f16 v[112:115], v[196:199], v[128:131], v[112:115]
	ds_read_b128 v[128:131], v243 offset:55296
	s_waitcnt lgkmcnt(6)
	v_mfma_f32_16x16x32_f16 v[108:111], v[160:163], v[142:145], v[108:111]
	v_mfma_f32_16x16x32_f16 v[36:39], v[166:169], v[142:145], v[36:39]
	v_mfma_f32_16x16x32_f16 v[104:107], v[192:195], v[142:145], v[104:107]
	v_mfma_f32_16x16x32_f16 v[32:35], v[196:199], v[142:145], v[32:35]
	ds_read_b128 v[142:145], v242 offset:32768
	s_waitcnt lgkmcnt(6)
	v_mfma_f32_16x16x32_f16 v[28:31], v[160:163], v[152:155], v[28:31]
	v_mfma_f32_16x16x32_f16 v[20:23], v[166:169], v[152:155], v[20:23]
	v_mfma_f32_16x16x32_f16 v[24:27], v[192:195], v[152:155], v[24:27]
	v_mfma_f32_16x16x32_f16 v[16:19], v[196:199], v[152:155], v[16:19]
	ds_read_b128 v[152:155], v242 offset:34816
	s_waitcnt lgkmcnt(6)
; __device__ __forceinline__ float siluf_(float x) { return x / (1.0f + __expf(-x)); }
; __device__ __forceinline__ void phase_g4(const Params& p, f16* smem) {
;     ...
; #pragma unroll
;     for (int i = 0; i < 4; ++i) {
;       int m = m0 + wm * 64 + i * 16 + (lane & 15);
; #pragma unroll
;       for (int jj = 0; jj < 2; ++jj) {
;         int u = nt * 64 + wn * 32 + jj * 16 + 4 * (lane >> 4);
;         f16x4 o;
; #pragma unroll
;         for (int r = 0; r < 4; ++r) o[r] = (f16)(siluf_(acc[i][jj][r]) * acc[i][jj + 2][r]);
;         *(f16x4*)(hid + (size_t)m * FF + u) = o;
;       }
	v_mfma_f32_16x16x32_f16 v[12:15], v[160:163], v[156:159], v[12:15]
	v_mfma_f32_16x16x32_f16 v[4:7], v[166:169], v[156:159], v[4:7]
	v_mfma_f32_16x16x32_f16 v[8:11], v[192:195], v[156:159], v[8:11]
	v_mfma_f32_16x16x32_f16 v[0:3], v[196:199], v[156:159], v[0:3]
	ds_read_b128 v[156:159], v242 offset:36864
	ds_read_b128 v[160:163], v242 offset:38912
	s_waitcnt lgkmcnt(3)
	v_mfma_f32_16x16x32_f16 v[124:127], v[244:247], v[142:145], v[124:127]
	v_mfma_f32_16x16x32_f16 v[116:119], v[248:251], v[142:145], v[116:119]
	v_mfma_f32_16x16x32_f16 v[120:123], v[252:255], v[142:145], v[120:123]
	v_mfma_f32_16x16x32_f16 v[112:115], v[128:131], v[142:145], v[112:115]
	s_waitcnt lgkmcnt(2)
	v_mfma_f32_16x16x32_f16 v[108:111], v[244:247], v[152:155], v[108:111]
	v_mfma_f32_16x16x32_f16 v[36:39], v[248:251], v[152:155], v[36:39]
	v_mfma_f32_16x16x32_f16 v[104:107], v[252:255], v[152:155], v[104:107]
	v_mfma_f32_16x16x32_f16 v[32:35], v[128:131], v[152:155], v[32:35]
	s_waitcnt lgkmcnt(1)
	v_mfma_f32_16x16x32_f16 v[28:31], v[244:247], v[156:159], v[28:31]
	v_mfma_f32_16x16x32_f16 v[20:23], v[248:251], v[156:159], v[20:23]
	v_mfma_f32_16x16x32_f16 v[24:27], v[252:255], v[156:159], v[24:27]
	v_mfma_f32_16x16x32_f16 v[16:19], v[128:131], v[156:159], v[16:19]
	s_waitcnt lgkmcnt(0)
	v_mfma_f32_16x16x32_f16 v[12:15], v[244:247], v[160:163], v[12:15]
	v_mfma_f32_16x16x32_f16 v[4:7], v[248:251], v[160:163], v[4:7]
	v_mfma_f32_16x16x32_f16 v[8:11], v[252:255], v[160:163], v[8:11]
	v_mfma_f32_16x16x32_f16 v[0:3], v[128:131], v[160:163], v[0:3]
	s_waitcnt lgkmcnt(0)
	s_setprio 0
	s_waitcnt vmcnt(15)
	v_mul_f32_e32 v41, 0xbfb8aa3b, v124
	s_waitcnt vmcnt(11)
	v_exp_f32_e32 v46, v41
	v_mul_f32_e32 v41, 0xbfb8aa3b, v125
	v_exp_f32_e32 v47, v41
	v_add_u32_e32 v42, s10, v146
	v_lshl_or_b32 v40, s12, 6, v149
	v_mad_i64_i32 v[44:45], s[10:11], v42, s96, v[132:133]
	v_pk_add_f32 v[46:47], v[46:47], 1.0 op_sel_hi:[1,0]
	s_add_i32 s5, s5, s26
	s_movk_i32 s14, 0x2cb0
	s_cmp_eq_u32 s4, 3
	s_cselect_b32 s14, 0x2c00, s14
	s_cmp_lt_i32 s5, s14
	v_rcp_f32_e32 v43, v47
	s_nop 0
	v_mul_f32_e32 v41, v125, v43
	v_mov_b32_e32 v47, v41
	s_nop 0
	v_rcp_f32_e32 v43, v46
	s_nop 0
	v_mul_f32_e32 v41, v124, v43
	v_mov_b32_e32 v46, v41
	v_mul_f32_e32 v41, 0xbfb8aa3b, v126
	v_exp_f32_e32 v48, v41
	v_mul_f32_e32 v41, 0xbfb8aa3b, v127
	v_exp_f32_e32 v49, v41
	v_pk_mul_f32 v[46:47], v[120:121], v[46:47]
	v_pk_add_f32 v[48:49], v[48:49], 1.0 op_sel_hi:[1,0]
	s_nop 0
	v_cvt_pk_f16_f32 v46, v46, v47
	v_rcp_f32_e32 v43, v49
	s_nop 0
	v_mul_f32_e32 v41, v127, v43
	v_mov_b32_e32 v49, v41
	s_nop 0
	v_rcp_f32_e32 v43, v48
	s_nop 0
	v_mul_f32_e32 v41, v126, v43
	v_mov_b32_e32 v48, v41
	v_ashrrev_i32_e32 v41, 31, v40
	v_pk_mul_f32 v[48:49], v[122:123], v[48:49]
	v_lshlrev_b64 v[40:41], 1, v[40:41]
	v_cvt_pk_f16_f32 v47, v48, v49
	v_lshl_add_u64 v[44:45], v[44:45], 0, v[40:41]
	v_mul_f32_e32 v43, 0xbfb8aa3b, v116
	global_store_dwordx2 v[44:45], v[46:47], off
	v_exp_f32_e32 v46, v43
	v_mul_f32_e32 v43, 0xbfb8aa3b, v117
	v_exp_f32_e32 v47, v43
	s_nop 0
	v_pk_add_f32 v[46:47], v[46:47], 1.0 op_sel_hi:[1,0]
	s_nop 0
	s_nop 0
	v_rcp_f32_e32 v48, v47
	s_nop 0
	v_mul_f32_e32 v43, v117, v48
	v_mov_b32_e32 v47, v43
	s_nop 0
	v_rcp_f32_e32 v48, v46
	s_nop 0
	v_mul_f32_e32 v43, v116, v48
	v_mov_b32_e32 v46, v43
	v_mul_f32_e32 v43, 0xbfb8aa3b, v118
	v_exp_f32_e32 v48, v43
	v_mul_f32_e32 v43, 0xbfb8aa3b, v119
	v_exp_f32_e32 v49, v43
	v_pk_mul_f32 v[46:47], v[112:113], v[46:47]
	v_pk_add_f32 v[48:49], v[48:49], 1.0 op_sel_hi:[1,0]
	s_nop 0
	v_cvt_pk_f16_f32 v46, v46, v47
	s_nop 0
	v_rcp_f32_e32 v47, v49
	s_nop 0
	v_mul_f32_e32 v43, v119, v47
	v_mov_b32_e32 v49, v43
	s_nop 0
	v_rcp_f32_e32 v47, v48
	s_nop 0
	v_mul_f32_e32 v43, v118, v47
	v_mov_b32_e32 v48, v43
	v_pk_mul_f32 v[48:49], v[114:115], v[48:49]
	v_or_b32_e32 v43, 16, v42
	v_cvt_pk_f16_f32 v47, v48, v49
	global_store_dwordx2 v[44:45], v[46:47], off offset:32
	v_mad_i64_i32 v[44:45], s[10:11], v43, s96, v[132:133]
	v_mul_f32_e32 v43, 0xbfb8aa3b, v108
	v_exp_f32_e32 v46, v43
	v_mul_f32_e32 v43, 0xbfb8aa3b, v109
	v_exp_f32_e32 v47, v43
	v_lshl_add_u64 v[44:45], v[44:45], 0, v[40:41]
	v_pk_add_f32 v[46:47], v[46:47], 1.0 op_sel_hi:[1,0]
	s_nop 0
	s_nop 0
	v_rcp_f32_e32 v48, v47
	s_nop 0
	v_mul_f32_e32 v43, v109, v48
	v_mov_b32_e32 v47, v43
	s_nop 0
	v_rcp_f32_e32 v48, v46
	s_nop 0
	v_mul_f32_e32 v43, v108, v48
	v_mov_b32_e32 v46, v43
	v_mul_f32_e32 v43, 0xbfb8aa3b, v110
	v_exp_f32_e32 v48, v43
	v_mul_f32_e32 v43, 0xbfb8aa3b, v111
	v_exp_f32_e32 v49, v43
	v_pk_mul_f32 v[46:47], v[104:105], v[46:47]
	v_pk_add_f32 v[48:49], v[48:49], 1.0 op_sel_hi:[1,0]
	s_nop 0
	v_cvt_pk_f16_f32 v46, v46, v47
	s_nop 0
	v_rcp_f32_e32 v47, v49
	s_nop 0
	v_mul_f32_e32 v43, v111, v47
	v_mov_b32_e32 v49, v43
	s_nop 0
	v_rcp_f32_e32 v47, v48
	s_nop 0
	v_mul_f32_e32 v43, v110, v47
	v_mov_b32_e32 v48, v43
	v_pk_mul_f32 v[48:49], v[106:107], v[48:49]
	v_mul_f32_e32 v43, 0xbfb8aa3b, v36
	v_cvt_pk_f16_f32 v47, v48, v49
	global_store_dwordx2 v[44:45], v[46:47], off
	v_exp_f32_e32 v46, v43
; __device__ __forceinline__ float siluf_(float x) { return x / (1.0f + __expf(-x)); }
; __device__ __forceinline__ void phase_g4(const Params& p, f16* smem) {
;     ...
; #pragma unroll
;     for (int i = 0; i < 4; ++i) {
;       int m = m0 + wm * 64 + i * 16 + (lane & 15);
; #pragma unroll
;       for (int jj = 0; jj < 2; ++jj) {
;         int u = nt * 64 + wn * 32 + jj * 16 + 4 * (lane >> 4);
;         f16x4 o;
; #pragma unroll
;         for (int r = 0; r < 4; ++r) o[r] = (f16)(siluf_(acc[i][jj][r]) * acc[i][jj + 2][r]);
;         *(f16x4*)(hid + (size_t)m * FF + u) = o;
;       }
	v_mul_f32_e32 v43, 0xbfb8aa3b, v37
	v_exp_f32_e32 v47, v43
	s_nop 0
	v_pk_add_f32 v[46:47], v[46:47], 1.0 op_sel_hi:[1,0]
	s_nop 0
	s_nop 0
	v_rcp_f32_e32 v48, v47
	s_nop 0
	v_mul_f32_e32 v43, v37, v48
	v_mov_b32_e32 v37, v43
	s_nop 0
	v_rcp_f32_e32 v47, v46
	s_nop 0
	v_mul_f32_e32 v43, v36, v47
	v_mov_b32_e32 v36, v43
	v_pk_mul_f32 v[32:33], v[32:33], v[36:37]
	s_nop 0
	v_cvt_pk_f16_f32 v32, v32, v33
	v_mul_f32_e32 v33, 0xbfb8aa3b, v38
	v_exp_f32_e32 v36, v33
	v_mul_f32_e32 v33, 0xbfb8aa3b, v39
	v_exp_f32_e32 v37, v33
	s_nop 0
	v_pk_add_f32 v[36:37], v[36:37], 1.0 op_sel_hi:[1,0]
	s_nop 0
	s_nop 0
	v_rcp_f32_e32 v43, v37
	s_nop 0
	v_mul_f32_e32 v33, v39, v43
	v_mov_b32_e32 v37, v33
	s_nop 0
	v_rcp_f32_e32 v39, v36
	s_nop 0
	v_mul_f32_e32 v33, v38, v39
	v_mov_b32_e32 v36, v33
	v_pk_mul_f32 v[34:35], v[34:35], v[36:37]
	s_nop 0
	v_cvt_pk_f16_f32 v33, v34, v35
	v_mul_f32_e32 v34, 0xbfb8aa3b, v28
	v_mul_f32_e32 v35, 0xbfb8aa3b, v29
	v_exp_f32_e32 v34, v34
	v_exp_f32_e32 v35, v35
	global_store_dwordx2 v[44:45], v[32:33], off offset:32
	v_or_b32_e32 v32, 32, v42
	v_mad_i64_i32 v[32:33], s[10:11], v32, s96, v[132:133]
	v_pk_add_f32 v[34:35], v[34:35], 1.0 op_sel_hi:[1,0]
	s_nop 0
	s_nop 0
	v_rcp_f32_e32 v37, v35
	s_nop 0
	v_mul_f32_e32 v36, v29, v37
	v_mov_b32_e32 v29, v36
	s_nop 0
	v_rcp_f32_e32 v36, v34
	s_nop 0
	v_mul_f32_e32 v35, v28, v36
	v_mov_b32_e32 v28, v35
	v_pk_mul_f32 v[24:25], v[24:25], v[28:29]
	s_nop 0
	v_cvt_pk_f16_f32 v24, v24, v25
	v_mul_f32_e32 v25, 0xbfb8aa3b, v30
	v_exp_f32_e32 v28, v25
	v_mul_f32_e32 v25, 0xbfb8aa3b, v31
	v_exp_f32_e32 v29, v25
	s_nop 0
	v_pk_add_f32 v[28:29], v[28:29], 1.0 op_sel_hi:[1,0]
	s_nop 0
	s_nop 0
	v_rcp_f32_e32 v34, v29
	s_nop 0
	v_mul_f32_e32 v25, v31, v34
	v_mov_b32_e32 v29, v25
	s_nop 0
	v_rcp_f32_e32 v31, v28
	s_nop 0
	v_mul_f32_e32 v25, v30, v31
	v_mov_b32_e32 v28, v25
	v_pk_mul_f32 v[26:27], v[26:27], v[28:29]
	s_nop 0
	v_cvt_pk_f16_f32 v25, v26, v27
	v_lshl_add_u64 v[26:27], v[32:33], 0, v[40:41]
	global_store_dwordx2 v[26:27], v[24:25], off
	v_mul_f32_e32 v24, 0xbfb8aa3b, v20
	v_mul_f32_e32 v25, 0xbfb8aa3b, v21
	v_exp_f32_e32 v24, v24
	v_exp_f32_e32 v25, v25
	s_nop 0
	v_pk_add_f32 v[24:25], v[24:25], 1.0 op_sel_hi:[1,0]
	s_nop 0
	s_nop 0
	v_rcp_f32_e32 v29, v25
	s_nop 0
	v_mul_f32_e32 v28, v21, v29
	v_mov_b32_e32 v21, v28
	s_nop 0
	v_rcp_f32_e32 v28, v24
	s_nop 0
	v_mul_f32_e32 v25, v20, v28
	v_mov_b32_e32 v20, v25
	v_pk_mul_f32 v[16:17], v[16:17], v[20:21]
	s_nop 0
	v_cvt_pk_f16_f32 v16, v16, v17
	v_mul_f32_e32 v17, 0xbfb8aa3b, v22
	v_exp_f32_e32 v20, v17
	v_mul_f32_e32 v17, 0xbfb8aa3b, v23
	v_exp_f32_e32 v21, v17
	s_nop 0
	v_pk_add_f32 v[20:21], v[20:21], 1.0 op_sel_hi:[1,0]
	s_nop 0
	s_nop 0
	v_rcp_f32_e32 v24, v21
	s_nop 0
	v_mul_f32_e32 v17, v23, v24
	v_mov_b32_e32 v21, v17
	s_nop 0
	v_rcp_f32_e32 v23, v20
	s_nop 0
	v_mul_f32_e32 v17, v22, v23
	v_mov_b32_e32 v20, v17
	v_pk_mul_f32 v[18:19], v[18:19], v[20:21]
	s_nop 0
	v_cvt_pk_f16_f32 v17, v18, v19
	v_mul_f32_e32 v18, 0xbfb8aa3b, v12
	v_mul_f32_e32 v19, 0xbfb8aa3b, v13
	v_exp_f32_e32 v18, v18
	v_exp_f32_e32 v19, v19
	global_store_dwordx2 v[26:27], v[16:17], off offset:32
	v_or_b32_e32 v16, 48, v42
	v_mad_i64_i32 v[16:17], s[10:11], v16, s96, v[132:133]
	v_pk_add_f32 v[18:19], v[18:19], 1.0 op_sel_hi:[1,0]
	s_nop 0
	s_nop 0
	v_rcp_f32_e32 v21, v19
	s_nop 0
	v_mul_f32_e32 v20, v13, v21
	v_mov_b32_e32 v13, v20
	s_nop 0
	v_rcp_f32_e32 v20, v18
	s_nop 0
	v_mul_f32_e32 v19, v12, v20
	v_mov_b32_e32 v12, v19
	v_pk_mul_f32 v[8:9], v[8:9], v[12:13]
	s_nop 0
	v_cvt_pk_f16_f32 v8, v8, v9
	v_mul_f32_e32 v9, 0xbfb8aa3b, v14
	v_exp_f32_e32 v12, v9
	v_mul_f32_e32 v9, 0xbfb8aa3b, v15
	v_exp_f32_e32 v13, v9
	s_nop 0
	v_pk_add_f32 v[12:13], v[12:13], 1.0 op_sel_hi:[1,0]
	s_nop 0
	s_nop 0
	v_rcp_f32_e32 v18, v13
	s_nop 0
	v_mul_f32_e32 v9, v15, v18
	v_mov_b32_e32 v13, v9
	s_nop 0
	v_rcp_f32_e32 v15, v12
	s_nop 0
	v_mul_f32_e32 v9, v14, v15
	v_mov_b32_e32 v12, v9
	v_pk_mul_f32 v[10:11], v[10:11], v[12:13]
	s_nop 0
	v_cvt_pk_f16_f32 v9, v10, v11
	v_lshl_add_u64 v[10:11], v[16:17], 0, v[40:41]
	global_store_dwordx2 v[10:11], v[8:9], off
	v_mul_f32_e32 v8, 0xbfb8aa3b, v4
	v_mul_f32_e32 v9, 0xbfb8aa3b, v5
	v_exp_f32_e32 v8, v8
	v_exp_f32_e32 v9, v9
	s_nop 0
	v_pk_add_f32 v[8:9], v[8:9], 1.0 op_sel_hi:[1,0]
	s_nop 0
	s_nop 0
	v_rcp_f32_e32 v13, v9
	s_nop 0
	v_mul_f32_e32 v12, v5, v13
	v_mov_b32_e32 v5, v12
	s_nop 0
	v_rcp_f32_e32 v12, v8
	s_nop 0
	v_mul_f32_e32 v9, v4, v12
	v_mov_b32_e32 v4, v9
	v_pk_mul_f32 v[0:1], v[0:1], v[4:5]
	s_nop 0
	v_cvt_pk_f16_f32 v0, v0, v1
	v_mul_f32_e32 v1, 0xbfb8aa3b, v6
	v_exp_f32_e32 v4, v1
	v_mul_f32_e32 v1, 0xbfb8aa3b, v7
	v_exp_f32_e32 v5, v1
	s_nop 0
	v_pk_add_f32 v[4:5], v[4:5], 1.0 op_sel_hi:[1,0]
	s_nop 0
	s_nop 0
	v_rcp_f32_e32 v8, v5
	s_nop 0
	v_mul_f32_e32 v1, v7, v8
	v_mov_b32_e32 v5, v1
	s_nop 0
	v_rcp_f32_e32 v7, v4
	s_nop 0
	v_mul_f32_e32 v1, v6, v7
	v_mov_b32_e32 v4, v1
	v_pk_mul_f32 v[2:3], v[2:3], v[4:5]
	s_nop 0
	v_cvt_pk_f16_f32 v1, v2, v3
	global_store_dwordx2 v[10:11], v[0:1], off offset:32
	s_cbranch_scc1 .LBB0_1397

; template <int NJ>
; __device__ __forceinline__ void gemm_tile(const f16* __restrict__ A, int lda, const f16* __restrict__ Bt, int ldb,
;                                           int K, f32x4 (&acc)[4][NJ], f16* sA, f16* sB, const int tid) {
;     ...
;   G_LOAD(ra0, rb0, 0)
;   if (K > 64) G_LOAD(ra1, rb1, 64)
;   __syncthreads();
;   G_STORE(ra0, rb0, 0)
;   if (K > 128) G_LOAD(ra0, rb0, 128)
;   __syncthreads();
; template <int NJ>
; __device__ __forceinline__ void gres_tile(const Params& p, const f16* A, int lda, const f16* W, int K, const float* mod,
;                                           bool first_in, f16* sA, f16* sB, int m0, int n0) {
;   const int lane = TIDX(p) & 63, wave = TIDX(p) >> 6, wm = wave >> 1, wn = wave & 1;
;   f32x4 acc[4][NJ];
;   zero_acc<NJ>(acc);
;   gemm_tile<NJ>(A + (size_t)m0 * lda, lda, W + (size_t)n0 * K, K, K, acc, sA, sB, TIDX(p));
.Lxm_g5:
	s_ashr_i32 s6, s10, 31
	s_lshr_b32 s6, s6, 29
	s_add_i32 s7, s10, s6
	s_lshl_b32 s6, s7, 4
	s_and_b32 s6, s6, 0xffffff80
	v_mad_i64_i32 v[146:147], s[12:13], s6, v191, v[142:143]
	v_add_co_u32_e32 v2, vcc, 0x2c000, v146
	s_and_b32 s7, s7, -8
	s_nop 0
	v_addc_co_u32_e32 v3, vcc, 0, v147, vcc
	s_sub_i32 s7, s10, s7
	v_add_co_u32_e32 v4, vcc, s97, v146
	s_mul_i32 s10, s7, 0x58000
	s_nop 0
	v_addc_co_u32_e32 v5, vcc, 0, v147, vcc
	s_ashr_i32 s11, s10, 31
	v_add_co_u32_e32 v6, vcc, 0x84000, v146
	v_lshl_add_u64 v[148:149], s[10:11], 1, v[144:145]
	s_nop 0
	v_addc_co_u32_e32 v7, vcc, 0, v147, vcc
	v_add_co_u32_e32 v8, vcc, s81, v148
	global_load_dwordx4 v[82:85], v[146:147], off
	s_nop 0
	v_addc_co_u32_e32 v9, vcc, 0, v149, vcc
	v_add_co_u32_e32 v10, vcc, s97, v148
	global_load_dwordx4 v[86:89], v[2:3], off
	s_nop 0
	v_addc_co_u32_e32 v11, vcc, 0, v149, vcc
	v_add_co_u32_e32 v12, vcc, s27, v148
	global_load_dwordx4 v[90:93], v[4:5], off
	s_nop 0
	v_addc_co_u32_e32 v13, vcc, 0, v149, vcc
	global_load_dwordx4 v[94:97], v[6:7], off
	global_load_dwordx4 v[98:101], v[148:149], off
	global_load_dwordx4 v[102:105], v[8:9], off
	global_load_dwordx4 v[106:109], v[10:11], off
	global_load_dwordx4 v[110:113], v[12:13], off
	global_load_dwordx4 v[18:21], v[146:147], off offset:128
	global_load_dwordx4 v[26:29], v[2:3], off offset:128
	global_load_dwordx4 v[22:25], v[148:149], off offset:128
	global_load_dwordx4 v[30:33], v[4:5], off offset:128
	global_load_dwordx4 v[34:37], v[6:7], off offset:128
	global_load_dwordx4 v[38:41], v[8:9], off offset:128
	global_load_dwordx4 v[46:49], v[10:11], off offset:128
	global_load_dwordx4 v[50:53], v[12:13], off offset:128
	s_barrier
	global_load_dwordx4 v[58:61], v[2:3], off offset:256
	global_load_dwordx4 v[62:65], v[4:5], off offset:256
	global_load_dwordx4 v[42:45], v[146:147], off offset:256
	global_load_dwordx4 v[54:57], v[148:149], off offset:256
	global_load_dwordx4 v[66:69], v[6:7], off offset:256
	global_load_dwordx4 v[70:73], v[8:9], off offset:256
	global_load_dwordx4 v[74:77], v[10:11], off offset:256
	global_load_dwordx4 v[78:81], v[12:13], off offset:256
	v_mov_b32_e32 v2, 0
	s_mov_b32 s10, 0
	v_mov_b32_e32 v3, v2
	v_mov_b32_e32 v4, v2
	v_mov_b32_e32 v5, v2
	v_mov_b32_e32 v6, v2
	v_mov_b32_e32 v7, v2
	v_mov_b32_e32 v8, v2
	v_mov_b32_e32 v9, v2
	v_mov_b32_e32 v10, v2
	v_mov_b32_e32 v11, v2
	v_mov_b32_e32 v12, v2
	v_mov_b32_e32 v13, v2
	v_mov_b32_e32 v14, v2
	v_mov_b32_e32 v15, v2
	v_mov_b32_e32 v16, v2
	v_mov_b32_e32 v17, v2
	v_mov_b32_e32 v114, v2
	v_mov_b32_e32 v115, v2
	v_mov_b32_e32 v116, v2
	v_mov_b32_e32 v117, v2
	v_mov_b32_e32 v118, v2
	v_mov_b32_e32 v119, v2
	v_mov_b32_e32 v120, v2
	v_mov_b32_e32 v121, v2
	v_mov_b32_e32 v122, v2
	v_mov_b32_e32 v123, v2
	v_mov_b32_e32 v124, v2
	v_mov_b32_e32 v125, v2
	v_mov_b32_e32 v126, v2
	v_mov_b32_e32 v127, v2
	v_mov_b32_e32 v128, v2
	v_mov_b32_e32 v129, v2
	s_waitcnt vmcnt(23)
	ds_write_b128 v161, v[82:85]
	s_waitcnt vmcnt(22)
	ds_write_b128 v161, v[86:89] offset:4096
	s_waitcnt vmcnt(19)
	ds_write_b128 v161, v[98:101] offset:16384
	ds_write_b128 v161, v[90:93] offset:8192
	ds_write_b128 v161, v[94:97] offset:12288
	s_waitcnt vmcnt(18)
	ds_write_b128 v161, v[102:105] offset:20480
	s_waitcnt vmcnt(17)
	ds_write_b128 v161, v[106:109] offset:24576
	s_waitcnt vmcnt(16)
	ds_write_b128 v161, v[110:113] offset:28672
	s_waitcnt lgkmcnt(0)
	s_barrier
	v_mov_b32_e32 v82, v2
	v_mov_b32_e32 v83, v2
	v_mov_b32_e32 v84, v2
	v_mov_b32_e32 v85, v2
	v_mov_b32_e32 v86, v2
	v_mov_b32_e32 v87, v2
	v_mov_b32_e32 v88, v2
	v_mov_b32_e32 v89, v2
	v_mov_b32_e32 v90, v2
	v_mov_b32_e32 v91, v2
	v_mov_b32_e32 v92, v2
	v_mov_b32_e32 v93, v2
	v_mov_b32_e32 v94, v2
	v_mov_b32_e32 v95, v2
	v_mov_b32_e32 v96, v2
	v_mov_b32_e32 v97, v2
	v_mov_b32_e32 v98, v2
	v_mov_b32_e32 v99, v2
	v_mov_b32_e32 v100, v2
	v_mov_b32_e32 v101, v2
	v_mov_b32_e32 v102, v2
	v_mov_b32_e32 v103, v2
	v_mov_b32_e32 v104, v2
	v_mov_b32_e32 v105, v2
	v_mov_b32_e32 v106, v2
	v_mov_b32_e32 v107, v2
	v_mov_b32_e32 v108, v2
	v_mov_b32_e32 v109, v2
	v_mov_b32_e32 v110, v2
	v_mov_b32_e32 v111, v2
	v_mov_b32_e32 v112, v2
	v_mov_b32_e32 v113, v2
	s_bitcmp1_b32 s95, 8
	s_cbranch_scc0 .Lprio_1457
	s_setprio 1
.Lprio_1457:
.LBB0_1457:
	ds_read_b128 v[204:207], v163 offset:16384
	ds_read_b128 v[208:211], v163 offset:18432
	ds_read_b128 v[212:215], v163 offset:20480
	ds_read_b128 v[216:219], v163 offset:22528
	s_add_i32 s11, s10, 0xc0
	ds_read_b128 v[192:195], v162
	ds_read_b128 v[196:199], v162 offset:2048
	s_cmpk_lt_u32 s10, 0xa40
	s_cselect_b32 s42, s11, 0xac0
	ds_read_b128 v[200:203], v162 offset:4096
	s_lshl_b64 s[12:13], s[42:43], 1
	v_lshl_add_u64 v[152:153], v[146:147], 0, s[12:13]
	ds_read_b128 v[130:133], v162 offset:6144
	ds_read_b128 v[244:247], v243 offset:16384
	ds_read_b128 v[248:251], v243 offset:18432
	ds_read_b128 v[252:255], v243 offset:20480
	s_waitcnt lgkmcnt(6)
	v_mfma_f32_16x16x32_f16 v[126:129], v[204:207], v[192:195], v[126:129]
	v_lshl_add_u64 v[150:151], v[148:149], 0, s[12:13]
	s_add_i32 s11, s10, 0x100
	s_cmpk_lt_u32 s10, 0xa00
	v_mfma_f32_16x16x32_f16 v[122:125], v[208:211], v[192:195], v[122:125]
	s_cselect_b32 s42, s11, 0xac0
	s_lshl_b64 s[12:13], s[42:43], 1
	v_lshl_add_u64 v[168:169], v[148:149], 0, s[12:13]
	v_mfma_f32_16x16x32_f16 v[118:121], v[212:215], v[192:195], v[118:121]
	s_add_i32 s11, s10, 0x80
	s_cmpk_lt_u32 s10, 0x980
	s_mov_b32 s10, s11
	v_mfma_f32_16x16x32_f16 v[114:117], v[216:219], v[192:195], v[114:117]
	ds_read_b128 v[192:195], v243 offset:22528
	s_waitcnt vmcnt(15)
	ds_write_b128 v161, v[18:21] offset:32768
	global_load_dwordx4 v[18:21], v[152:153], off
	s_waitcnt lgkmcnt(7)
	v_mfma_f32_16x16x32_f16 v[110:113], v[204:207], v[196:199], v[110:113]
	v_mfma_f32_16x16x32_f16 v[106:109], v[208:211], v[196:199], v[106:109]
	v_mfma_f32_16x16x32_f16 v[102:105], v[212:215], v[196:199], v[102:105]
	v_mfma_f32_16x16x32_f16 v[98:101], v[216:219], v[196:199], v[98:101]
	ds_read_b128 v[196:199], v242
	s_waitcnt vmcnt(15)
	ds_write_b128 v161, v[26:29] offset:36864
	v_add_co_u32_e32 v26, vcc, s81, v152
	s_nop 1
	v_addc_co_u32_e32 v27, vcc, 0, v153, vcc
	global_load_dwordx4 v[26:29], v[26:27], off
	s_waitcnt lgkmcnt(8)
	v_mfma_f32_16x16x32_f16 v[94:97], v[204:207], v[200:203], v[94:97]
	v_mfma_f32_16x16x32_f16 v[90:93], v[208:211], v[200:203], v[90:93]
	v_mfma_f32_16x16x32_f16 v[86:89], v[212:215], v[200:203], v[86:89]
	v_mfma_f32_16x16x32_f16 v[82:85], v[216:219], v[200:203], v[82:85]
	ds_read_b128 v[200:203], v242 offset:2048
	s_waitcnt vmcnt(14)
	ds_write_b128 v161, v[30:33] offset:40960
	v_add_co_u32_e32 v30, vcc, s97, v152
	s_nop 1
	v_addc_co_u32_e32 v31, vcc, 0, v153, vcc
	global_load_dwordx4 v[30:33], v[30:31], off
	s_waitcnt lgkmcnt(9)
	v_mfma_f32_16x16x32_f16 v[14:17], v[204:207], v[130:133], v[14:17]
	v_mfma_f32_16x16x32_f16 v[10:13], v[208:211], v[130:133], v[10:13]
	v_mfma_f32_16x16x32_f16 v[6:9], v[212:215], v[130:133], v[6:9]
	v_mfma_f32_16x16x32_f16 v[2:5], v[216:219], v[130:133], v[2:5]
	ds_read_b128 v[130:133], v242 offset:4096
	ds_read_b128 v[204:207], v242 offset:6144
	s_waitcnt vmcnt(14)
	ds_write_b128 v161, v[34:37] offset:45056
	v_add_co_u32_e32 v34, vcc, s27, v152
	s_nop 1
	v_addc_co_u32_e32 v35, vcc, 0, v153, vcc
	global_load_dwordx4 v[34:37], v[34:35], off
	s_waitcnt lgkmcnt(6)
	v_mfma_f32_16x16x32_f16 v[126:129], v[244:247], v[196:199], v[126:129]
	v_mfma_f32_16x16x32_f16 v[122:125], v[248:251], v[196:199], v[122:125]
	v_mfma_f32_16x16x32_f16 v[118:121], v[252:255], v[196:199], v[118:121]
	v_mfma_f32_16x16x32_f16 v[114:117], v[192:195], v[196:199], v[114:117]
	ds_write_b128 v161, v[22:25] offset:49152
	global_load_dwordx4 v[22:25], v[150:151], off
	v_lshl_add_u64 v[216:217], v[146:147], 0, s[12:13]
	s_waitcnt lgkmcnt(5)
	v_mfma_f32_16x16x32_f16 v[110:113], v[244:247], v[200:203], v[110:113]
	v_mfma_f32_16x16x32_f16 v[106:109], v[248:251], v[200:203], v[106:109]
	v_mfma_f32_16x16x32_f16 v[102:105], v[252:255], v[200:203], v[102:105]
	v_mfma_f32_16x16x32_f16 v[98:101], v[192:195], v[200:203], v[98:101]
	s_waitcnt vmcnt(15)
	ds_write_b128 v161, v[38:41] offset:53248
	v_add_co_u32_e32 v38, vcc, s81, v150
	s_nop 1
	v_addc_co_u32_e32 v39, vcc, 0, v151, vcc
	global_load_dwordx4 v[38:41], v[38:39], off
	s_waitcnt lgkmcnt(4)
	v_mfma_f32_16x16x32_f16 v[94:97], v[244:247], v[130:133], v[94:97]
	v_mfma_f32_16x16x32_f16 v[90:93], v[248:251], v[130:133], v[90:93]
	v_mfma_f32_16x16x32_f16 v[86:89], v[252:255], v[130:133], v[86:89]
	v_mfma_f32_16x16x32_f16 v[82:85], v[192:195], v[130:133], v[82:85]
	s_waitcnt vmcnt(15)
	ds_write_b128 v161, v[46:49] offset:57344
	v_add_co_u32_e32 v46, vcc, s97, v150
	s_nop 1
	v_addc_co_u32_e32 v47, vcc, 0, v151, vcc
	global_load_dwordx4 v[46:49], v[46:47], off
	s_waitcnt lgkmcnt(4)
	v_mfma_f32_16x16x32_f16 v[14:17], v[244:247], v[204:207], v[14:17]
	v_mfma_f32_16x16x32_f16 v[10:13], v[248:251], v[204:207], v[10:13]
	v_mfma_f32_16x16x32_f16 v[6:9], v[252:255], v[204:207], v[6:9]
	v_mfma_f32_16x16x32_f16 v[2:5], v[192:195], v[204:207], v[2:5]
	s_waitcnt vmcnt(15)
	ds_write_b128 v161, v[50:53] offset:61440
	v_add_co_u32_e32 v50, vcc, s27, v150
	s_nop 1
	v_addc_co_u32_e32 v51, vcc, 0, v151, vcc
	global_load_dwordx4 v[50:53], v[50:51], off
	s_waitcnt lgkmcnt(0)
	s_barrier
	ds_read_b128 v[200:203], v163 offset:49152
	ds_read_b128 v[204:207], v163 offset:51200
	ds_read_b128 v[208:211], v163 offset:53248
	ds_read_b128 v[212:215], v163 offset:55296
	ds_read_b128 v[130:133], v162 offset:32768
	ds_read_b128 v[150:153], v162 offset:34816
	ds_read_b128 v[192:195], v162 offset:36864
	ds_read_b128 v[196:199], v162 offset:38912
	ds_read_b128 v[244:247], v243 offset:49152
	ds_read_b128 v[248:251], v243 offset:51200
	ds_read_b128 v[252:255], v243 offset:53248
	s_waitcnt lgkmcnt(6)
	v_mfma_f32_16x16x32_f16 v[126:129], v[200:203], v[130:133], v[126:129]
	v_mfma_f32_16x16x32_f16 v[122:125], v[204:207], v[130:133], v[122:125]
	v_mfma_f32_16x16x32_f16 v[118:121], v[208:211], v[130:133], v[118:121]
	v_mfma_f32_16x16x32_f16 v[114:117], v[212:215], v[130:133], v[114:117]
	ds_read_b128 v[130:133], v243 offset:55296
	s_waitcnt vmcnt(13)
	ds_write_b128 v161, v[42:45]
	global_load_dwordx4 v[42:45], v[216:217], off
	s_waitcnt lgkmcnt(7)
	v_mfma_f32_16x16x32_f16 v[110:113], v[200:203], v[150:153], v[110:113]
	v_mfma_f32_16x16x32_f16 v[106:109], v[204:207], v[150:153], v[106:109]
	v_mfma_f32_16x16x32_f16 v[102:105], v[208:211], v[150:153], v[102:105]
	v_mfma_f32_16x16x32_f16 v[98:101], v[212:215], v[150:153], v[98:101]
	ds_read_b128 v[150:153], v242 offset:32768
	ds_write_b128 v161, v[58:61] offset:4096
	v_add_co_u32_e32 v58, vcc, s81, v216
	s_nop 1
	v_addc_co_u32_e32 v59, vcc, 0, v217, vcc
	global_load_dwordx4 v[58:61], v[58:59], off
	s_waitcnt lgkmcnt(8)
	v_mfma_f32_16x16x32_f16 v[94:97], v[200:203], v[192:195], v[94:97]
	v_mfma_f32_16x16x32_f16 v[90:93], v[204:207], v[192:195], v[90:93]
	v_mfma_f32_16x16x32_f16 v[86:89], v[208:211], v[192:195], v[86:89]
	v_mfma_f32_16x16x32_f16 v[82:85], v[212:215], v[192:195], v[82:85]
	ds_read_b128 v[192:195], v242 offset:34816
	ds_write_b128 v161, v[62:65] offset:8192
	v_add_co_u32_e32 v62, vcc, s97, v216
	s_nop 1
	v_addc_co_u32_e32 v63, vcc, 0, v217, vcc
	global_load_dwordx4 v[62:65], v[62:63], off
	s_waitcnt lgkmcnt(9)
; template <int NJ>
; __device__ __forceinline__ void gemm_tile(const f16* __restrict__ A, int lda, const f16* __restrict__ Bt, int ldb,
;                                           int K, f32x4 (&acc)[4][NJ], f16* sA, f16* sB, const int tid) {
;     ...
;     {
;       const int kof = (k0 + 192 < K) ? k0 + 192 : K - 64;
;       G_STEP(0, ra1, rb1, true, true, kof)
;     }
;     __syncthreads();
;     if (k0 + 64 >= K) break;
;     {
;       const int kof = (k0 + 256 < K) ? k0 + 256 : K - 64;
;       G_STEP(1, ra0, rb0, true, true, kof)
;     }
;     __syncthreads();
	v_mfma_f32_16x16x32_f16 v[14:17], v[200:203], v[196:199], v[14:17]
	v_mfma_f32_16x16x32_f16 v[10:13], v[204:207], v[196:199], v[10:13]
	v_mfma_f32_16x16x32_f16 v[6:9], v[208:211], v[196:199], v[6:9]
	v_mfma_f32_16x16x32_f16 v[2:5], v[212:215], v[196:199], v[2:5]
	ds_read_b128 v[196:199], v242 offset:36864
	ds_read_b128 v[200:203], v242 offset:38912
	s_waitcnt vmcnt(14)
	ds_write_b128 v161, v[66:69] offset:12288
	v_add_co_u32_e32 v66, vcc, s27, v216
	s_nop 1
	v_addc_co_u32_e32 v67, vcc, 0, v217, vcc
	global_load_dwordx4 v[66:69], v[66:67], off
	s_waitcnt lgkmcnt(6)
	v_mfma_f32_16x16x32_f16 v[126:129], v[244:247], v[150:153], v[126:129]
	v_mfma_f32_16x16x32_f16 v[122:125], v[248:251], v[150:153], v[122:125]
	v_mfma_f32_16x16x32_f16 v[118:121], v[252:255], v[150:153], v[118:121]
	v_mfma_f32_16x16x32_f16 v[114:117], v[130:133], v[150:153], v[114:117]
	ds_write_b128 v161, v[54:57] offset:16384
	global_load_dwordx4 v[54:57], v[168:169], off
	s_waitcnt lgkmcnt(5)
	v_mfma_f32_16x16x32_f16 v[110:113], v[244:247], v[192:195], v[110:113]
	v_mfma_f32_16x16x32_f16 v[106:109], v[248:251], v[192:195], v[106:109]
	v_mfma_f32_16x16x32_f16 v[102:105], v[252:255], v[192:195], v[102:105]
	v_mfma_f32_16x16x32_f16 v[98:101], v[130:133], v[192:195], v[98:101]
	s_waitcnt vmcnt(15)
	ds_write_b128 v161, v[70:73] offset:20480
	v_add_co_u32_e32 v70, vcc, s81, v168
	s_nop 1
	v_addc_co_u32_e32 v71, vcc, 0, v169, vcc
	global_load_dwordx4 v[70:73], v[70:71], off
	s_waitcnt lgkmcnt(4)
	v_mfma_f32_16x16x32_f16 v[94:97], v[244:247], v[196:199], v[94:97]
	v_mfma_f32_16x16x32_f16 v[90:93], v[248:251], v[196:199], v[90:93]
	v_mfma_f32_16x16x32_f16 v[86:89], v[252:255], v[196:199], v[86:89]
	v_mfma_f32_16x16x32_f16 v[82:85], v[130:133], v[196:199], v[82:85]
	s_waitcnt vmcnt(15)
	ds_write_b128 v161, v[74:77] offset:24576
	v_add_co_u32_e32 v74, vcc, s97, v168
	s_nop 1
	v_addc_co_u32_e32 v75, vcc, 0, v169, vcc
	global_load_dwordx4 v[74:77], v[74:75], off
	s_waitcnt lgkmcnt(4)
	v_mfma_f32_16x16x32_f16 v[14:17], v[244:247], v[200:203], v[14:17]
	v_mfma_f32_16x16x32_f16 v[10:13], v[248:251], v[200:203], v[10:13]
	v_mfma_f32_16x16x32_f16 v[6:9], v[252:255], v[200:203], v[6:9]
	v_mfma_f32_16x16x32_f16 v[2:5], v[130:133], v[200:203], v[2:5]
	s_waitcnt vmcnt(15)
	ds_write_b128 v161, v[78:81] offset:28672
	v_add_co_u32_e32 v78, vcc, s27, v168
	s_nop 1
	v_addc_co_u32_e32 v79, vcc, 0, v169, vcc
	global_load_dwordx4 v[78:81], v[78:79], off
	s_waitcnt lgkmcnt(0)
	s_barrier
	s_cbranch_scc1 .LBB0_1457
	ds_read_b128 v[204:207], v163 offset:16384
	ds_read_b128 v[208:211], v163 offset:18432
	ds_read_b128 v[212:215], v163 offset:20480
	ds_read_b128 v[216:219], v163 offset:22528
	s_add_i32 s11, s10, 0xc0
	ds_read_b128 v[192:195], v162
	ds_read_b128 v[196:199], v162 offset:2048
	s_cmpk_lt_u32 s10, 0xa40
	s_cselect_b32 s42, s11, 0xac0
	ds_read_b128 v[200:203], v162 offset:4096
	s_lshl_b64 s[12:13], s[42:43], 1
	v_lshl_add_u64 v[152:153], v[146:147], 0, s[12:13]
	ds_read_b128 v[130:133], v162 offset:6144
	ds_read_b128 v[244:247], v243 offset:16384
	ds_read_b128 v[248:251], v243 offset:18432
	ds_read_b128 v[252:255], v243 offset:20480
	s_waitcnt lgkmcnt(6)
	v_mfma_f32_16x16x32_f16 v[126:129], v[204:207], v[192:195], v[126:129]
	v_lshl_add_u64 v[150:151], v[148:149], 0, s[12:13]
	s_add_i32 s11, s10, 0x100
	s_cmpk_lt_u32 s10, 0xa00
	v_mfma_f32_16x16x32_f16 v[122:125], v[208:211], v[192:195], v[122:125]
	s_cselect_b32 s42, s11, 0xac0
	s_lshl_b64 s[12:13], s[42:43], 1
	v_lshl_add_u64 v[168:169], v[148:149], 0, s[12:13]
	v_mfma_f32_16x16x32_f16 v[118:121], v[212:215], v[192:195], v[118:121]
	s_add_i32 s11, s10, 0x80
	s_cmpk_lt_u32 s10, 0xa80
	s_mov_b32 s10, s11
	v_mfma_f32_16x16x32_f16 v[114:117], v[216:219], v[192:195], v[114:117]
	ds_read_b128 v[192:195], v243 offset:22528
	s_waitcnt vmcnt(15)
	ds_write_b128 v161, v[18:21] offset:32768
	global_load_dwordx4 v[18:21], v[152:153], off
	s_waitcnt lgkmcnt(7)
	v_mfma_f32_16x16x32_f16 v[110:113], v[204:207], v[196:199], v[110:113]
	v_mfma_f32_16x16x32_f16 v[106:109], v[208:211], v[196:199], v[106:109]
	v_mfma_f32_16x16x32_f16 v[102:105], v[212:215], v[196:199], v[102:105]
	v_mfma_f32_16x16x32_f16 v[98:101], v[216:219], v[196:199], v[98:101]
	ds_read_b128 v[196:199], v242
	s_waitcnt vmcnt(15)
	ds_write_b128 v161, v[26:29] offset:36864
	v_add_co_u32_e32 v26, vcc, s81, v152
	s_nop 1
	v_addc_co_u32_e32 v27, vcc, 0, v153, vcc
	global_load_dwordx4 v[26:29], v[26:27], off
	s_waitcnt lgkmcnt(8)
	v_mfma_f32_16x16x32_f16 v[94:97], v[204:207], v[200:203], v[94:97]
	v_mfma_f32_16x16x32_f16 v[90:93], v[208:211], v[200:203], v[90:93]
	v_mfma_f32_16x16x32_f16 v[86:89], v[212:215], v[200:203], v[86:89]
	v_mfma_f32_16x16x32_f16 v[82:85], v[216:219], v[200:203], v[82:85]
	ds_read_b128 v[200:203], v242 offset:2048
	s_waitcnt vmcnt(15)
	ds_write_b128 v161, v[30:33] offset:40960
	v_add_co_u32_e32 v30, vcc, s97, v152
	s_nop 1
	v_addc_co_u32_e32 v31, vcc, 0, v153, vcc
	global_load_dwordx4 v[30:33], v[30:31], off
	s_waitcnt lgkmcnt(9)
	v_mfma_f32_16x16x32_f16 v[14:17], v[204:207], v[130:133], v[14:17]
	v_mfma_f32_16x16x32_f16 v[10:13], v[208:211], v[130:133], v[10:13]
	v_mfma_f32_16x16x32_f16 v[6:9], v[212:215], v[130:133], v[6:9]
	v_mfma_f32_16x16x32_f16 v[2:5], v[216:219], v[130:133], v[2:5]
	ds_read_b128 v[130:133], v242 offset:4096
	ds_read_b128 v[204:207], v242 offset:6144
	s_waitcnt vmcnt(15)
	ds_write_b128 v161, v[34:37] offset:45056
	v_add_co_u32_e32 v34, vcc, s27, v152
	s_nop 1
	v_addc_co_u32_e32 v35, vcc, 0, v153, vcc
	global_load_dwordx4 v[34:37], v[34:35], off
	s_waitcnt lgkmcnt(6)
	v_mfma_f32_16x16x32_f16 v[126:129], v[244:247], v[196:199], v[126:129]
	v_mfma_f32_16x16x32_f16 v[122:125], v[248:251], v[196:199], v[122:125]
	v_mfma_f32_16x16x32_f16 v[118:121], v[252:255], v[196:199], v[118:121]
	v_mfma_f32_16x16x32_f16 v[114:117], v[192:195], v[196:199], v[114:117]
	s_waitcnt vmcnt(15)
	ds_write_b128 v161, v[22:25] offset:49152
	global_load_dwordx4 v[22:25], v[150:151], off
	v_lshl_add_u64 v[216:217], v[146:147], 0, s[12:13]
	s_waitcnt lgkmcnt(5)
	v_mfma_f32_16x16x32_f16 v[110:113], v[244:247], v[200:203], v[110:113]
	v_mfma_f32_16x16x32_f16 v[106:109], v[248:251], v[200:203], v[106:109]
	v_mfma_f32_16x16x32_f16 v[102:105], v[252:255], v[200:203], v[102:105]
	v_mfma_f32_16x16x32_f16 v[98:101], v[192:195], v[200:203], v[98:101]
	s_waitcnt vmcnt(15)
	ds_write_b128 v161, v[38:41] offset:53248
	v_add_co_u32_e32 v38, vcc, s81, v150
	s_nop 1
	v_addc_co_u32_e32 v39, vcc, 0, v151, vcc
	global_load_dwordx4 v[38:41], v[38:39], off
	s_waitcnt lgkmcnt(4)
	v_mfma_f32_16x16x32_f16 v[94:97], v[244:247], v[130:133], v[94:97]
	v_mfma_f32_16x16x32_f16 v[90:93], v[248:251], v[130:133], v[90:93]
	v_mfma_f32_16x16x32_f16 v[86:89], v[252:255], v[130:133], v[86:89]
	v_mfma_f32_16x16x32_f16 v[82:85], v[192:195], v[130:133], v[82:85]
	s_waitcnt vmcnt(15)
	ds_write_b128 v161, v[46:49] offset:57344
	v_add_co_u32_e32 v46, vcc, s97, v150
	s_nop 1
	v_addc_co_u32_e32 v47, vcc, 0, v151, vcc
	global_load_dwordx4 v[46:49], v[46:47], off
	s_waitcnt lgkmcnt(4)
	v_mfma_f32_16x16x32_f16 v[14:17], v[244:247], v[204:207], v[14:17]
	v_mfma_f32_16x16x32_f16 v[10:13], v[248:251], v[204:207], v[10:13]
	v_mfma_f32_16x16x32_f16 v[6:9], v[252:255], v[204:207], v[6:9]
	v_mfma_f32_16x16x32_f16 v[2:5], v[192:195], v[204:207], v[2:5]
	s_waitcnt vmcnt(15)
	ds_write_b128 v161, v[50:53] offset:61440
	v_add_co_u32_e32 v50, vcc, s27, v150
	s_nop 1
	v_addc_co_u32_e32 v51, vcc, 0, v151, vcc
	global_load_dwordx4 v[50:53], v[50:51], off
	s_waitcnt lgkmcnt(0)
	s_barrier
	ds_read_b128 v[200:203], v163 offset:49152
	ds_read_b128 v[204:207], v163 offset:51200
	ds_read_b128 v[208:211], v163 offset:53248
	ds_read_b128 v[212:215], v163 offset:55296
	ds_read_b128 v[130:133], v162 offset:32768
	ds_read_b128 v[150:153], v162 offset:34816
	ds_read_b128 v[192:195], v162 offset:36864
	ds_read_b128 v[196:199], v162 offset:38912
	ds_read_b128 v[244:247], v243 offset:49152
	ds_read_b128 v[248:251], v243 offset:51200
	ds_read_b128 v[252:255], v243 offset:53248
	s_waitcnt lgkmcnt(6)
	v_mfma_f32_16x16x32_f16 v[126:129], v[200:203], v[130:133], v[126:129]
	v_mfma_f32_16x16x32_f16 v[122:125], v[204:207], v[130:133], v[122:125]
	v_mfma_f32_16x16x32_f16 v[118:121], v[208:211], v[130:133], v[118:121]
	v_mfma_f32_16x16x32_f16 v[114:117], v[212:215], v[130:133], v[114:117]
	ds_read_b128 v[130:133], v243 offset:55296
	s_waitcnt vmcnt(15)
	ds_write_b128 v161, v[42:45]
	s_waitcnt lgkmcnt(7)
	v_mfma_f32_16x16x32_f16 v[110:113], v[200:203], v[150:153], v[110:113]
	v_mfma_f32_16x16x32_f16 v[106:109], v[204:207], v[150:153], v[106:109]
	v_mfma_f32_16x16x32_f16 v[102:105], v[208:211], v[150:153], v[102:105]
	v_mfma_f32_16x16x32_f16 v[98:101], v[212:215], v[150:153], v[98:101]
	ds_read_b128 v[150:153], v242 offset:32768
	s_waitcnt vmcnt(14)
	ds_write_b128 v161, v[58:61] offset:4096
	s_waitcnt lgkmcnt(8)
	v_mfma_f32_16x16x32_f16 v[94:97], v[200:203], v[192:195], v[94:97]
	v_mfma_f32_16x16x32_f16 v[90:93], v[204:207], v[192:195], v[90:93]
	v_mfma_f32_16x16x32_f16 v[86:89], v[208:211], v[192:195], v[86:89]
	v_mfma_f32_16x16x32_f16 v[82:85], v[212:215], v[192:195], v[82:85]
	ds_read_b128 v[192:195], v242 offset:34816
	s_waitcnt vmcnt(13)
	ds_write_b128 v161, v[62:65] offset:8192
	s_waitcnt lgkmcnt(9)
	v_mfma_f32_16x16x32_f16 v[14:17], v[200:203], v[196:199], v[14:17]
	v_mfma_f32_16x16x32_f16 v[10:13], v[204:207], v[196:199], v[10:13]
	v_mfma_f32_16x16x32_f16 v[6:9], v[208:211], v[196:199], v[6:9]
	v_mfma_f32_16x16x32_f16 v[2:5], v[212:215], v[196:199], v[2:5]
	ds_read_b128 v[196:199], v242 offset:36864
	ds_read_b128 v[200:203], v242 offset:38912
	s_waitcnt vmcnt(12)
	ds_write_b128 v161, v[66:69] offset:12288
	s_waitcnt lgkmcnt(6)
	v_mfma_f32_16x16x32_f16 v[126:129], v[244:247], v[150:153], v[126:129]
	v_mfma_f32_16x16x32_f16 v[122:125], v[248:251], v[150:153], v[122:125]
	v_mfma_f32_16x16x32_f16 v[118:121], v[252:255], v[150:153], v[118:121]
	v_mfma_f32_16x16x32_f16 v[114:117], v[130:133], v[150:153], v[114:117]
	s_waitcnt vmcnt(11)
	ds_write_b128 v161, v[54:57] offset:16384
	s_waitcnt lgkmcnt(5)
	v_mfma_f32_16x16x32_f16 v[110:113], v[244:247], v[192:195], v[110:113]
	v_mfma_f32_16x16x32_f16 v[106:109], v[248:251], v[192:195], v[106:109]
	v_mfma_f32_16x16x32_f16 v[102:105], v[252:255], v[192:195], v[102:105]
	v_mfma_f32_16x16x32_f16 v[98:101], v[130:133], v[192:195], v[98:101]
	s_waitcnt vmcnt(10)
	ds_write_b128 v161, v[70:73] offset:20480
	s_waitcnt lgkmcnt(4)
	v_mfma_f32_16x16x32_f16 v[94:97], v[244:247], v[196:199], v[94:97]
	v_mfma_f32_16x16x32_f16 v[90:93], v[248:251], v[196:199], v[90:93]
	v_mfma_f32_16x16x32_f16 v[86:89], v[252:255], v[196:199], v[86:89]
	v_mfma_f32_16x16x32_f16 v[82:85], v[130:133], v[196:199], v[82:85]
	s_waitcnt vmcnt(9)
	ds_write_b128 v161, v[74:77] offset:24576
	s_waitcnt lgkmcnt(4)
	v_mfma_f32_16x16x32_f16 v[14:17], v[244:247], v[200:203], v[14:17]
	v_mfma_f32_16x16x32_f16 v[10:13], v[248:251], v[200:203], v[10:13]
	v_mfma_f32_16x16x32_f16 v[6:9], v[252:255], v[200:203], v[6:9]
	v_mfma_f32_16x16x32_f16 v[2:5], v[130:133], v[200:203], v[2:5]
	s_waitcnt vmcnt(8)
	ds_write_b128 v161, v[78:81] offset:28672
	s_waitcnt lgkmcnt(0)
	s_barrier
	ds_read_b128 v[204:207], v163 offset:16384
	ds_read_b128 v[208:211], v163 offset:18432
	ds_read_b128 v[212:215], v163 offset:20480
	ds_read_b128 v[216:219], v163 offset:22528
	s_add_i32 s11, s10, 0xc0
	ds_read_b128 v[192:195], v162
	ds_read_b128 v[196:199], v162 offset:2048
	s_cmpk_lt_u32 s10, 0xa40
	s_cselect_b32 s42, s11, 0xac0
	ds_read_b128 v[200:203], v162 offset:4096
	s_lshl_b64 s[12:13], s[42:43], 1
	v_lshl_add_u64 v[152:153], v[146:147], 0, s[12:13]
	ds_read_b128 v[130:133], v162 offset:6144
	ds_read_b128 v[244:247], v243 offset:16384
	ds_read_b128 v[248:251], v243 offset:18432
	ds_read_b128 v[252:255], v243 offset:20480
	s_waitcnt lgkmcnt(6)
	v_mfma_f32_16x16x32_f16 v[126:129], v[204:207], v[192:195], v[126:129]
	v_lshl_add_u64 v[150:151], v[148:149], 0, s[12:13]
	s_add_i32 s11, s10, 0x100
	s_cmpk_lt_u32 s10, 0xa00
	v_mfma_f32_16x16x32_f16 v[122:125], v[208:211], v[192:195], v[122:125]
	s_cselect_b32 s42, s11, 0xac0
	s_lshl_b64 s[12:13], s[42:43], 1
	v_lshl_add_u64 v[168:169], v[148:149], 0, s[12:13]
	v_mfma_f32_16x16x32_f16 v[118:121], v[212:215], v[192:195], v[118:121]
	s_add_i32 s11, s10, 0x80
	s_cmpk_lt_u32 s10, 0xa80
	s_mov_b32 s10, s11
	v_mfma_f32_16x16x32_f16 v[114:117], v[216:219], v[192:195], v[114:117]
	ds_read_b128 v[192:195], v243 offset:22528
	s_waitcnt vmcnt(7)
	ds_write_b128 v161, v[18:21] offset:32768
	s_waitcnt lgkmcnt(7)
	v_mfma_f32_16x16x32_f16 v[110:113], v[204:207], v[196:199], v[110:113]
	v_mfma_f32_16x16x32_f16 v[106:109], v[208:211], v[196:199], v[106:109]
	v_mfma_f32_16x16x32_f16 v[102:105], v[212:215], v[196:199], v[102:105]
	v_mfma_f32_16x16x32_f16 v[98:101], v[216:219], v[196:199], v[98:101]
	ds_read_b128 v[196:199], v242
	s_waitcnt vmcnt(6)
	ds_write_b128 v161, v[26:29] offset:36864
	s_waitcnt lgkmcnt(8)
	v_mfma_f32_16x16x32_f16 v[94:97], v[204:207], v[200:203], v[94:97]
	v_mfma_f32_16x16x32_f16 v[90:93], v[208:211], v[200:203], v[90:93]
	v_mfma_f32_16x16x32_f16 v[86:89], v[212:215], v[200:203], v[86:89]
	v_mfma_f32_16x16x32_f16 v[82:85], v[216:219], v[200:203], v[82:85]
	ds_read_b128 v[200:203], v242 offset:2048
	s_waitcnt vmcnt(5)
	ds_write_b128 v161, v[30:33] offset:40960
	s_waitcnt lgkmcnt(9)
	v_mfma_f32_16x16x32_f16 v[14:17], v[204:207], v[130:133], v[14:17]
	v_mfma_f32_16x16x32_f16 v[10:13], v[208:211], v[130:133], v[10:13]
	v_mfma_f32_16x16x32_f16 v[6:9], v[212:215], v[130:133], v[6:9]
	v_mfma_f32_16x16x32_f16 v[2:5], v[216:219], v[130:133], v[2:5]
	ds_read_b128 v[130:133], v242 offset:4096
	ds_read_b128 v[204:207], v242 offset:6144
	s_waitcnt vmcnt(4)
	ds_write_b128 v161, v[34:37] offset:45056
	s_waitcnt lgkmcnt(6)
	v_mfma_f32_16x16x32_f16 v[126:129], v[244:247], v[196:199], v[126:129]
	v_mfma_f32_16x16x32_f16 v[122:125], v[248:251], v[196:199], v[122:125]
	v_mfma_f32_16x16x32_f16 v[118:121], v[252:255], v[196:199], v[118:121]
	v_mfma_f32_16x16x32_f16 v[114:117], v[192:195], v[196:199], v[114:117]
	s_waitcnt vmcnt(3)
	ds_write_b128 v161, v[22:25] offset:49152
	v_lshl_add_u64 v[216:217], v[146:147], 0, s[12:13]
	s_waitcnt lgkmcnt(5)
	v_mfma_f32_16x16x32_f16 v[110:113], v[244:247], v[200:203], v[110:113]
	v_mfma_f32_16x16x32_f16 v[106:109], v[248:251], v[200:203], v[106:109]
	v_mfma_f32_16x16x32_f16 v[102:105], v[252:255], v[200:203], v[102:105]
	v_mfma_f32_16x16x32_f16 v[98:101], v[192:195], v[200:203], v[98:101]
	s_waitcnt vmcnt(2)
	ds_write_b128 v161, v[38:41] offset:53248
	s_waitcnt lgkmcnt(4)
	v_mfma_f32_16x16x32_f16 v[94:97], v[244:247], v[130:133], v[94:97]
	v_mfma_f32_16x16x32_f16 v[90:93], v[248:251], v[130:133], v[90:93]
	v_mfma_f32_16x16x32_f16 v[86:89], v[252:255], v[130:133], v[86:89]
	v_mfma_f32_16x16x32_f16 v[82:85], v[192:195], v[130:133], v[82:85]
	s_waitcnt vmcnt(1)
	ds_write_b128 v161, v[46:49] offset:57344
	s_waitcnt lgkmcnt(4)
	v_mfma_f32_16x16x32_f16 v[14:17], v[244:247], v[204:207], v[14:17]
	v_mfma_f32_16x16x32_f16 v[10:13], v[248:251], v[204:207], v[10:13]
	v_mfma_f32_16x16x32_f16 v[6:9], v[252:255], v[204:207], v[6:9]
	v_mfma_f32_16x16x32_f16 v[2:5], v[192:195], v[204:207], v[2:5]
	s_waitcnt vmcnt(0)
	ds_write_b128 v161, v[50:53] offset:61440
	s_waitcnt lgkmcnt(0)
	s_barrier
	ds_read_b128 v[200:203], v163 offset:49152
	ds_read_b128 v[204:207], v163 offset:51200
	ds_read_b128 v[208:211], v163 offset:53248
	ds_read_b128 v[212:215], v163 offset:55296
	ds_read_b128 v[130:133], v162 offset:32768
	ds_read_b128 v[150:153], v162 offset:34816
	ds_read_b128 v[192:195], v162 offset:36864
	ds_read_b128 v[196:199], v162 offset:38912
	ds_read_b128 v[244:247], v243 offset:49152
	ds_read_b128 v[248:251], v243 offset:51200
	ds_read_b128 v[252:255], v243 offset:53248
	s_waitcnt lgkmcnt(6)
	v_mfma_f32_16x16x32_f16 v[126:129], v[200:203], v[130:133], v[126:129]
	v_mfma_f32_16x16x32_f16 v[122:125], v[204:207], v[130:133], v[122:125]
	v_mfma_f32_16x16x32_f16 v[118:121], v[208:211], v[130:133], v[118:121]
	v_mfma_f32_16x16x32_f16 v[114:117], v[212:215], v[130:133], v[114:117]
	ds_read_b128 v[130:133], v243 offset:55296
	s_waitcnt lgkmcnt(6)
	v_mfma_f32_16x16x32_f16 v[110:113], v[200:203], v[150:153], v[110:113]
	v_mfma_f32_16x16x32_f16 v[106:109], v[204:207], v[150:153], v[106:109]
	v_mfma_f32_16x16x32_f16 v[102:105], v[208:211], v[150:153], v[102:105]
	v_mfma_f32_16x16x32_f16 v[98:101], v[212:215], v[150:153], v[98:101]
	ds_read_b128 v[150:153], v242 offset:32768
	s_waitcnt lgkmcnt(6)
	v_mfma_f32_16x16x32_f16 v[94:97], v[200:203], v[192:195], v[94:97]
	v_mfma_f32_16x16x32_f16 v[90:93], v[204:207], v[192:195], v[90:93]
	v_mfma_f32_16x16x32_f16 v[86:89], v[208:211], v[192:195], v[86:89]
	v_mfma_f32_16x16x32_f16 v[82:85], v[212:215], v[192:195], v[82:85]
	ds_read_b128 v[192:195], v242 offset:34816
	s_waitcnt lgkmcnt(6)
; template <int NJ>
; __device__ __forceinline__ void gres_tile(const Params& p, const f16* A, int lda, const f16* W, int K, const float* mod,
;                                           bool first_in, f16* sA, f16* sB, int m0, int n0) {
;     ...
; #pragma unroll
;   for (int i = 0; i < 4; ++i) {
;     int m = m0 + wm * 64 + i * 16 + (lane & 15);
;     const float* xi = xrow_in(p, first_in ? 0 : 1, m);
;     float* xo = xrow_out(p, m);
;     const float* gt = mod + (size_t)modrow_of(m) * 6 * DM;
; #pragma unroll
;     for (int j = 0; j < NJ; ++j) {
;       int n = n0 + wn * (NJ * 16) + j * 16 + 4 * (lane >> 4);
;       float4 xv = *(const float4*)(xi + n);
;       float4 gv = *(const float4*)(gt + n);
;       float4 o;
;       o.x = xv.x + gv.x * acc[i][j][0];
;       o.y = xv.y + gv.y * acc[i][j][1];
;       o.z = xv.z + gv.z * acc[i][j][2];
;       o.w = xv.w + gv.w * acc[i][j][3];
;       *(float4*)(xo + n) = o;
;     }
;   }
	v_mfma_f32_16x16x32_f16 v[14:17], v[200:203], v[196:199], v[14:17]
	v_mfma_f32_16x16x32_f16 v[10:13], v[204:207], v[196:199], v[10:13]
	v_mfma_f32_16x16x32_f16 v[6:9], v[208:211], v[196:199], v[6:9]
	v_mfma_f32_16x16x32_f16 v[2:5], v[212:215], v[196:199], v[2:5]
	ds_read_b128 v[196:199], v242 offset:36864
	ds_read_b128 v[200:203], v242 offset:38912
	s_waitcnt lgkmcnt(3)
	v_mfma_f32_16x16x32_f16 v[126:129], v[244:247], v[150:153], v[126:129]
	v_mfma_f32_16x16x32_f16 v[122:125], v[248:251], v[150:153], v[122:125]
	v_mfma_f32_16x16x32_f16 v[118:121], v[252:255], v[150:153], v[118:121]
	v_mfma_f32_16x16x32_f16 v[114:117], v[130:133], v[150:153], v[114:117]
	s_waitcnt lgkmcnt(2)
	v_mfma_f32_16x16x32_f16 v[110:113], v[244:247], v[192:195], v[110:113]
	v_mfma_f32_16x16x32_f16 v[106:109], v[248:251], v[192:195], v[106:109]
	v_mfma_f32_16x16x32_f16 v[102:105], v[252:255], v[192:195], v[102:105]
	v_mfma_f32_16x16x32_f16 v[98:101], v[130:133], v[192:195], v[98:101]
	s_waitcnt lgkmcnt(1)
	v_mfma_f32_16x16x32_f16 v[94:97], v[244:247], v[196:199], v[94:97]
	v_mfma_f32_16x16x32_f16 v[90:93], v[248:251], v[196:199], v[90:93]
	v_mfma_f32_16x16x32_f16 v[86:89], v[252:255], v[196:199], v[86:89]
	v_mfma_f32_16x16x32_f16 v[82:85], v[130:133], v[196:199], v[82:85]
	s_waitcnt lgkmcnt(0)
	v_mfma_f32_16x16x32_f16 v[14:17], v[244:247], v[200:203], v[14:17]
	v_mfma_f32_16x16x32_f16 v[10:13], v[248:251], v[200:203], v[10:13]
	v_mfma_f32_16x16x32_f16 v[6:9], v[252:255], v[200:203], v[6:9]
	v_mfma_f32_16x16x32_f16 v[2:5], v[130:133], v[200:203], v[2:5]
	s_waitcnt lgkmcnt(0)
	s_setprio 0
	s_waitcnt vmcnt(15)
	v_or_b32_e32 v18, s6, v154
	v_add_u32_e32 v21, v18, v160
	v_cmp_gt_i32_e32 vcc, s80, v21
	v_ashrrev_i32_e32 v20, 31, v21
	s_waitcnt vmcnt(11)
	v_add_u32_e32 v22, 0xffff8000, v21
	v_cndmask_b32_e32 v23, 0, v20, vcc
	v_cndmask_b32_e32 v22, v22, v21, vcc
	v_cndmask_b32_e32 v25, v137, v1, vcc
	v_cndmask_b32_e32 v24, v136, v0, vcc
	v_lshlrev_b64 v[22:23], 12, v[22:23]
	v_lshrrev_b32_e32 v20, 18, v20
	v_lshl_add_u64 v[22:23], v[24:25], 0, v[22:23]
	v_add_u32_e32 v24, v21, v20
	v_lshl_or_b32 v18, s7, 7, v166
	v_ashrrev_i32_e32 v24, 14, v24
	v_ashrrev_i32_e32 v19, 31, v18
	v_cndmask_b32_e32 v24, 2, v24, vcc
	v_mul_hi_i32_i24_e32 v25, 0x6000, v24
	v_mul_i32_i24_e32 v24, 0x6000, v24
	v_lshlrev_b64 v[18:19], 2, v[18:19]
	v_lshl_add_u64 v[24:25], v[134:135], 0, v[24:25]
	v_lshl_add_u64 v[30:31], v[22:23], 0, v[18:19]
	v_lshl_add_u64 v[32:33], v[24:25], 0, v[18:19]
	global_load_dwordx4 v[22:25], v[30:31], off
	global_load_dwordx4 v[26:29], v[32:33], off
	s_add_i32 s5, s5, s26
	s_cmp_ge_i32 s5, s74
	s_waitcnt vmcnt(0)
	v_pk_fma_f32 v[22:23], v[126:127], v[26:27], v[22:23]
	v_pk_fma_f32 v[24:25], v[128:129], v[28:29], v[24:25]
	global_store_dwordx4 v[30:31], v[22:25], off
	global_load_dwordx4 v[22:25], v[30:31], off offset:64
	s_nop 0
	global_load_dwordx4 v[26:29], v[32:33], off offset:64
	s_waitcnt vmcnt(0)
	v_pk_fma_f32 v[22:23], v[122:123], v[26:27], v[22:23]
	v_pk_fma_f32 v[24:25], v[124:125], v[28:29], v[24:25]
	global_store_dwordx4 v[30:31], v[22:25], off offset:64
	global_load_dwordx4 v[22:25], v[30:31], off offset:128
	s_nop 0
	global_load_dwordx4 v[26:29], v[32:33], off offset:128
	s_waitcnt vmcnt(0)
	v_pk_fma_f32 v[22:23], v[118:119], v[26:27], v[22:23]
	v_pk_fma_f32 v[24:25], v[120:121], v[28:29], v[24:25]
	global_store_dwordx4 v[30:31], v[22:25], off offset:128
	global_load_dwordx4 v[22:25], v[30:31], off offset:192
	s_nop 0
	global_load_dwordx4 v[26:29], v[32:33], off offset:192
	s_waitcnt vmcnt(0)
	v_pk_fma_f32 v[22:23], v[114:115], v[26:27], v[22:23]
	v_pk_fma_f32 v[24:25], v[116:117], v[28:29], v[24:25]
	v_or_b32_e32 v26, 16, v21
	global_store_dwordx4 v[30:31], v[22:25], off offset:192
	v_cmp_gt_i32_e32 vcc, s80, v26
	s_nop 0
	v_ashrrev_i32_e32 v22, 31, v26
	v_add_u32_e32 v24, 0xffff8010, v21
	v_cndmask_b32_e32 v23, 0, v22, vcc
	v_cndmask_b32_e32 v22, v24, v26, vcc
	v_cndmask_b32_e32 v25, v137, v1, vcc
	v_cndmask_b32_e32 v24, v136, v0, vcc
	v_lshlrev_b64 v[22:23], 12, v[22:23]
	v_lshl_add_u64 v[22:23], v[24:25], 0, v[22:23]
	v_add_u32_e32 v24, v26, v20
	v_ashrrev_i32_e32 v24, 14, v24
	v_cndmask_b32_e32 v24, 2, v24, vcc
	v_mul_hi_i32_i24_e32 v25, 0x6000, v24
	v_mul_i32_i24_e32 v24, 0x6000, v24
	v_lshl_add_u64 v[24:25], v[134:135], 0, v[24:25]
	v_lshl_add_u64 v[30:31], v[22:23], 0, v[18:19]
	v_lshl_add_u64 v[32:33], v[24:25], 0, v[18:19]
	global_load_dwordx4 v[22:25], v[30:31], off
	global_load_dwordx4 v[26:29], v[32:33], off
	s_waitcnt vmcnt(0)
; template <int NJ>
; __device__ __forceinline__ void gres_tile(const Params& p, const f16* A, int lda, const f16* W, int K, const float* mod,
;                                           bool first_in, f16* sA, f16* sB, int m0, int n0) {
;     ...
; #pragma unroll
;     for (int j = 0; j < NJ; ++j) {
;       int n = n0 + wn * (NJ * 16) + j * 16 + 4 * (lane >> 4);
;       float4 xv = *(const float4*)(xi + n);
;       float4 gv = *(const float4*)(gt + n);
;       float4 o;
;       o.x = xv.x + gv.x * acc[i][j][0];
;       o.y = xv.y + gv.y * acc[i][j][1];
;       o.z = xv.z + gv.z * acc[i][j][2];
;       o.w = xv.w + gv.w * acc[i][j][3];
;       *(float4*)(xo + n) = o;
;     }
;   }
	v_pk_fma_f32 v[22:23], v[110:111], v[26:27], v[22:23]
	v_pk_fma_f32 v[24:25], v[112:113], v[28:29], v[24:25]
	global_store_dwordx4 v[30:31], v[22:25], off
	global_load_dwordx4 v[22:25], v[30:31], off offset:64
	s_nop 0
	global_load_dwordx4 v[26:29], v[32:33], off offset:64
	s_waitcnt vmcnt(0)
	v_pk_fma_f32 v[22:23], v[106:107], v[26:27], v[22:23]
	v_pk_fma_f32 v[24:25], v[108:109], v[28:29], v[24:25]
	global_store_dwordx4 v[30:31], v[22:25], off offset:64
	global_load_dwordx4 v[22:25], v[30:31], off offset:128
	s_nop 0
	global_load_dwordx4 v[26:29], v[32:33], off offset:128
	s_waitcnt vmcnt(0)
	v_pk_fma_f32 v[22:23], v[102:103], v[26:27], v[22:23]
	v_pk_fma_f32 v[24:25], v[104:105], v[28:29], v[24:25]
	global_store_dwordx4 v[30:31], v[22:25], off offset:128
	global_load_dwordx4 v[22:25], v[30:31], off offset:192
	s_nop 0
	global_load_dwordx4 v[26:29], v[32:33], off offset:192
	s_waitcnt vmcnt(0)
	v_pk_fma_f32 v[22:23], v[98:99], v[26:27], v[22:23]
	v_pk_fma_f32 v[24:25], v[100:101], v[28:29], v[24:25]
	v_or_b32_e32 v26, 32, v21
	global_store_dwordx4 v[30:31], v[22:25], off offset:192
	v_cmp_gt_i32_e32 vcc, s80, v26
	s_nop 0
	v_ashrrev_i32_e32 v22, 31, v26
	v_add_u32_e32 v24, 0xffff8020, v21
	v_cndmask_b32_e32 v23, 0, v22, vcc
	v_cndmask_b32_e32 v22, v24, v26, vcc
	v_cndmask_b32_e32 v25, v137, v1, vcc
	v_cndmask_b32_e32 v24, v136, v0, vcc
	v_lshlrev_b64 v[22:23], 12, v[22:23]
	v_lshl_add_u64 v[22:23], v[24:25], 0, v[22:23]
	v_add_u32_e32 v24, v26, v20
	v_ashrrev_i32_e32 v24, 14, v24
	v_cndmask_b32_e32 v24, 2, v24, vcc
	v_mul_hi_i32_i24_e32 v25, 0x6000, v24
	v_mul_i32_i24_e32 v24, 0x6000, v24
	v_lshl_add_u64 v[24:25], v[134:135], 0, v[24:25]
	v_lshl_add_u64 v[30:31], v[22:23], 0, v[18:19]
	v_lshl_add_u64 v[32:33], v[24:25], 0, v[18:19]
	global_load_dwordx4 v[22:25], v[30:31], off
	global_load_dwordx4 v[26:29], v[32:33], off
	s_waitcnt vmcnt(0)
	v_pk_fma_f32 v[22:23], v[94:95], v[26:27], v[22:23]
	v_pk_fma_f32 v[24:25], v[96:97], v[28:29], v[24:25]
	global_store_dwordx4 v[30:31], v[22:25], off
	global_load_dwordx4 v[22:25], v[30:31], off offset:64
	s_nop 0
	global_load_dwordx4 v[26:29], v[32:33], off offset:64
	s_waitcnt vmcnt(0)
	v_pk_fma_f32 v[22:23], v[90:91], v[26:27], v[22:23]
	v_pk_fma_f32 v[24:25], v[92:93], v[28:29], v[24:25]
	global_store_dwordx4 v[30:31], v[22:25], off offset:64
	global_load_dwordx4 v[22:25], v[30:31], off offset:128
	s_nop 0
	global_load_dwordx4 v[26:29], v[32:33], off offset:128
	s_waitcnt vmcnt(0)
	v_pk_fma_f32 v[22:23], v[86:87], v[26:27], v[22:23]
	v_pk_fma_f32 v[24:25], v[88:89], v[28:29], v[24:25]
	global_store_dwordx4 v[30:31], v[22:25], off offset:128
	global_load_dwordx4 v[22:25], v[30:31], off offset:192
	s_nop 0
	global_load_dwordx4 v[26:29], v[32:33], off offset:192
	s_waitcnt vmcnt(0)
	v_pk_fma_f32 v[22:23], v[82:83], v[26:27], v[22:23]
	v_pk_fma_f32 v[24:25], v[84:85], v[28:29], v[24:25]
	v_or_b32_e32 v26, 48, v21
	global_store_dwordx4 v[30:31], v[22:25], off offset:192
	v_cmp_gt_i32_e32 vcc, s80, v26
	v_add_u32_e32 v21, 0xffff8030, v21
	v_ashrrev_i32_e32 v22, 31, v26
	v_add_u32_e32 v20, v26, v20
	v_cndmask_b32_e32 v23, 0, v22, vcc
	v_cndmask_b32_e32 v22, v21, v26, vcc
	v_ashrrev_i32_e32 v20, 14, v20
	v_cndmask_b32_e32 v25, v137, v1, vcc
	v_cndmask_b32_e32 v24, v136, v0, vcc
	v_lshlrev_b64 v[22:23], 12, v[22:23]
	v_cndmask_b32_e32 v20, 2, v20, vcc
	v_lshl_add_u64 v[22:23], v[24:25], 0, v[22:23]
	v_mul_hi_i32_i24_e32 v21, 0x6000, v20
	v_mul_i32_i24_e32 v20, 0x6000, v20
	v_lshl_add_u64 v[20:21], v[134:135], 0, v[20:21]
	v_lshl_add_u64 v[26:27], v[22:23], 0, v[18:19]
	v_lshl_add_u64 v[28:29], v[20:21], 0, v[18:19]
	global_load_dwordx4 v[18:21], v[26:27], off
	global_load_dwordx4 v[22:25], v[28:29], off
	s_waitcnt vmcnt(0)
	v_pk_fma_f32 v[14:15], v[14:15], v[22:23], v[18:19]
	v_pk_fma_f32 v[16:17], v[16:17], v[24:25], v[20:21]
	global_store_dwordx4 v[26:27], v[14:17], off
	global_load_dwordx4 v[14:17], v[26:27], off offset:64
	s_nop 0
	global_load_dwordx4 v[18:21], v[28:29], off offset:64
	s_waitcnt vmcnt(0)
	v_pk_fma_f32 v[10:11], v[10:11], v[18:19], v[14:15]
	v_pk_fma_f32 v[12:13], v[12:13], v[20:21], v[16:17]
	global_store_dwordx4 v[26:27], v[10:13], off offset:64
	global_load_dwordx4 v[10:13], v[26:27], off offset:128
	s_nop 0
	global_load_dwordx4 v[14:17], v[28:29], off offset:128
	s_waitcnt vmcnt(0)
	v_pk_fma_f32 v[6:7], v[6:7], v[14:15], v[10:11]
	v_pk_fma_f32 v[8:9], v[8:9], v[16:17], v[12:13]
	global_store_dwordx4 v[26:27], v[6:9], off offset:128
	global_load_dwordx4 v[6:9], v[26:27], off offset:192
	s_nop 0
	global_load_dwordx4 v[10:13], v[28:29], off offset:192
	s_waitcnt vmcnt(0)
	v_pk_fma_f32 v[2:3], v[2:3], v[10:11], v[6:7]
	v_pk_fma_f32 v[4:5], v[4:5], v[12:13], v[8:9]
	global_store_dwordx4 v[26:27], v[2:5], off offset:192
	s_cbranch_scc0 .LBB0_1456
